# 16-byte store pairing: pair formed in place in the accumulator quad when its upper half is dead (2 moves instead of 4)
# baseline (speedup 1.0000x reference)
; template <int N> DI void wait_vm() { asm volatile("s_waitcnt vmcnt(%0)" ::"n"(N) : "memory"); }
; template <int BM, class Epi>
; DI void gemm_dma(const u16* __restrict__ X, long ldx, const u16* __restrict__ W, long ldw, int K, char* smem,
;                  int m0, int n0, const Epi& epi) {
;     ...
;   do {
;     if (kt + D - 2 < nk) wait_vm<PW * (D - 2)>(); else wait_vm<0>();
;     __syncthreads();
;     if (kt + D - 1 < nk) GD_ISSUE(nxt)
;     nxt = (nxt + 1 == D) ? 0 : nxt + 1;
;     const char* base = smem + cur * STG;
;     cur = (cur + 1 == D) ? 0 : cur + 1;
;     bf16x8 xf[MT];
; #pragma unroll
;     for (int i = 0; i < MT; ++i) xf[i] = *(const bf16x8*)(base + (xrow0 + i * 16) * 64 + rd);
; #pragma unroll
;     for (int nh = 0; nh < NT / 4; ++nh) {
;       bf16x8 wf[4];
; #pragma unroll
;       for (int i = 0; i < 4; ++i) wf[i] = *(const bf16x8*)(base + BM * 64 + (wrow0 + (nh * 4 + i) * 16) * 64 + rd);
; #pragma unroll
;       for (int i = 0; i < 4; ++i)
; #pragma unroll
;         for (int mt = 0; mt < MT; ++mt)
;           acc[nh * 4 + i][mt] = __builtin_amdgcn_mfma_f32_16x16x32_bf16(wf[i], xf[mt], acc[nh * 4 + i][mt], 0, 0, 0);
;     }
;   } while (++kt < nk);
;     ...
;   epi.run(acc, m0 + xrow0 + lr, n0 + wrow0 + 4 * g);
.LBB0_32:
	s_mul_i32 s12, s10, 0x6000
	v_lshl_add_u64 v[196:197], v[130:131], 0, s[40:41]
	s_waitcnt vmcnt(6)
	s_barrier
	s_mul_i32 s98, s11, 0x6000
	v_or_b32_e32 v137, s98, v134
	v_add_u32_e32 v150, v137, v136
	ds_read_b128 v[138:141], v150
	ds_read_b128 v[142:145], v150 offset:1024
	ds_read_b128 v[146:149], v150 offset:2048
	ds_read_b128 v[150:153], v150 offset:3072
	ds_read_b128 v[154:157], v137 offset:16384
	ds_read_b128 v[158:161], v137 offset:17408
	ds_read_b128 v[162:165], v137 offset:18432
	ds_read_b128 v[166:169], v137 offset:19456
	ds_read_b128 v[226:229], v137 offset:20480
	ds_read_b128 v[230:233], v137 offset:21504
	ds_read_b128 v[234:237], v137 offset:22528
	ds_read_b128 v[238:241], v137 offset:23552
	s_add_i32 s13, s12, s8
	s_mov_b32 m0, s13
	s_nop 0
	global_load_lds_dwordx4 v[196:197], off
	v_lshl_add_u64 v[224:225], v[196:197], 0, s[16:17]
	s_add_i32 s14, s13, 0x400
	s_mov_b32 m0, s14
	s_nop 0
	global_load_lds_dwordx4 v[224:225], off
	v_lshl_add_u64 v[224:225], v[196:197], 0, s[18:19]
	s_add_i32 s14, s13, 0x800
	s_mov_b32 m0, s14
	s_nop 0
	global_load_lds_dwordx4 v[224:225], off
	v_lshl_add_u64 v[196:197], v[196:197], 0, s[20:21]
	s_addk_i32 s13, 0xc00
	s_mov_b32 m0, s13
	s_nop 0
	global_load_lds_dwordx4 v[196:197], off
	s_add_i32 s12, s12, s9
	v_lshl_add_u64 v[194:195], v[128:129], 0, s[40:41]
	s_mov_b32 m0, s12
	s_nop 0
	global_load_lds_dwordx4 v[194:195], off
	s_addk_i32 s12, 0x400
	v_lshl_add_u64 v[194:195], v[194:195], 0, s[16:17]
	s_mov_b32 m0, s12
	s_nop 0
	global_load_lds_dwordx4 v[194:195], off
	s_waitcnt lgkmcnt(7)
	v_mfma_f32_16x16x32_bf16 v[124:127], v[154:157], v[138:141], v[124:127]
	s_add_i32 s10, s10, 1
	s_add_i32 s11, s11, 1
	s_cmp_lg_u32 s10, 3
	v_mfma_f32_16x16x32_bf16 v[120:123], v[154:157], v[142:145], v[120:123]
	s_cselect_b32 s10, s10, 0
	s_cmp_lg_u32 s11, 3
	s_cselect_b32 s11, s11, 0
	v_mfma_f32_16x16x32_bf16 v[116:119], v[154:157], v[146:149], v[116:119]
	s_add_u32 s40, s40, 64
	s_addc_u32 s41, s41, 0
	s_cmpk_lg_i32 s40, 0x780
	v_mfma_f32_16x16x32_bf16 v[112:115], v[154:157], v[150:153], v[112:115]
	s_waitcnt lgkmcnt(6)
	v_mfma_f32_16x16x32_bf16 v[108:111], v[158:161], v[138:141], v[108:111]
	v_mfma_f32_16x16x32_bf16 v[104:107], v[158:161], v[142:145], v[104:107]
	v_mfma_f32_16x16x32_bf16 v[100:103], v[158:161], v[146:149], v[100:103]
	v_mfma_f32_16x16x32_bf16 v[96:99], v[158:161], v[150:153], v[96:99]
	s_waitcnt lgkmcnt(5)
	v_mfma_f32_16x16x32_bf16 v[92:95], v[162:165], v[138:141], v[92:95]
	v_mfma_f32_16x16x32_bf16 v[88:91], v[162:165], v[142:145], v[88:91]
	v_mfma_f32_16x16x32_bf16 v[84:87], v[162:165], v[146:149], v[84:87]
	v_mfma_f32_16x16x32_bf16 v[80:83], v[162:165], v[150:153], v[80:83]
	s_waitcnt lgkmcnt(4)
	v_mfma_f32_16x16x32_bf16 v[76:79], v[166:169], v[138:141], v[76:79]
	v_mfma_f32_16x16x32_bf16 v[72:75], v[166:169], v[142:145], v[72:75]
	v_mfma_f32_16x16x32_bf16 v[68:71], v[166:169], v[146:149], v[68:71]
	v_mfma_f32_16x16x32_bf16 v[64:67], v[166:169], v[150:153], v[64:67]
	s_waitcnt lgkmcnt(3)
	v_mfma_f32_16x16x32_bf16 v[60:63], v[226:229], v[138:141], v[60:63]
	v_mfma_f32_16x16x32_bf16 v[56:59], v[226:229], v[142:145], v[56:59]
	v_mfma_f32_16x16x32_bf16 v[52:55], v[226:229], v[146:149], v[52:55]
	v_mfma_f32_16x16x32_bf16 v[48:51], v[226:229], v[150:153], v[48:51]
	s_waitcnt lgkmcnt(2)
	v_mfma_f32_16x16x32_bf16 v[44:47], v[230:233], v[138:141], v[44:47]
	v_mfma_f32_16x16x32_bf16 v[40:43], v[230:233], v[142:145], v[40:43]
	v_mfma_f32_16x16x32_bf16 v[36:39], v[230:233], v[146:149], v[36:39]
	v_mfma_f32_16x16x32_bf16 v[32:35], v[230:233], v[150:153], v[32:35]
	s_waitcnt lgkmcnt(1)
	v_mfma_f32_16x16x32_bf16 v[28:31], v[234:237], v[138:141], v[28:31]
	v_mfma_f32_16x16x32_bf16 v[24:27], v[234:237], v[142:145], v[24:27]
	v_mfma_f32_16x16x32_bf16 v[20:23], v[234:237], v[146:149], v[20:23]
	v_mfma_f32_16x16x32_bf16 v[16:19], v[234:237], v[150:153], v[16:19]
	s_waitcnt lgkmcnt(0)
	v_mfma_f32_16x16x32_bf16 v[12:15], v[238:241], v[138:141], v[12:15]
	v_mfma_f32_16x16x32_bf16 v[8:11], v[238:241], v[142:145], v[8:11]
	v_mfma_f32_16x16x32_bf16 v[4:7], v[238:241], v[146:149], v[4:7]
	v_mfma_f32_16x16x32_bf16 v[0:3], v[238:241], v[150:153], v[0:3]
	s_cbranch_scc1 .LBB0_32
	v_add_u32_e32 v180, v134, v136
	s_waitcnt vmcnt(6)
	s_barrier
	ds_read_b128 v[128:131], v180
	ds_read_b128 v[136:139], v180 offset:1024
	ds_read_b128 v[140:143], v180 offset:2048
	ds_read_b128 v[144:147], v180 offset:3072
	ds_read_b128 v[148:151], v134 offset:16384
	ds_read_b128 v[152:155], v134 offset:17408
	ds_read_b128 v[156:159], v134 offset:18432
	ds_read_b128 v[160:163], v134 offset:19456
	s_waitcnt lgkmcnt(3)
	v_mfma_f32_16x16x32_bf16 v[124:127], v[148:151], v[128:131], v[124:127]
	s_lshl_b32 s7, s7, 8
	v_lshl_or_b32 v182, v132, 3, s7
	v_mfma_f32_16x16x32_bf16 v[120:123], v[148:151], v[136:139], v[120:123]
	v_mfma_f32_16x16x32_bf16 v[116:119], v[148:151], v[140:143], v[116:119]
	v_mfma_f32_16x16x32_bf16 v[112:115], v[148:151], v[144:147], v[112:115]
	s_waitcnt lgkmcnt(2)
	v_mfma_f32_16x16x32_bf16 v[108:111], v[152:155], v[128:131], v[108:111]
	v_mfma_f32_16x16x32_bf16 v[104:107], v[152:155], v[136:139], v[104:107]
	v_mfma_f32_16x16x32_bf16 v[100:103], v[152:155], v[140:143], v[100:103]
	v_mfma_f32_16x16x32_bf16 v[96:99], v[152:155], v[144:147], v[96:99]
	s_waitcnt lgkmcnt(1)
	v_mfma_f32_16x16x32_bf16 v[92:95], v[156:159], v[128:131], v[92:95]
	v_mfma_f32_16x16x32_bf16 v[88:91], v[156:159], v[136:139], v[88:91]
	v_mfma_f32_16x16x32_bf16 v[84:87], v[156:159], v[140:143], v[84:87]
	v_mfma_f32_16x16x32_bf16 v[148:151], v[156:159], v[144:147], v[80:83]
	s_waitcnt lgkmcnt(0)
	v_mfma_f32_16x16x32_bf16 v[76:79], v[160:163], v[128:131], v[76:79]
	v_mfma_f32_16x16x32_bf16 v[152:155], v[160:163], v[136:139], v[72:75]
	v_mfma_f32_16x16x32_bf16 v[68:71], v[160:163], v[140:143], v[68:71]
	v_mfma_f32_16x16x32_bf16 v[156:159], v[160:163], v[144:147], v[64:67]
	s_nop 2
	ds_read_b128 v[64:67], v134 offset:20480
	ds_read_b128 v[72:75], v134 offset:21504
	ds_read_b128 v[80:83], v134 offset:22528
	ds_read_b128 v[160:163], v134 offset:23552
	s_waitcnt vmcnt(0)
	s_waitcnt lgkmcnt(0)
	v_mfma_f32_16x16x32_bf16 v[60:63], v[64:67], v[128:131], v[60:63]
	s_barrier
; template <int BM, class Epi>
; DI void gemm_dma(const u16* __restrict__ X, long ldx, const u16* __restrict__ W, long ldw, int K, char* smem,
;                  int m0, int n0, const Epi& epi) {
;     ...
;     for (int i = 0; i < MT; ++i) xf[i] = *(const bf16x8*)(base + (xrow0 + i * 16) * 64 + rd);
; #pragma unroll
;     for (int nh = 0; nh < NT / 4; ++nh) {
;       bf16x8 wf[4];
; #pragma unroll
;       for (int i = 0; i < 4; ++i) wf[i] = *(const bf16x8*)(base + BM * 64 + (wrow0 + (nh * 4 + i) * 16) * 64 + rd);
; #pragma unroll
;       for (int i = 0; i < 4; ++i)
; #pragma unroll
;         for (int mt = 0; mt < MT; ++mt)
;           acc[nh * 4 + i][mt] = __builtin_amdgcn_mfma_f32_16x16x32_bf16(wf[i], xf[mt], acc[nh * 4 + i][mt], 0, 0, 0);
	v_mfma_f32_16x16x32_bf16 v[164:167], v[64:67], v[136:139], v[56:59]
	v_mfma_f32_16x16x32_bf16 v[52:55], v[64:67], v[140:143], v[52:55]
	v_mfma_f32_16x16x32_bf16 v[168:171], v[64:67], v[144:147], v[48:51]
	v_mfma_f32_16x16x32_bf16 v[44:47], v[72:75], v[128:131], v[44:47]
	v_mfma_f32_16x16x32_bf16 v[172:175], v[72:75], v[136:139], v[40:43]
	v_mfma_f32_16x16x32_bf16 v[36:39], v[72:75], v[140:143], v[36:39]
	v_mfma_f32_16x16x32_bf16 v[176:179], v[72:75], v[144:147], v[32:35]
	v_mfma_f32_16x16x32_bf16 v[28:31], v[80:83], v[128:131], v[28:31]
	v_mfma_f32_16x16x32_bf16 v[24:27], v[80:83], v[136:139], v[24:27]
	v_mfma_f32_16x16x32_bf16 v[20:23], v[80:83], v[140:143], v[20:23]
	v_mfma_f32_16x16x32_bf16 v[16:19], v[80:83], v[144:147], v[16:19]
	v_mfma_f32_16x16x32_bf16 v[12:15], v[160:163], v[128:131], v[12:15]
	v_mfma_f32_16x16x32_bf16 v[8:11], v[160:163], v[136:139], v[8:11]
	v_mfma_f32_16x16x32_bf16 v[4:7], v[160:163], v[140:143], v[4:7]
	v_mfma_f32_16x16x32_bf16 v[0:3], v[160:163], v[144:147], v[0:3]
	ds_read_b128 v[128:131], v180 offset:24576
	ds_read_b128 v[136:139], v180 offset:25600
	ds_read_b128 v[140:143], v180 offset:26624
	ds_read_b128 v[144:147], v180 offset:27648
	ds_read_b128 v[32:35], v134 offset:40960
	ds_read_b128 v[40:43], v134 offset:41984
	ds_read_b128 v[48:51], v134 offset:43008
	ds_read_b128 v[160:163], v134 offset:44032
	s_waitcnt lgkmcnt(2)
	v_mfma_f32_16x16x32_bf16 v[108:111], v[40:43], v[128:131], v[108:111]
	v_mfma_f32_16x16x32_bf16 v[104:107], v[40:43], v[136:139], v[104:107]
	v_mfma_f32_16x16x32_bf16 v[100:103], v[40:43], v[140:143], v[100:103]
	s_nop 5
	v_cvt_pk_bf16_f32 v108, v108, v109
	v_cvt_pk_bf16_f32 v109, v110, v111
	v_cvt_pk_bf16_f32 v104, v104, v105
	v_mfma_f32_16x16x32_bf16 v[96:99], v[40:43], v[144:147], v[96:99]
	v_cvt_pk_bf16_f32 v105, v106, v107
	v_cvt_pk_bf16_f32 v100, v100, v101
	v_cvt_pk_bf16_f32 v101, v102, v103
	s_waitcnt lgkmcnt(1)
	v_mfma_f32_16x16x32_bf16 v[92:95], v[48:51], v[128:131], v[92:95]
	v_mfma_f32_16x16x32_bf16 v[80:83], v[48:51], v[136:139], v[88:91]
	s_nop 1
	v_cvt_pk_bf16_f32 v96, v96, v97
	v_cvt_pk_bf16_f32 v97, v98, v99
	s_nop 2
	v_cvt_pk_bf16_f32 v92, v92, v93
	v_mfma_f32_16x16x32_bf16 v[72:75], v[48:51], v[140:143], v[84:87]
	v_cvt_pk_bf16_f32 v93, v94, v95
	v_cvt_pk_bf16_f32 v80, v80, v81
	v_cvt_pk_bf16_f32 v81, v82, v83
	v_mfma_f32_16x16x32_bf16 v[64:67], v[48:51], v[144:147], v[148:151]
	s_waitcnt lgkmcnt(0)
	v_mfma_f32_16x16x32_bf16 v[48:51], v[160:163], v[136:139], v[152:155]
	s_nop 1
	v_cvt_pk_bf16_f32 v72, v72, v73
	v_cvt_pk_bf16_f32 v73, v74, v75
	s_nop 1
	v_cvt_pk_bf16_f32 v64, v64, v65
	v_mfma_f32_16x16x32_bf16 v[40:43], v[160:163], v[140:143], v[68:71]
	s_nop 2
	ds_read_b128 v[68:71], v134 offset:45056
	ds_read_b128 v[88:91], v134 offset:46080
	ds_read_b128 v[148:151], v134 offset:47104
	ds_read_b128 v[152:155], v134 offset:48128
	v_cvt_pk_bf16_f32 v65, v66, v67
	v_cvt_pk_bf16_f32 v48, v48, v49
	v_mfma_f32_16x16x32_bf16 v[124:127], v[32:35], v[128:131], v[124:127]
	v_cvt_pk_bf16_f32 v49, v50, v51
	v_cvt_pk_bf16_f32 v40, v40, v41
	v_cvt_pk_bf16_f32 v41, v42, v43
	v_mfma_f32_16x16x32_bf16 v[120:123], v[32:35], v[136:139], v[120:123]
	v_mfma_f32_16x16x32_bf16 v[116:119], v[32:35], v[140:143], v[116:119]
	v_mfma_f32_16x16x32_bf16 v[112:115], v[32:35], v[144:147], v[112:115]
	s_nop 5
	v_cvt_pk_bf16_f32 v120, v120, v121
	v_cvt_pk_bf16_f32 v121, v122, v123
	v_cvt_pk_bf16_f32 v116, v116, v117
	v_mfma_f32_16x16x32_bf16 v[56:59], v[160:163], v[128:131], v[76:79]
	v_cvt_pk_bf16_f32 v117, v118, v119
	v_cvt_pk_bf16_f32 v112, v112, v113
	v_cvt_pk_bf16_f32 v113, v114, v115
	v_mfma_f32_16x16x32_bf16 v[32:35], v[160:163], v[144:147], v[156:159]
	s_waitcnt lgkmcnt(3)
	v_mfma_f32_16x16x32_bf16 v[156:159], v[68:71], v[128:131], v[60:63]
	s_nop 1
	v_cvt_pk_bf16_f32 v56, v56, v57
	s_nop 2
	v_cvt_pk_bf16_f32 v32, v32, v33
	v_cvt_pk_bf16_f32 v33, v34, v35
	v_mfma_f32_16x16x32_bf16 v[76:79], v[68:71], v[140:143], v[52:55]
	v_cvt_pk_bf16_f32 v57, v58, v59
	s_waitcnt lgkmcnt(2)
	v_mfma_f32_16x16x32_bf16 v[60:63], v[88:91], v[128:131], v[44:47]
	v_mfma_f32_16x16x32_bf16 v[52:55], v[88:91], v[136:139], v[172:175]
	v_mfma_f32_16x16x32_bf16 v[44:47], v[88:91], v[140:143], v[36:39]
	v_mfma_f32_16x16x32_bf16 v[36:39], v[88:91], v[144:147], v[176:179]
	v_lshl_add_u32 v88, s38, 8, v135
	v_cvt_pk_bf16_f32 v90, v124, v125
	v_cvt_pk_bf16_f32 v91, v126, v127
	s_waitcnt lgkmcnt(1)
	v_mfma_f32_16x16x32_bf16 v[28:31], v[148:151], v[128:131], v[28:31]
	s_waitcnt lgkmcnt(0)
; DI void st_bf4(u16* p, float a, float b, float c, float d) { *(uint2*)p = make_uint2(pk2(a, b), pk2(c, d)); }
;   template <int NT, int MT> DI void run(f32x4 (&acc)[NT][MT], int mb, int nb) const {
; #pragma unroll
;     for (int nt = 0; nt < NT; ++nt)
; #pragma unroll
;       for (int mt = 0; mt < MT; ++mt) {
;         f32x4 v = acc[nt][mt];
;         st_bf4(C + (size_t)(mb + mt * 16) * ldc + nb + nt * 16, v[0], v[1], v[2], v[3]);
;       }
;   }
	v_mfma_f32_16x16x32_bf16 v[12:15], v[152:155], v[128:131], v[12:15]
	v_or_b32_e32 v128, v88, v133
	v_ashrrev_i32_e32 v129, 31, v128
	v_lshlrev_b64 v[88:89], 11, v[128:129]
	v_lshl_add_u64 v[88:89], s[92:93], 0, v[88:89]
	v_bfe_u32 v130, v185, 4, 1
	v_mad_u32_u24 v182, v130, 24, v182
	v_lshl_add_u64 v[88:89], v[88:89], 0, v[182:183]
	v_mov_b32_e32 v160, v90
	v_mov_b32_e32 v161, v91
	v_or_b32_e32 v90, 16, v128
	v_ashrrev_i32_e32 v91, 31, v90
	v_lshlrev_b64 v[90:91], 11, v[90:91]
	v_lshl_add_u64 v[90:91], s[92:93], 0, v[90:91]
	v_lshl_add_u64 v[90:91], v[90:91], 0, v[182:183]
	v_mov_b32_e32 v172, v120
	v_mov_b32_e32 v173, v121
	v_or_b32_e32 v120, 32, v128
	v_ashrrev_i32_e32 v121, 31, v120
	v_lshlrev_b64 v[120:121], 11, v[120:121]
	v_lshl_add_u64 v[120:121], s[92:93], 0, v[120:121]
	v_lshl_add_u64 v[120:121], v[120:121], 0, v[182:183]
	v_mov_b32_e32 v176, v116
	v_mov_b32_e32 v177, v117
	v_or_b32_e32 v116, 48, v128
	v_ashrrev_i32_e32 v117, 31, v116
	v_mfma_f32_16x16x32_bf16 v[84:87], v[68:71], v[136:139], v[164:167]
	v_lshlrev_b64 v[116:117], 11, v[116:117]
	v_lshl_add_u64 v[116:117], s[92:93], 0, v[116:117]
	v_lshl_add_u64 v[116:117], v[116:117], 0, v[182:183]
	v_mfma_f32_16x16x32_bf16 v[68:71], v[68:71], v[144:147], v[168:171]
	v_mov_b32_e32 v196, v32
	v_mov_b32_e32 v197, v33
	v_cvt_pk_bf16_f32 v32, v156, v157
	v_cvt_pk_bf16_f32 v33, v158, v159
	v_mov_b32_e32 v224, v32
	v_mov_b32_e32 v225, v33
	v_cvt_pk_bf16_f32 v32, v84, v85
	v_cvt_pk_bf16_f32 v33, v86, v87
	v_mov_b32_e32 v128, v32
	v_mov_b32_e32 v129, v33
	v_cvt_pk_bf16_f32 v32, v76, v77
	v_cvt_pk_bf16_f32 v33, v78, v79
	v_mfma_f32_16x16x32_bf16 v[24:27], v[148:151], v[136:139], v[24:27]
	v_mov_b32_e32 v164, v32
	v_mov_b32_e32 v165, v33
	v_cvt_pk_bf16_f32 v32, v68, v69
	v_cvt_pk_bf16_f32 v33, v70, v71
	v_mfma_f32_16x16x32_bf16 v[20:23], v[148:151], v[140:143], v[20:23]
	v_mov_b32_e32 v156, v32
	v_mov_b32_e32 v157, v33
	v_cvt_pk_bf16_f32 v32, v60, v61
	v_cvt_pk_bf16_f32 v33, v62, v63
	v_mfma_f32_16x16x32_bf16 v[16:19], v[148:151], v[144:147], v[16:19]
	v_mov_b32_e32 v226, v32
	v_mov_b32_e32 v227, v33
	s_nop 1
	v_permlane16_swap_b32_e32 v224, v226
	v_permlane16_swap_b32_e32 v225, v227
	global_store_dwordx4 v[88:89], v[224:227], off offset:128
	v_cvt_pk_bf16_f32 v32, v52, v53
	v_cvt_pk_bf16_f32 v33, v54, v55
	v_mfma_f32_16x16x32_bf16 v[8:11], v[152:155], v[136:139], v[8:11]
	v_mov_b32_e32 v130, v32
	v_mov_b32_e32 v131, v33
	s_nop 1
	v_permlane16_swap_b32_e32 v128, v130
	v_permlane16_swap_b32_e32 v129, v131
	global_store_dwordx4 v[90:91], v[128:131], off offset:128
	v_cvt_pk_bf16_f32 v32, v44, v45
	v_cvt_pk_bf16_f32 v33, v46, v47
	v_mfma_f32_16x16x32_bf16 v[4:7], v[152:155], v[140:143], v[4:7]
	v_mov_b32_e32 v166, v32
	v_mov_b32_e32 v167, v33
	s_nop 1
	v_permlane16_swap_b32_e32 v164, v166
	v_permlane16_swap_b32_e32 v165, v167
	global_store_dwordx4 v[120:121], v[164:167], off offset:128
	v_cvt_pk_bf16_f32 v32, v36, v37
	v_cvt_pk_bf16_f32 v33, v38, v39
	v_mfma_f32_16x16x32_bf16 v[0:3], v[152:155], v[144:147], v[0:3]
	v_cvt_pk_bf16_f32 v28, v28, v29
	v_cvt_pk_bf16_f32 v29, v30, v31
	v_cvt_pk_bf16_f32 v24, v24, v25
	v_cvt_pk_bf16_f32 v25, v26, v27
	v_cvt_pk_bf16_f32 v20, v20, v21
	v_cvt_pk_bf16_f32 v21, v22, v23
	v_cvt_pk_bf16_f32 v16, v16, v17
	v_cvt_pk_bf16_f32 v17, v18, v19
	v_cvt_pk_bf16_f32 v12, v12, v13
	v_cvt_pk_bf16_f32 v13, v14, v15
	v_cvt_pk_bf16_f32 v8, v8, v9
	v_cvt_pk_bf16_f32 v9, v10, v11
	v_cvt_pk_bf16_f32 v4, v4, v5
	v_cvt_pk_bf16_f32 v5, v6, v7
	v_cvt_pk_bf16_f32 v0, v0, v1
	v_cvt_pk_bf16_f32 v1, v2, v3
	v_mov_b32_e32 v162, v108
	v_mov_b32_e32 v163, v109
	s_nop 1
	v_permlane16_swap_b32_e32 v160, v162
	v_permlane16_swap_b32_e32 v161, v163
	global_store_dwordx4 v[88:89], v[160:163], off
	v_mov_b32_e32 v174, v104
	v_mov_b32_e32 v175, v105
	s_nop 1
	v_permlane16_swap_b32_e32 v172, v174
	v_permlane16_swap_b32_e32 v173, v175
	global_store_dwordx4 v[90:91], v[172:175], off
	v_mov_b32_e32 v178, v100
	v_mov_b32_e32 v179, v101
	s_nop 1
	v_permlane16_swap_b32_e32 v176, v178
	v_permlane16_swap_b32_e32 v177, v179
	global_store_dwordx4 v[120:121], v[176:179], off
	v_mov_b32_e32 v114, v96
	v_mov_b32_e32 v115, v97
	s_nop 1
	v_permlane16_swap_b32_e32 v112, v114
	v_permlane16_swap_b32_e32 v113, v115
	global_store_dwordx4 v[116:117], v[112:115], off
	v_mov_b32_e32 v194, v64
	v_mov_b32_e32 v195, v65
	s_nop 1
	v_permlane16_swap_b32_e32 v194, v196
	v_permlane16_swap_b32_e32 v195, v197
	global_store_dwordx4 v[116:117], v[194:197], off offset:64
	v_mov_b32_e32 v94, v56
	v_mov_b32_e32 v95, v57
	s_nop 1
	v_permlane16_swap_b32_e32 v92, v94
	v_permlane16_swap_b32_e32 v93, v95
	global_store_dwordx4 v[88:89], v[92:95], off offset:64
	v_mov_b32_e32 v82, v48
	v_mov_b32_e32 v83, v49
	s_nop 1
	v_permlane16_swap_b32_e32 v80, v82
	v_permlane16_swap_b32_e32 v81, v83
	global_store_dwordx4 v[90:91], v[80:83], off offset:64
	v_mov_b32_e32 v74, v40
	v_mov_b32_e32 v75, v41
	s_nop 1
	v_permlane16_swap_b32_e32 v72, v74
	v_permlane16_swap_b32_e32 v73, v75
	global_store_dwordx4 v[120:121], v[72:75], off offset:64
	v_mov_b32_e32 v158, v32
	v_mov_b32_e32 v159, v33
	s_nop 1
	v_permlane16_swap_b32_e32 v156, v158
	v_permlane16_swap_b32_e32 v157, v159
	global_store_dwordx4 v[116:117], v[156:159], off offset:128
	v_mov_b32_e32 v30, v12
	v_mov_b32_e32 v31, v13
	s_nop 1
	v_permlane16_swap_b32_e32 v28, v30
	v_permlane16_swap_b32_e32 v29, v31
	global_store_dwordx4 v[88:89], v[28:31], off offset:192
	v_mov_b32_e32 v26, v8
	v_mov_b32_e32 v27, v9
	s_nop 1
	v_permlane16_swap_b32_e32 v24, v26
	v_permlane16_swap_b32_e32 v25, v27
	global_store_dwordx4 v[90:91], v[24:27], off offset:192
	v_mov_b32_e32 v22, v4
	v_mov_b32_e32 v23, v5
	s_nop 1
	v_permlane16_swap_b32_e32 v20, v22
	v_permlane16_swap_b32_e32 v21, v23
	global_store_dwordx4 v[120:121], v[20:23], off offset:192
	v_mov_b32_e32 v18, v0
	v_mov_b32_e32 v19, v1
	s_nop 1
	v_permlane16_swap_b32_e32 v16, v18
	v_permlane16_swap_b32_e32 v17, v19
	global_store_dwordx4 v[116:117], v[16:19], off offset:192
	s_branch .LBB0_25

; template <int BM, class Epi>
; DI void gemm_dma(const u16* __restrict__ X, long ldx, const u16* __restrict__ W, long ldw, int K, char* smem,
;                  int m0, int n0, const Epi& epi) {
;     ...
;   const int tid = get_tid(), lane = tid & 63, wave = tid >> 6;
;   const int lr = lane & 15, g = lane >> 4;
;   const int rd = lr * 64 + ((g ^ ((4 - (lr >> 2)) & 3)) << 4);
;   const int xrow0 = BIG ? wave * 64 : (wave & 1) * (BM / 2);
;   const int wrow0 = BIG ? 0 : (wave >> 1) * 64;
;   f32x4 acc[NT][MT];
;   { const float z = zero_f();
; #pragma unroll
;   for (int a = 0; a < NT; ++a)
; #pragma unroll
;     for (int b = 0; b < MT; ++b) acc[a][b] = (f32x4){z, z, z, z}; }
;   const int wu = __builtin_amdgcn_readfirstlane(wave);
;   const unsigned sbase = (unsigned)__builtin_amdgcn_readfirstlane((int)(unsigned)(size_t)smem);
;   const int r16 = lane >> 2, chunk = (lane & 3) ^ ((4 - (r16 >> 2)) & 3);
;   const u16* xs = X + (long)(wu * XD * 16 + r16) * ldx + (chunk << 3);
;   const u16* ws = W + (long)(wu * 32 + r16) * ldw + (chunk << 3);
;   const long ldx16 = 16 * ldx, ldw16 = 16 * ldw;
;   const unsigned xdst = sbase + wu * XD * 1024, wdst = sbase + BM * 64 + wu * 2048;
;     ...
;   const int nk = K >> 5;
;   __syncthreads();
; #pragma unroll
;   for (int s = 0; s < D - 1; ++s) GD_ISSUE(s)
;   int cur = 0, nxt = D - 1, kt = 0;
;   do {
;     if (kt + D - 2 < nk) wait_vm<PW * (D - 2)>(); else wait_vm<0>();
;     __syncthreads();
;     if (kt + D - 1 < nk) GD_ISSUE(nxt)
;     nxt = (nxt + 1 == D) ? 0 : nxt + 1;
;     const char* base = smem + cur * STG;
;     cur = (cur + 1 == D) ? 0 : cur + 1;
;     bf16x8 xf[MT];
; #pragma unroll
;     for (int i = 0; i < MT; ++i) xf[i] = *(const bf16x8*)(base + (xrow0 + i * 16) * 64 + rd);
; #pragma unroll
;     for (int nh = 0; nh < NT / 4; ++nh) {
;       bf16x8 wf[4];
; #pragma unroll
;       for (int i = 0; i < 4; ++i) wf[i] = *(const bf16x8*)(base + BM * 64 + (wrow0 + (nh * 4 + i) * 16) * 64 + rd);
; DI void knope_tile(const Params& p, int u, char* smem) {
;   const u16* W = (const u16*)(p.ws + OFF_W);
;   const u16* ckvb = (const u16*)(p.ws + OFF_CKVB);
;   EpiBF16 ek{(u16*)(p.ws + OFF_KN), 1024};
;   const int tm = u >> 3, tn = u & 7;
;   gemm_dma<256>(ckvb + (size_t)tm * 256 * 256, 256, W + WO_KV + (size_t)tn * 128 * 256, 256, 256, smem, tm * 256, tn * 128, ek);
; }
.LBB0_84:
	s_cmpk_gt_i32 s4, 0x77f
	s_cbranch_scc1 .LBB0_92
	s_cmpk_gt_i32 s4, 0x43f
	s_mov_b64 s[38:39], -1
	s_cbranch_scc0 .LBB0_87
	s_add_i32 s5, s4, 0xfffffcc0
	s_bfe_u32 s98, s5, 0x30003
	s_and_b32 s99, s5, 7
	s_lshl_b32 s99, s99, 3
	s_andn2_b32 s5, s5, 63
	s_or_b32 s5, s5, s99
	s_or_b32 s5, s5, s98
	s_lshr_b32 s6, s5, 3
	s_and_b32 s5, s5, 7
	s_lshl_b32 s7, s6, 17
	s_add_u32 s8, s0, s7
	s_addc_u32 s9, s1, 0
	s_lshl_b32 s7, s5, 16
	v_mov_b32_e32 v11, v185
	s_add_u32 s10, s87, s7
	s_addc_u32 s11, s90, 0
	v_readfirstlane_b32 s7, v11
	v_lshrrev_b32_e32 v6, 4, v11
	s_ashr_i32 s12, s7, 6
	v_bfe_u32 v8, v11, 2, 4
	v_sub_u32_e32 v6, 0, v6
	s_andn2_b32 s7, s7, 63
	v_lshrrev_b32_e32 v3, 2, v11
	v_xor_b32_e32 v9, v11, v6
	v_or_b32_e32 v6, s7, v8
	v_and_b32_e32 v90, 15, v11
	v_bfe_u32 v1, v11, 4, 2
	v_sub_u32_e32 v3, 0, v3
	v_ashrrev_i32_e32 v7, 31, v6
	v_lshlrev_b32_e32 v2, 6, v90
	v_bitop3_b32 v3, v1, v3, 3 bitop3:0x78
	v_lshlrev_b64 v[6:7], 9, v[6:7]
	v_lshlrev_b32_e32 v9, 4, v9
	v_lshl_or_b32 v8, s12, 5, v8
	v_lshl_or_b32 v10, v3, 4, v2
	v_mov_b32_e32 v2, v183
	v_lshl_add_u64 v[6:7], s[8:9], 0, v[6:7]
	v_and_b32_e32 v182, 48, v9
	v_ashrrev_i32_e32 v9, 31, v8
	v_lshl_add_u64 v[6:7], v[6:7], 0, v[182:183]
	v_lshlrev_b64 v[8:9], 9, v[8:9]
	s_lshl_b32 s14, s12, 12
	s_barrier
	s_mov_b32 m0, s14
	s_nop 0
	global_load_lds_dwordx4 v[6:7], off
	s_mov_b64 s[8:9], 0x2000
	v_lshl_add_u64 v[8:9], s[10:11], 0, v[8:9]
	v_lshl_add_u64 v[12:13], v[6:7], 0, s[8:9]
	s_or_b32 s15, s14, 0x400
	s_mov_b32 m0, s15
	s_nop 0
	global_load_lds_dwordx4 v[12:13], off
	s_mov_b64 s[10:11], 0x4000
	v_lshl_add_u64 v[12:13], v[6:7], 0, s[10:11]
	s_or_b32 s16, s14, 0x800
	s_mov_b32 m0, s16
	s_nop 0
	global_load_lds_dwordx4 v[12:13], off
	s_mov_b64 s[10:11], 0x6000
	s_lshl_b32 s41, s12, 11
	v_lshl_add_u64 v[12:13], v[6:7], 0, s[10:11]
	s_or_b32 s17, s14, 0xc00
	s_mov_b32 m0, s17
	s_nop 0
	global_load_lds_dwordx4 v[12:13], off
	v_lshl_add_u64 v[8:9], v[8:9], 0, v[182:183]
	s_add_i32 s13, s41, 0x4000
	s_mov_b32 m0, s13
	s_nop 0
	global_load_lds_dwordx4 v[8:9], off
	v_lshl_add_u64 v[12:13], v[8:9], 0, s[8:9]
	s_add_i32 s18, s41, 0x4400
	s_mov_b32 m0, s18
	s_nop 0
	global_load_lds_dwordx4 v[12:13], off
	v_lshl_add_u64 v[12:13], v[6:7], 0, 64
	s_add_i32 s7, s14, 0x6000
	s_mov_b32 m0, s7
	s_nop 0
	global_load_lds_dwordx4 v[12:13], off
	s_mov_b64 s[20:21], 0x2040
	v_lshl_add_u64 v[12:13], v[6:7], 0, s[20:21]
	s_add_i32 s8, s14, 0x6400
	s_mov_b32 m0, s8
	s_nop 0
	global_load_lds_dwordx4 v[12:13], off
	s_mov_b64 s[10:11], 0x4040
	v_lshl_add_u64 v[12:13], v[6:7], 0, s[10:11]
	s_add_i32 s9, s14, 0x6800
	s_mov_b32 m0, s9
	s_nop 0
	global_load_lds_dwordx4 v[12:13], off
	s_mov_b64 s[10:11], 0x6040
	v_lshl_add_u64 v[12:13], v[6:7], 0, s[10:11]
	s_add_i32 s10, s14, 0x6c00
	s_mov_b32 m0, s10
	s_nop 0
	global_load_lds_dwordx4 v[12:13], off
	v_lshl_add_u64 v[14:15], v[8:9], 0, 64
	s_add_i32 s11, s41, 0xa000
	s_mov_b32 m0, s11
	s_nop 0
	global_load_lds_dwordx4 v[14:15], off
	v_lshl_add_u64 v[12:13], v[8:9], 0, s[20:21]
	s_add_i32 s12, s41, 0xa400
	s_mov_b32 m0, s12
	s_nop 0
	global_load_lds_dwordx4 v[12:13], off
	s_waitcnt vmcnt(6)
	s_barrier
	v_lshl_add_u64 v[14:15], v[6:7], 0, s[28:29]
	s_add_i32 s19, s14, 0xc000
	s_mov_b32 m0, s19
	s_nop 0
	global_load_lds_dwordx4 v[14:15], off
	s_mov_b64 s[20:21], 0x2080
	v_lshl_add_u64 v[14:15], v[6:7], 0, s[20:21]
	s_add_i32 s34, s14, 0xc400
	s_mov_b32 m0, s34
	s_nop 0
	global_load_lds_dwordx4 v[14:15], off
	v_lshl_add_u64 v[14:15], v[6:7], 0, s[94:95]
	s_add_i32 s38, s14, 0xc800
	s_mov_b32 m0, s38
	s_nop 0
	global_load_lds_dwordx4 v[14:15], off
	s_mov_b64 s[22:23], 0x6080
	v_lshl_add_u64 v[14:15], v[6:7], 0, s[22:23]
	s_add_i32 s39, s14, 0xcc00
	s_mov_b32 m0, s39
	s_nop 0
	global_load_lds_dwordx4 v[14:15], off
	v_and_b32_e32 v91, 0xffffffc0, v11
	v_lshl_add_u64 v[12:13], v[8:9], 0, s[28:29]
	s_add_i32 s40, s41, 0x10000
	s_mov_b32 m0, s40
	s_nop 0
	global_load_lds_dwordx4 v[12:13], off
	v_lshl_add_u64 v[12:13], v[8:9], 0, s[20:21]
	s_add_i32 s41, s41, 0x10400
	s_mov_b32 m0, s41
	s_nop 0
	global_load_lds_dwordx4 v[12:13], off
	v_lshl_or_b32 v11, v91, 6, v10
	ds_read_b128 v[12:15], v11
	ds_read_b128 v[16:19], v11 offset:1024
	ds_read_b128 v[20:23], v11 offset:2048
	ds_read_b128 v[24:27], v11 offset:3072
	ds_read_b128 v[28:31], v10 offset:16384
	ds_read_b128 v[32:35], v10 offset:17408
	ds_read_b128 v[36:39], v10 offset:18432
	ds_read_b128 v[40:43], v10 offset:19456
	ds_read_b128 v[96:99], v10 offset:20480
	ds_read_b128 v[100:103], v10 offset:21504
	ds_read_b128 v[104:107], v10 offset:22528
	ds_read_b128 v[108:111], v10 offset:23552
	s_mov_b64 s[20:21], 0xc0
	v_mov_b32_e32 v3, v2
	v_mov_b32_e32 v4, v2
	v_mov_b32_e32 v5, v2
	v_lshl_add_u64 v[88:89], v[6:7], 0, s[20:21]
	v_lshl_add_u64 v[148:149], v[8:9], 0, s[20:21]
	s_waitcnt vmcnt(6)
	s_waitcnt lgkmcnt(0)
	s_barrier
; template <int BM, class Epi>
; DI void gemm_dma(const u16* __restrict__ X, long ldx, const u16* __restrict__ W, long ldw, int K, char* smem,
;                  int m0, int n0, const Epi& epi) {
;     ...
;     for (int nh = 0; nh < NT / 4; ++nh) {
;       bf16x8 wf[4];
; #pragma unroll
;       for (int i = 0; i < 4; ++i) wf[i] = *(const bf16x8*)(base + BM * 64 + (wrow0 + (nh * 4 + i) * 16) * 64 + rd);
; #pragma unroll
;       for (int i = 0; i < 4; ++i)
; #pragma unroll
;         for (int mt = 0; mt < MT; ++mt)
;           acc[nh * 4 + i][mt] = __builtin_amdgcn_mfma_f32_16x16x32_bf16(wf[i], xf[mt], acc[nh * 4 + i][mt], 0, 0, 0);
;     }
;   } while (++kt < nk);
	s_mov_b32 m0, s14
	s_nop 0
	global_load_lds_dwordx4 v[88:89], off
	s_mov_b64 s[20:21], 0x20c0
	v_mfma_f32_16x16x32_bf16 v[44:47], v[28:31], v[12:15], v[2:5]
	s_mov_b64 s[22:23], 0x40c0
	v_or_b32_e32 v174, 0x10000, v10
	v_or_b32_e32 v175, 0x10400, v10
	v_mfma_f32_16x16x32_bf16 v[48:51], v[28:31], v[16:19], v[2:5]
	v_or_b32_e32 v176, 0x10800, v10
	v_or_b32_e32 v177, 0x10c00, v10
	v_or_b32_e32 v178, 0x11000, v10
	v_mfma_f32_16x16x32_bf16 v[52:55], v[28:31], v[20:23], v[2:5]
	v_or_b32_e32 v179, 0x11400, v10
	v_or_b32_e32 v180, 0x11800, v10
	v_or_b32_e32 v181, 0x11c00, v10
	v_mfma_f32_16x16x32_bf16 v[28:31], v[28:31], v[24:27], v[2:5]
	v_lshl_add_u32 v91, s6, 8, v91
	s_lshl_b32 s5, s5, 8
	v_lshl_or_b32 v182, v1, 3, s5
	v_mfma_f32_16x16x32_bf16 v[56:59], v[32:35], v[12:15], v[2:5]
	v_mfma_f32_16x16x32_bf16 v[60:63], v[32:35], v[16:19], v[2:5]
	v_mfma_f32_16x16x32_bf16 v[64:67], v[32:35], v[20:23], v[2:5]
	v_mfma_f32_16x16x32_bf16 v[32:35], v[32:35], v[24:27], v[2:5]
	v_mfma_f32_16x16x32_bf16 v[68:71], v[36:39], v[12:15], v[2:5]
	v_mfma_f32_16x16x32_bf16 v[72:75], v[36:39], v[16:19], v[2:5]
	v_mfma_f32_16x16x32_bf16 v[76:79], v[36:39], v[20:23], v[2:5]
	v_mfma_f32_16x16x32_bf16 v[36:39], v[36:39], v[24:27], v[2:5]
	v_mfma_f32_16x16x32_bf16 v[80:83], v[40:43], v[12:15], v[2:5]
	v_mfma_f32_16x16x32_bf16 v[84:87], v[40:43], v[16:19], v[2:5]
	v_mfma_f32_16x16x32_bf16 v[92:95], v[40:43], v[20:23], v[2:5]
	v_mfma_f32_16x16x32_bf16 v[40:43], v[40:43], v[24:27], v[2:5]
	v_mfma_f32_16x16x32_bf16 v[112:115], v[96:99], v[12:15], v[2:5]
	v_mfma_f32_16x16x32_bf16 v[116:119], v[96:99], v[16:19], v[2:5]
	v_mfma_f32_16x16x32_bf16 v[120:123], v[96:99], v[20:23], v[2:5]
	v_mfma_f32_16x16x32_bf16 v[96:99], v[96:99], v[24:27], v[2:5]
	v_mfma_f32_16x16x32_bf16 v[124:127], v[100:103], v[12:15], v[2:5]
	v_mfma_f32_16x16x32_bf16 v[128:131], v[100:103], v[16:19], v[2:5]
	v_mfma_f32_16x16x32_bf16 v[132:135], v[100:103], v[20:23], v[2:5]
	v_mfma_f32_16x16x32_bf16 v[100:103], v[100:103], v[24:27], v[2:5]
	v_mfma_f32_16x16x32_bf16 v[136:139], v[104:107], v[12:15], v[2:5]
	v_mfma_f32_16x16x32_bf16 v[140:143], v[104:107], v[16:19], v[2:5]
	v_mfma_f32_16x16x32_bf16 v[144:147], v[104:107], v[20:23], v[2:5]
	v_mfma_f32_16x16x32_bf16 v[104:107], v[104:107], v[24:27], v[2:5]
	v_mfma_f32_16x16x32_bf16 v[12:15], v[108:111], v[12:15], v[2:5]
	v_mfma_f32_16x16x32_bf16 v[16:19], v[108:111], v[16:19], v[2:5]
	v_mfma_f32_16x16x32_bf16 v[20:23], v[108:111], v[20:23], v[2:5]
	v_mfma_f32_16x16x32_bf16 v[2:5], v[108:111], v[24:27], v[2:5]
	v_lshl_add_u64 v[24:25], v[6:7], 0, s[20:21]
	s_mov_b32 m0, s15
	s_nop 0
	global_load_lds_dwordx4 v[24:25], off
	v_lshl_add_u64 v[24:25], v[6:7], 0, s[22:23]
	s_mov_b32 m0, s16
	s_nop 0
	global_load_lds_dwordx4 v[24:25], off
	s_mov_b64 s[22:23], 0x60c0
	v_lshl_add_u64 v[24:25], v[6:7], 0, s[22:23]
	s_mov_b32 m0, s17
	s_nop 0
	global_load_lds_dwordx4 v[24:25], off
	v_lshl_add_u64 v[24:25], v[8:9], 0, s[20:21]
	s_mov_b32 m0, s13
	s_nop 0
	global_load_lds_dwordx4 v[148:149], off
	s_mov_b64 s[20:21], 0x100
	s_mov_b32 m0, s18
	s_nop 0
	global_load_lds_dwordx4 v[24:25], off
	ds_read_b128 v[24:27], v11 offset:24576
	ds_read_b128 v[108:111], v11 offset:25600
	ds_read_b128 v[148:151], v11 offset:26624
	ds_read_b128 v[152:155], v11 offset:27648
	ds_read_b128 v[156:159], v10 offset:40960
	ds_read_b128 v[160:163], v10 offset:41984
	ds_read_b128 v[164:167], v10 offset:43008
	ds_read_b128 v[168:171], v10 offset:44032
	s_waitcnt lgkmcnt(3)
	v_mfma_f32_16x16x32_bf16 v[44:47], v[156:159], v[24:27], v[44:47]
	v_lshl_add_u64 v[88:89], v[6:7], 0, s[20:21]
	v_lshl_add_u64 v[172:173], v[8:9], 0, s[20:21]
	s_mov_b64 s[20:21], 0x2100
	v_mfma_f32_16x16x32_bf16 v[48:51], v[156:159], v[108:111], v[48:51]
	s_mov_b64 s[22:23], 0x4100
	v_mfma_f32_16x16x32_bf16 v[52:55], v[156:159], v[148:151], v[52:55]
	v_mfma_f32_16x16x32_bf16 v[28:31], v[156:159], v[152:155], v[28:31]
	s_waitcnt lgkmcnt(2)
	v_mfma_f32_16x16x32_bf16 v[56:59], v[160:163], v[24:27], v[56:59]
	v_mfma_f32_16x16x32_bf16 v[60:63], v[160:163], v[108:111], v[60:63]
	v_mfma_f32_16x16x32_bf16 v[64:67], v[160:163], v[148:151], v[64:67]
	v_mfma_f32_16x16x32_bf16 v[32:35], v[160:163], v[152:155], v[32:35]
	s_waitcnt lgkmcnt(1)
	v_mfma_f32_16x16x32_bf16 v[68:71], v[164:167], v[24:27], v[68:71]
	v_mfma_f32_16x16x32_bf16 v[72:75], v[164:167], v[108:111], v[72:75]
	v_mfma_f32_16x16x32_bf16 v[76:79], v[164:167], v[148:151], v[76:79]
	v_mfma_f32_16x16x32_bf16 v[36:39], v[164:167], v[152:155], v[36:39]
	s_waitcnt lgkmcnt(0)
	v_mfma_f32_16x16x32_bf16 v[80:83], v[168:171], v[24:27], v[80:83]
	v_mfma_f32_16x16x32_bf16 v[84:87], v[168:171], v[108:111], v[84:87]
	v_mfma_f32_16x16x32_bf16 v[92:95], v[168:171], v[148:151], v[92:95]
	v_mfma_f32_16x16x32_bf16 v[40:43], v[168:171], v[152:155], v[40:43]
	ds_read_b128 v[156:159], v10 offset:45056
	ds_read_b128 v[160:163], v10 offset:46080
	ds_read_b128 v[164:167], v10 offset:47104
	ds_read_b128 v[168:171], v10 offset:48128
	s_waitcnt vmcnt(6)
	s_waitcnt lgkmcnt(0)
	s_barrier
; template <int N> DI void wait_vm() { asm volatile("s_waitcnt vmcnt(%0)" ::"n"(N) : "memory"); }
; template <int BM, class Epi>
; DI void gemm_dma(const u16* __restrict__ X, long ldx, const u16* __restrict__ W, long ldw, int K, char* smem,
;                  int m0, int n0, const Epi& epi) {
;     ...
;   do {
;     if (kt + D - 2 < nk) wait_vm<PW * (D - 2)>(); else wait_vm<0>();
;     __syncthreads();
;     if (kt + D - 1 < nk) GD_ISSUE(nxt)
;     nxt = (nxt + 1 == D) ? 0 : nxt + 1;
;     const char* base = smem + cur * STG;
;     cur = (cur + 1 == D) ? 0 : cur + 1;
;     bf16x8 xf[MT];
; #pragma unroll
;     for (int i = 0; i < MT; ++i) xf[i] = *(const bf16x8*)(base + (xrow0 + i * 16) * 64 + rd);
; #pragma unroll
;     for (int nh = 0; nh < NT / 4; ++nh) {
;       bf16x8 wf[4];
; #pragma unroll
;       for (int i = 0; i < 4; ++i) wf[i] = *(const bf16x8*)(base + BM * 64 + (wrow0 + (nh * 4 + i) * 16) * 64 + rd);
; #pragma unroll
;       for (int i = 0; i < 4; ++i)
; #pragma unroll
;         for (int mt = 0; mt < MT; ++mt)
;           acc[nh * 4 + i][mt] = __builtin_amdgcn_mfma_f32_16x16x32_bf16(wf[i], xf[mt], acc[nh * 4 + i][mt], 0, 0, 0);
;     }
;   } while (++kt < nk);
	s_mov_b32 m0, s7
	s_nop 0
	global_load_lds_dwordx4 v[88:89], off
	v_mfma_f32_16x16x32_bf16 v[112:115], v[156:159], v[24:27], v[112:115]
	v_mfma_f32_16x16x32_bf16 v[124:127], v[160:163], v[24:27], v[124:127]
	v_mfma_f32_16x16x32_bf16 v[136:139], v[164:167], v[24:27], v[136:139]
	v_mfma_f32_16x16x32_bf16 v[12:15], v[168:171], v[24:27], v[12:15]
	v_lshl_add_u64 v[24:25], v[6:7], 0, s[20:21]
	s_mov_b32 m0, s8
	s_nop 0
	global_load_lds_dwordx4 v[24:25], off
	v_lshl_add_u64 v[24:25], v[6:7], 0, s[22:23]
	s_mov_b32 m0, s9
	s_nop 0
	global_load_lds_dwordx4 v[24:25], off
	s_mov_b64 s[22:23], 0x6100
	v_lshl_add_u64 v[24:25], v[6:7], 0, s[22:23]
	s_mov_b32 m0, s10
	s_nop 0
	global_load_lds_dwordx4 v[24:25], off
	v_lshl_add_u64 v[24:25], v[8:9], 0, s[20:21]
	s_mov_b32 m0, s11
	s_nop 0
	global_load_lds_dwordx4 v[172:173], off
	v_mfma_f32_16x16x32_bf16 v[116:119], v[156:159], v[108:111], v[116:119]
	s_mov_b32 m0, s12
	s_nop 0
	global_load_lds_dwordx4 v[24:25], off
	s_mov_b64 s[20:21], 0x140
	v_lshl_add_u64 v[88:89], v[6:7], 0, s[20:21]
	v_mfma_f32_16x16x32_bf16 v[120:123], v[156:159], v[148:151], v[120:123]
	v_lshl_add_u64 v[172:173], v[8:9], 0, s[20:21]
	s_mov_b64 s[20:21], 0x2140
	s_mov_b64 s[22:23], 0x4140
	v_mfma_f32_16x16x32_bf16 v[96:99], v[156:159], v[152:155], v[96:99]
	v_mfma_f32_16x16x32_bf16 v[128:131], v[160:163], v[108:111], v[128:131]
	v_mfma_f32_16x16x32_bf16 v[132:135], v[160:163], v[148:151], v[132:135]
	v_mfma_f32_16x16x32_bf16 v[100:103], v[160:163], v[152:155], v[100:103]
	v_mfma_f32_16x16x32_bf16 v[140:143], v[164:167], v[108:111], v[140:143]
	v_mfma_f32_16x16x32_bf16 v[144:147], v[164:167], v[148:151], v[144:147]
	v_mfma_f32_16x16x32_bf16 v[104:107], v[164:167], v[152:155], v[104:107]
	v_mfma_f32_16x16x32_bf16 v[16:19], v[168:171], v[108:111], v[16:19]
	v_mfma_f32_16x16x32_bf16 v[20:23], v[168:171], v[148:151], v[20:23]
	v_mfma_f32_16x16x32_bf16 v[2:5], v[168:171], v[152:155], v[2:5]
	ds_read_b128 v[24:27], v11 offset:49152
	ds_read_b128 v[108:111], v11 offset:50176
	ds_read_b128 v[148:151], v11 offset:51200
	ds_read_b128 v[152:155], v11 offset:52224
	ds_read_b128 v[156:159], v174
	ds_read_b128 v[160:163], v175
	ds_read_b128 v[164:167], v176
	ds_read_b128 v[168:171], v177
	s_waitcnt lgkmcnt(3)
	v_mfma_f32_16x16x32_bf16 v[44:47], v[156:159], v[24:27], v[44:47]
	v_mfma_f32_16x16x32_bf16 v[48:51], v[156:159], v[108:111], v[48:51]
	v_mfma_f32_16x16x32_bf16 v[52:55], v[156:159], v[148:151], v[52:55]
	v_mfma_f32_16x16x32_bf16 v[28:31], v[156:159], v[152:155], v[28:31]
	ds_read_b128 v[156:159], v178
	s_waitcnt lgkmcnt(3)
	v_mfma_f32_16x16x32_bf16 v[56:59], v[160:163], v[24:27], v[56:59]
	v_mfma_f32_16x16x32_bf16 v[60:63], v[160:163], v[108:111], v[60:63]
	v_mfma_f32_16x16x32_bf16 v[64:67], v[160:163], v[148:151], v[64:67]
	v_mfma_f32_16x16x32_bf16 v[32:35], v[160:163], v[152:155], v[32:35]
	ds_read_b128 v[160:163], v179
	s_waitcnt lgkmcnt(3)
	v_mfma_f32_16x16x32_bf16 v[68:71], v[164:167], v[24:27], v[68:71]
	v_mfma_f32_16x16x32_bf16 v[72:75], v[164:167], v[108:111], v[72:75]
	v_mfma_f32_16x16x32_bf16 v[76:79], v[164:167], v[148:151], v[76:79]
	v_mfma_f32_16x16x32_bf16 v[36:39], v[164:167], v[152:155], v[36:39]
	ds_read_b128 v[164:167], v180
	s_waitcnt lgkmcnt(3)
	v_mfma_f32_16x16x32_bf16 v[80:83], v[168:171], v[24:27], v[80:83]
	v_mfma_f32_16x16x32_bf16 v[84:87], v[168:171], v[108:111], v[84:87]
	v_mfma_f32_16x16x32_bf16 v[92:95], v[168:171], v[148:151], v[92:95]
	v_mfma_f32_16x16x32_bf16 v[40:43], v[168:171], v[152:155], v[40:43]
	ds_read_b128 v[168:171], v181
	s_waitcnt vmcnt(6)
	s_waitcnt lgkmcnt(0)
	s_barrier
	s_mov_b32 m0, s19
	s_nop 0
	global_load_lds_dwordx4 v[88:89], off
	v_mfma_f32_16x16x32_bf16 v[112:115], v[156:159], v[24:27], v[112:115]
	v_mfma_f32_16x16x32_bf16 v[124:127], v[160:163], v[24:27], v[124:127]
	v_mfma_f32_16x16x32_bf16 v[136:139], v[164:167], v[24:27], v[136:139]
	v_mfma_f32_16x16x32_bf16 v[12:15], v[168:171], v[24:27], v[12:15]
	v_lshl_add_u64 v[24:25], v[6:7], 0, s[20:21]
	s_mov_b32 m0, s34
	s_nop 0
	global_load_lds_dwordx4 v[24:25], off
	v_lshl_add_u64 v[24:25], v[6:7], 0, s[22:23]
	s_mov_b32 m0, s38
	s_nop 0
	global_load_lds_dwordx4 v[24:25], off
	s_mov_b64 s[22:23], 0x6140
	v_lshl_add_u64 v[24:25], v[6:7], 0, s[22:23]
	s_mov_b32 m0, s39
	s_nop 0
	global_load_lds_dwordx4 v[24:25], off
	v_lshl_add_u64 v[24:25], v[8:9], 0, s[20:21]
	s_mov_b32 m0, s40
	s_nop 0
	global_load_lds_dwordx4 v[172:173], off
	v_mfma_f32_16x16x32_bf16 v[116:119], v[156:159], v[108:111], v[116:119]
	s_mov_b32 m0, s41
	s_nop 0
	global_load_lds_dwordx4 v[24:25], off
	s_mov_b64 s[20:21], 0x180
	v_lshl_add_u64 v[88:89], v[6:7], 0, s[20:21]
	v_mfma_f32_16x16x32_bf16 v[120:123], v[156:159], v[148:151], v[120:123]
	v_lshl_add_u64 v[172:173], v[8:9], 0, s[20:21]
	s_mov_b64 s[20:21], 0x2180
	s_mov_b64 s[38:39], 0
	v_mfma_f32_16x16x32_bf16 v[96:99], v[156:159], v[152:155], v[96:99]
	v_mfma_f32_16x16x32_bf16 v[128:131], v[160:163], v[108:111], v[128:131]
	v_mfma_f32_16x16x32_bf16 v[132:135], v[160:163], v[148:151], v[132:135]
	v_mfma_f32_16x16x32_bf16 v[100:103], v[160:163], v[152:155], v[100:103]
	v_mfma_f32_16x16x32_bf16 v[140:143], v[164:167], v[108:111], v[140:143]
	v_mfma_f32_16x16x32_bf16 v[144:147], v[164:167], v[148:151], v[144:147]
	v_mfma_f32_16x16x32_bf16 v[104:107], v[164:167], v[152:155], v[104:107]
	v_mfma_f32_16x16x32_bf16 v[16:19], v[168:171], v[108:111], v[16:19]
	v_mfma_f32_16x16x32_bf16 v[20:23], v[168:171], v[148:151], v[20:23]
	v_mfma_f32_16x16x32_bf16 v[2:5], v[168:171], v[152:155], v[2:5]
	ds_read_b128 v[24:27], v11
	ds_read_b128 v[108:111], v11 offset:1024
	ds_read_b128 v[148:151], v11 offset:2048
	ds_read_b128 v[152:155], v11 offset:3072
	ds_read_b128 v[156:159], v10 offset:16384
	ds_read_b128 v[160:163], v10 offset:17408
	ds_read_b128 v[164:167], v10 offset:18432
	ds_read_b128 v[168:171], v10 offset:19456
	s_waitcnt lgkmcnt(3)
; template <int N> DI void wait_vm() { asm volatile("s_waitcnt vmcnt(%0)" ::"n"(N) : "memory"); }
; template <int BM, class Epi>
; DI void gemm_dma(const u16* __restrict__ X, long ldx, const u16* __restrict__ W, long ldw, int K, char* smem,
;                  int m0, int n0, const Epi& epi) {
;     ...
;   do {
;     if (kt + D - 2 < nk) wait_vm<PW * (D - 2)>(); else wait_vm<0>();
;     __syncthreads();
;     if (kt + D - 1 < nk) GD_ISSUE(nxt)
;     nxt = (nxt + 1 == D) ? 0 : nxt + 1;
;     const char* base = smem + cur * STG;
;     cur = (cur + 1 == D) ? 0 : cur + 1;
;     bf16x8 xf[MT];
; #pragma unroll
;     for (int i = 0; i < MT; ++i) xf[i] = *(const bf16x8*)(base + (xrow0 + i * 16) * 64 + rd);
; #pragma unroll
;     for (int nh = 0; nh < NT / 4; ++nh) {
;       bf16x8 wf[4];
; #pragma unroll
;       for (int i = 0; i < 4; ++i) wf[i] = *(const bf16x8*)(base + BM * 64 + (wrow0 + (nh * 4 + i) * 16) * 64 + rd);
; #pragma unroll
;       for (int i = 0; i < 4; ++i)
; #pragma unroll
;         for (int mt = 0; mt < MT; ++mt)
;           acc[nh * 4 + i][mt] = __builtin_amdgcn_mfma_f32_16x16x32_bf16(wf[i], xf[mt], acc[nh * 4 + i][mt], 0, 0, 0);
;     }
;   } while (++kt < nk);
	v_mfma_f32_16x16x32_bf16 v[44:47], v[156:159], v[24:27], v[44:47]
	v_mfma_f32_16x16x32_bf16 v[48:51], v[156:159], v[108:111], v[48:51]
	v_mfma_f32_16x16x32_bf16 v[52:55], v[156:159], v[148:151], v[52:55]
	v_mfma_f32_16x16x32_bf16 v[28:31], v[156:159], v[152:155], v[28:31]
	s_waitcnt lgkmcnt(2)
	v_mfma_f32_16x16x32_bf16 v[56:59], v[160:163], v[24:27], v[56:59]
	v_mfma_f32_16x16x32_bf16 v[60:63], v[160:163], v[108:111], v[60:63]
	v_mfma_f32_16x16x32_bf16 v[64:67], v[160:163], v[148:151], v[64:67]
	v_mfma_f32_16x16x32_bf16 v[32:35], v[160:163], v[152:155], v[32:35]
	s_waitcnt lgkmcnt(1)
	v_mfma_f32_16x16x32_bf16 v[68:71], v[164:167], v[24:27], v[68:71]
	v_mfma_f32_16x16x32_bf16 v[72:75], v[164:167], v[108:111], v[72:75]
	v_mfma_f32_16x16x32_bf16 v[76:79], v[164:167], v[148:151], v[76:79]
	v_mfma_f32_16x16x32_bf16 v[36:39], v[164:167], v[152:155], v[36:39]
	s_waitcnt lgkmcnt(0)
	v_mfma_f32_16x16x32_bf16 v[80:83], v[168:171], v[24:27], v[80:83]
	v_mfma_f32_16x16x32_bf16 v[84:87], v[168:171], v[108:111], v[84:87]
	v_mfma_f32_16x16x32_bf16 v[92:95], v[168:171], v[148:151], v[92:95]
	v_mfma_f32_16x16x32_bf16 v[40:43], v[168:171], v[152:155], v[40:43]
	ds_read_b128 v[156:159], v10 offset:20480
	ds_read_b128 v[160:163], v10 offset:21504
	ds_read_b128 v[164:167], v10 offset:22528
	ds_read_b128 v[168:171], v10 offset:23552
	s_waitcnt vmcnt(6)
	s_waitcnt lgkmcnt(0)
	s_barrier
	s_mov_b32 m0, s14
	s_nop 0
	global_load_lds_dwordx4 v[88:89], off
	v_mfma_f32_16x16x32_bf16 v[112:115], v[156:159], v[24:27], v[112:115]
	v_mfma_f32_16x16x32_bf16 v[124:127], v[160:163], v[24:27], v[124:127]
	v_mfma_f32_16x16x32_bf16 v[136:139], v[164:167], v[24:27], v[136:139]
	v_mfma_f32_16x16x32_bf16 v[12:15], v[168:171], v[24:27], v[12:15]
	v_lshl_add_u64 v[24:25], v[6:7], 0, s[20:21]
	s_mov_b32 m0, s15
	s_nop 0
	global_load_lds_dwordx4 v[24:25], off
	s_mov_b64 s[14:15], 0x4180
	v_lshl_add_u64 v[24:25], v[6:7], 0, s[14:15]
	s_mov_b32 m0, s16
	s_nop 0
	global_load_lds_dwordx4 v[24:25], off
	s_mov_b64 s[14:15], 0x6180
	v_lshl_add_u64 v[24:25], v[6:7], 0, s[14:15]
	s_mov_b32 m0, s17
	s_nop 0
	global_load_lds_dwordx4 v[24:25], off
	v_lshl_add_u64 v[24:25], v[8:9], 0, s[20:21]
	s_mov_b32 m0, s13
	s_nop 0
	global_load_lds_dwordx4 v[172:173], off
	s_mov_b32 m0, s18
	s_nop 0
	global_load_lds_dwordx4 v[24:25], off
	v_mfma_f32_16x16x32_bf16 v[116:119], v[156:159], v[108:111], v[116:119]
	s_mov_b64 s[14:15], 0x1c0
	v_lshl_add_u64 v[88:89], v[6:7], 0, s[14:15]
	v_lshl_add_u64 v[172:173], v[8:9], 0, s[14:15]
	v_mfma_f32_16x16x32_bf16 v[120:123], v[156:159], v[148:151], v[120:123]
	s_mov_b64 s[14:15], 0x21c0
	s_mov_b64 s[16:17], 0x41c0
	v_mfma_f32_16x16x32_bf16 v[96:99], v[156:159], v[152:155], v[96:99]
	v_mfma_f32_16x16x32_bf16 v[128:131], v[160:163], v[108:111], v[128:131]
	v_mfma_f32_16x16x32_bf16 v[132:135], v[160:163], v[148:151], v[132:135]
	v_mfma_f32_16x16x32_bf16 v[100:103], v[160:163], v[152:155], v[100:103]
	v_mfma_f32_16x16x32_bf16 v[140:143], v[164:167], v[108:111], v[140:143]
	v_mfma_f32_16x16x32_bf16 v[144:147], v[164:167], v[148:151], v[144:147]
	v_mfma_f32_16x16x32_bf16 v[104:107], v[164:167], v[152:155], v[104:107]
	v_mfma_f32_16x16x32_bf16 v[16:19], v[168:171], v[108:111], v[16:19]
	v_mfma_f32_16x16x32_bf16 v[20:23], v[168:171], v[148:151], v[20:23]
	v_mfma_f32_16x16x32_bf16 v[2:5], v[168:171], v[152:155], v[2:5]
	ds_read_b128 v[24:27], v11 offset:24576
	ds_read_b128 v[108:111], v11 offset:25600
	ds_read_b128 v[148:151], v11 offset:26624
	ds_read_b128 v[152:155], v11 offset:27648
	ds_read_b128 v[156:159], v10 offset:40960
	ds_read_b128 v[160:163], v10 offset:41984
	ds_read_b128 v[164:167], v10 offset:43008
	ds_read_b128 v[168:171], v10 offset:44032
	s_waitcnt lgkmcnt(3)
	v_mfma_f32_16x16x32_bf16 v[44:47], v[156:159], v[24:27], v[44:47]
	v_mfma_f32_16x16x32_bf16 v[48:51], v[156:159], v[108:111], v[48:51]
	v_mfma_f32_16x16x32_bf16 v[52:55], v[156:159], v[148:151], v[52:55]
	v_mfma_f32_16x16x32_bf16 v[28:31], v[156:159], v[152:155], v[28:31]
	s_waitcnt lgkmcnt(2)
	v_mfma_f32_16x16x32_bf16 v[56:59], v[160:163], v[24:27], v[56:59]
	v_mfma_f32_16x16x32_bf16 v[60:63], v[160:163], v[108:111], v[60:63]
	v_mfma_f32_16x16x32_bf16 v[64:67], v[160:163], v[148:151], v[64:67]
	v_mfma_f32_16x16x32_bf16 v[32:35], v[160:163], v[152:155], v[32:35]
	s_waitcnt lgkmcnt(1)
	v_mfma_f32_16x16x32_bf16 v[68:71], v[164:167], v[24:27], v[68:71]
	v_mfma_f32_16x16x32_bf16 v[72:75], v[164:167], v[108:111], v[72:75]
	v_mfma_f32_16x16x32_bf16 v[76:79], v[164:167], v[148:151], v[76:79]
	v_mfma_f32_16x16x32_bf16 v[36:39], v[164:167], v[152:155], v[36:39]
	s_waitcnt lgkmcnt(0)
	v_mfma_f32_16x16x32_bf16 v[80:83], v[168:171], v[24:27], v[80:83]
	v_mfma_f32_16x16x32_bf16 v[84:87], v[168:171], v[108:111], v[84:87]
	v_mfma_f32_16x16x32_bf16 v[92:95], v[168:171], v[148:151], v[92:95]
	v_mfma_f32_16x16x32_bf16 v[40:43], v[168:171], v[152:155], v[40:43]
	ds_read_b128 v[156:159], v10 offset:45056
	ds_read_b128 v[160:163], v10 offset:46080
	ds_read_b128 v[164:167], v10 offset:47104
	ds_read_b128 v[168:171], v10 offset:48128
	s_waitcnt vmcnt(6)
	s_waitcnt lgkmcnt(0)
	s_barrier
; template <int N> DI void wait_vm() { asm volatile("s_waitcnt vmcnt(%0)" ::"n"(N) : "memory"); }
; template <int BM, class Epi>
; DI void gemm_dma(const u16* __restrict__ X, long ldx, const u16* __restrict__ W, long ldw, int K, char* smem,
;                  int m0, int n0, const Epi& epi) {
;     ...
;   do {
;     if (kt + D - 2 < nk) wait_vm<PW * (D - 2)>(); else wait_vm<0>();
;     __syncthreads();
;     if (kt + D - 1 < nk) GD_ISSUE(nxt)
;     nxt = (nxt + 1 == D) ? 0 : nxt + 1;
;     const char* base = smem + cur * STG;
;     cur = (cur + 1 == D) ? 0 : cur + 1;
;     bf16x8 xf[MT];
; #pragma unroll
;     for (int i = 0; i < MT; ++i) xf[i] = *(const bf16x8*)(base + (xrow0 + i * 16) * 64 + rd);
; #pragma unroll
;     for (int nh = 0; nh < NT / 4; ++nh) {
;       bf16x8 wf[4];
; #pragma unroll
;       for (int i = 0; i < 4; ++i) wf[i] = *(const bf16x8*)(base + BM * 64 + (wrow0 + (nh * 4 + i) * 16) * 64 + rd);
; #pragma unroll
;       for (int i = 0; i < 4; ++i)
; #pragma unroll
;         for (int mt = 0; mt < MT; ++mt)
;           acc[nh * 4 + i][mt] = __builtin_amdgcn_mfma_f32_16x16x32_bf16(wf[i], xf[mt], acc[nh * 4 + i][mt], 0, 0, 0);
;     }
;   } while (++kt < nk);
	s_mov_b32 m0, s7
	s_nop 0
	global_load_lds_dwordx4 v[88:89], off
	v_mfma_f32_16x16x32_bf16 v[112:115], v[156:159], v[24:27], v[112:115]
	v_mfma_f32_16x16x32_bf16 v[124:127], v[160:163], v[24:27], v[124:127]
	v_mfma_f32_16x16x32_bf16 v[136:139], v[164:167], v[24:27], v[136:139]
	v_mfma_f32_16x16x32_bf16 v[12:15], v[168:171], v[24:27], v[12:15]
	v_lshl_add_u64 v[24:25], v[6:7], 0, s[14:15]
	s_mov_b32 m0, s8
	s_nop 0
	global_load_lds_dwordx4 v[24:25], off
	v_lshl_add_u64 v[24:25], v[6:7], 0, s[16:17]
	s_mov_b32 m0, s9
	s_nop 0
	global_load_lds_dwordx4 v[24:25], off
	s_mov_b64 s[8:9], 0x61c0
	v_lshl_add_u64 v[6:7], v[6:7], 0, s[8:9]
	s_mov_b32 m0, s10
	s_nop 0
	global_load_lds_dwordx4 v[6:7], off
	v_lshl_add_u64 v[6:7], v[8:9], 0, s[14:15]
	s_mov_b32 m0, s11
	s_nop 0
	global_load_lds_dwordx4 v[172:173], off
	v_mfma_f32_16x16x32_bf16 v[116:119], v[156:159], v[108:111], v[116:119]
	s_mov_b32 m0, s12
	s_nop 0
	global_load_lds_dwordx4 v[6:7], off
	v_mfma_f32_16x16x32_bf16 v[120:123], v[156:159], v[148:151], v[120:123]
	v_mfma_f32_16x16x32_bf16 v[96:99], v[156:159], v[152:155], v[96:99]
	v_mfma_f32_16x16x32_bf16 v[128:131], v[160:163], v[108:111], v[128:131]
	v_mfma_f32_16x16x32_bf16 v[132:135], v[160:163], v[148:151], v[132:135]
	v_mfma_f32_16x16x32_bf16 v[100:103], v[160:163], v[152:155], v[100:103]
	v_mfma_f32_16x16x32_bf16 v[140:143], v[164:167], v[108:111], v[140:143]
	v_mfma_f32_16x16x32_bf16 v[144:147], v[164:167], v[148:151], v[144:147]
	v_mfma_f32_16x16x32_bf16 v[104:107], v[164:167], v[152:155], v[104:107]
	v_mfma_f32_16x16x32_bf16 v[16:19], v[168:171], v[108:111], v[16:19]
	v_mfma_f32_16x16x32_bf16 v[20:23], v[168:171], v[148:151], v[20:23]
	v_mfma_f32_16x16x32_bf16 v[2:5], v[168:171], v[152:155], v[2:5]
	ds_read_b128 v[6:9], v11 offset:49152
	ds_read_b128 v[24:27], v11 offset:50176
	ds_read_b128 v[108:111], v11 offset:51200
	ds_read_b128 v[148:151], v11 offset:52224
	ds_read_b128 v[152:155], v174
	ds_read_b128 v[156:159], v175
	ds_read_b128 v[160:163], v176
	ds_read_b128 v[164:167], v177
	s_waitcnt lgkmcnt(3)
	v_mfma_f32_16x16x32_bf16 v[44:47], v[152:155], v[6:9], v[44:47]
	v_mfma_f32_16x16x32_bf16 v[48:51], v[152:155], v[24:27], v[48:51]
	v_mfma_f32_16x16x32_bf16 v[52:55], v[152:155], v[108:111], v[52:55]
	v_mfma_f32_16x16x32_bf16 v[28:31], v[152:155], v[148:151], v[28:31]
	s_waitcnt lgkmcnt(2)
	v_mfma_f32_16x16x32_bf16 v[56:59], v[156:159], v[6:9], v[56:59]
	v_mfma_f32_16x16x32_bf16 v[60:63], v[156:159], v[24:27], v[60:63]
	v_mfma_f32_16x16x32_bf16 v[64:67], v[156:159], v[108:111], v[64:67]
	v_mfma_f32_16x16x32_bf16 v[32:35], v[156:159], v[148:151], v[32:35]
	s_waitcnt lgkmcnt(1)
	v_mfma_f32_16x16x32_bf16 v[68:71], v[160:163], v[6:9], v[68:71]
	v_mfma_f32_16x16x32_bf16 v[72:75], v[160:163], v[24:27], v[72:75]
	v_mfma_f32_16x16x32_bf16 v[76:79], v[160:163], v[108:111], v[76:79]
	v_mfma_f32_16x16x32_bf16 v[36:39], v[160:163], v[148:151], v[36:39]
	s_waitcnt lgkmcnt(0)
	v_mfma_f32_16x16x32_bf16 v[80:83], v[164:167], v[6:9], v[80:83]
	v_mfma_f32_16x16x32_bf16 v[84:87], v[164:167], v[24:27], v[84:87]
	v_mfma_f32_16x16x32_bf16 v[92:95], v[164:167], v[108:111], v[92:95]
	v_mfma_f32_16x16x32_bf16 v[40:43], v[164:167], v[148:151], v[40:43]
	ds_read_b128 v[152:155], v178
	ds_read_b128 v[156:159], v179
	ds_read_b128 v[160:163], v180
	ds_read_b128 v[164:167], v181
	s_waitcnt vmcnt(6)
	s_waitcnt lgkmcnt(0)
	v_mfma_f32_16x16x32_bf16 v[112:115], v[152:155], v[6:9], v[112:115]
	s_barrier
	v_mfma_f32_16x16x32_bf16 v[116:119], v[152:155], v[24:27], v[116:119]
	v_mfma_f32_16x16x32_bf16 v[120:123], v[152:155], v[108:111], v[120:123]
	v_mfma_f32_16x16x32_bf16 v[96:99], v[152:155], v[148:151], v[96:99]
	v_mfma_f32_16x16x32_bf16 v[124:127], v[156:159], v[6:9], v[124:127]
	v_mfma_f32_16x16x32_bf16 v[128:131], v[156:159], v[24:27], v[128:131]
	v_mfma_f32_16x16x32_bf16 v[132:135], v[156:159], v[108:111], v[132:135]
	v_mfma_f32_16x16x32_bf16 v[100:103], v[156:159], v[148:151], v[100:103]
	v_mfma_f32_16x16x32_bf16 v[136:139], v[160:163], v[6:9], v[136:139]
	v_mfma_f32_16x16x32_bf16 v[140:143], v[160:163], v[24:27], v[140:143]
	v_mfma_f32_16x16x32_bf16 v[144:147], v[160:163], v[108:111], v[144:147]
	v_mfma_f32_16x16x32_bf16 v[104:107], v[160:163], v[148:151], v[104:107]
	v_mfma_f32_16x16x32_bf16 v[6:9], v[164:167], v[6:9], v[12:15]
	v_mfma_f32_16x16x32_bf16 v[12:15], v[164:167], v[24:27], v[16:19]
	v_mfma_f32_16x16x32_bf16 v[16:19], v[164:167], v[108:111], v[20:23]
	v_mfma_f32_16x16x32_bf16 v[2:5], v[164:167], v[148:151], v[2:5]
	s_nop 1
	ds_read_b128 v[20:23], v10 offset:23552
	ds_read_b128 v[24:27], v10 offset:22528
	ds_read_b128 v[108:111], v10 offset:21504
	ds_read_b128 v[148:151], v10 offset:20480
	ds_read_b128 v[152:155], v10 offset:19456
	ds_read_b128 v[156:159], v10 offset:18432
	ds_read_b128 v[160:163], v10 offset:17408
	ds_read_b128 v[164:167], v10 offset:16384
	ds_read_b128 v[168:171], v11 offset:3072
	ds_read_b128 v[172:175], v11 offset:2048
	ds_read_b128 v[176:179], v11 offset:1024
	ds_read_b128 v[186:189], v11
	s_waitcnt vmcnt(0)
	s_waitcnt lgkmcnt(0)
	v_mfma_f32_16x16x32_bf16 v[44:47], v[164:167], v[186:189], v[44:47]
	s_barrier
; DI void st_bf4(u16* p, float a, float b, float c, float d) { *(uint2*)p = make_uint2(pk2(a, b), pk2(c, d)); }
; template <int BM, class Epi>
; DI void gemm_dma(const u16* __restrict__ X, long ldx, const u16* __restrict__ W, long ldw, int K, char* smem,
;                  int m0, int n0, const Epi& epi) {
;     ...
;     for (int i = 0; i < MT; ++i) xf[i] = *(const bf16x8*)(base + (xrow0 + i * 16) * 64 + rd);
; #pragma unroll
;     for (int nh = 0; nh < NT / 4; ++nh) {
;       bf16x8 wf[4];
; #pragma unroll
;       for (int i = 0; i < 4; ++i) wf[i] = *(const bf16x8*)(base + BM * 64 + (wrow0 + (nh * 4 + i) * 16) * 64 + rd);
; #pragma unroll
;       for (int i = 0; i < 4; ++i)
; #pragma unroll
;         for (int mt = 0; mt < MT; ++mt)
;           acc[nh * 4 + i][mt] = __builtin_amdgcn_mfma_f32_16x16x32_bf16(wf[i], xf[mt], acc[nh * 4 + i][mt], 0, 0, 0);
;   template <int NT, int MT> DI void run(f32x4 (&acc)[NT][MT], int mb, int nb) const {
; #pragma unroll
;     for (int nt = 0; nt < NT; ++nt)
; #pragma unroll
;       for (int mt = 0; mt < MT; ++mt) {
;         f32x4 v = acc[nt][mt];
;         st_bf4(C + (size_t)(mb + mt * 16) * ldc + nb + nt * 16, v[0], v[1], v[2], v[3]);
;       }
;   }
	v_mfma_f32_16x16x32_bf16 v[48:51], v[164:167], v[176:179], v[48:51]
	v_mfma_f32_16x16x32_bf16 v[52:55], v[164:167], v[172:175], v[52:55]
	v_mfma_f32_16x16x32_bf16 v[28:31], v[164:167], v[168:171], v[28:31]
	v_mfma_f32_16x16x32_bf16 v[56:59], v[160:163], v[186:189], v[56:59]
	v_mfma_f32_16x16x32_bf16 v[60:63], v[160:163], v[176:179], v[60:63]
	v_mfma_f32_16x16x32_bf16 v[64:67], v[160:163], v[172:175], v[64:67]
	v_mfma_f32_16x16x32_bf16 v[32:35], v[160:163], v[168:171], v[32:35]
	v_mfma_f32_16x16x32_bf16 v[68:71], v[156:159], v[186:189], v[68:71]
	v_mfma_f32_16x16x32_bf16 v[72:75], v[156:159], v[176:179], v[72:75]
	v_mfma_f32_16x16x32_bf16 v[76:79], v[156:159], v[172:175], v[76:79]
	v_mfma_f32_16x16x32_bf16 v[36:39], v[156:159], v[168:171], v[36:39]
	v_mfma_f32_16x16x32_bf16 v[156:159], v[152:155], v[186:189], v[80:83]
	v_mfma_f32_16x16x32_bf16 v[86:89], v[152:155], v[176:179], v[84:87]
	v_mfma_f32_16x16x32_bf16 v[92:95], v[152:155], v[172:175], v[92:95]
	v_mfma_f32_16x16x32_bf16 v[152:155], v[152:155], v[168:171], v[40:43]
	v_mfma_f32_16x16x32_bf16 v[112:115], v[148:151], v[186:189], v[112:115]
	v_mfma_f32_16x16x32_bf16 v[116:119], v[148:151], v[176:179], v[116:119]
	v_mfma_f32_16x16x32_bf16 v[120:123], v[148:151], v[172:175], v[120:123]
	v_mfma_f32_16x16x32_bf16 v[96:99], v[148:151], v[168:171], v[96:99]
	v_mfma_f32_16x16x32_bf16 v[124:127], v[108:111], v[186:189], v[124:127]
	v_mfma_f32_16x16x32_bf16 v[128:131], v[108:111], v[176:179], v[128:131]
	v_mfma_f32_16x16x32_bf16 v[132:135], v[108:111], v[172:175], v[132:135]
	v_mfma_f32_16x16x32_bf16 v[100:103], v[108:111], v[168:171], v[100:103]
	v_mfma_f32_16x16x32_bf16 v[108:111], v[24:27], v[186:189], v[136:139]
	v_mfma_f32_16x16x32_bf16 v[136:139], v[24:27], v[176:179], v[140:143]
	v_mfma_f32_16x16x32_bf16 v[140:143], v[24:27], v[172:175], v[144:147]
	v_mfma_f32_16x16x32_bf16 v[104:107], v[24:27], v[168:171], v[104:107]
	v_mfma_f32_16x16x32_bf16 v[6:9], v[20:23], v[186:189], v[6:9]
	v_mfma_f32_16x16x32_bf16 v[144:147], v[20:23], v[176:179], v[12:15]
	v_mfma_f32_16x16x32_bf16 v[148:151], v[20:23], v[172:175], v[16:19]
	v_mfma_f32_16x16x32_bf16 v[2:5], v[20:23], v[168:171], v[2:5]
	s_nop 0
	ds_read_b128 v[12:15], v11 offset:24576
	ds_read_b128 v[160:163], v11 offset:25600
	ds_read_b128 v[164:167], v11 offset:26624
	ds_read_b128 v[168:171], v11 offset:27648
	ds_read_b128 v[16:19], v10 offset:40960
	ds_read_b128 v[20:23], v10 offset:41984
	ds_read_b128 v[24:27], v10 offset:43008
	ds_read_b128 v[172:175], v10 offset:44032
	s_waitcnt lgkmcnt(3)
	v_mfma_f32_16x16x32_bf16 v[176:179], v[16:19], v[12:15], v[44:47]
	v_mfma_f32_16x16x32_bf16 v[186:189], v[16:19], v[160:163], v[48:51]
	v_mfma_f32_16x16x32_bf16 v[190:193], v[16:19], v[164:167], v[52:55]
	v_mfma_f32_16x16x32_bf16 v[194:197], v[16:19], v[168:171], v[28:31]
	s_waitcnt lgkmcnt(2)
	v_mfma_f32_16x16x32_bf16 v[224:227], v[20:23], v[12:15], v[56:59]
	v_mfma_f32_16x16x32_bf16 v[228:231], v[20:23], v[160:163], v[60:63]
	v_mfma_f32_16x16x32_bf16 v[232:235], v[20:23], v[164:167], v[64:67]
	v_mfma_f32_16x16x32_bf16 v[236:239], v[20:23], v[168:171], v[32:35]
	s_waitcnt lgkmcnt(1)
	v_mfma_f32_16x16x32_bf16 v[240:243], v[24:27], v[12:15], v[68:71]
	v_mfma_f32_16x16x32_bf16 v[66:69], v[24:27], v[168:171], v[36:39]
	s_waitcnt lgkmcnt(0)
	v_mfma_f32_16x16x32_bf16 v[42:45], v[172:175], v[164:167], v[92:95]
	v_mfma_f32_16x16x32_bf16 v[34:37], v[172:175], v[168:171], v[152:155]
	ds_read_b128 v[16:19], v10 offset:45056
	ds_read_b128 v[20:23], v10 offset:46080
	ds_read_b128 v[92:95], v10 offset:47104
	ds_read_b128 v[152:155], v10 offset:48128
	s_nop 0
	v_cvt_pk_bf16_f32 v66, v66, v67
	v_cvt_pk_bf16_f32 v67, v68, v69
	v_mfma_f32_16x16x32_bf16 v[82:85], v[24:27], v[160:163], v[72:75]
	v_cvt_pk_bf16_f32 v34, v34, v35
	v_cvt_pk_bf16_f32 v35, v36, v37
	v_cvt_pk_bf16_f32 v42, v42, v43
	v_mfma_f32_16x16x32_bf16 v[74:77], v[24:27], v[164:167], v[76:79]
	v_cvt_pk_bf16_f32 v43, v44, v45
	s_nop 2
	v_cvt_pk_bf16_f32 v82, v82, v83
	v_cvt_pk_bf16_f32 v83, v84, v85
	v_mfma_f32_16x16x32_bf16 v[50:53], v[172:175], v[160:163], v[86:89]
	s_waitcnt lgkmcnt(3)
	v_mfma_f32_16x16x32_bf16 v[112:115], v[16:19], v[12:15], v[112:115]
	v_cvt_pk_bf16_f32 v74, v74, v75
	v_cvt_pk_bf16_f32 v75, v76, v77
	s_nop 3
	v_cvt_pk_bf16_f32 v50, v50, v51
	v_mfma_f32_16x16x32_bf16 v[86:89], v[16:19], v[160:163], v[116:119]
	v_cvt_pk_bf16_f32 v51, v52, v53
	v_mfma_f32_16x16x32_bf16 v[78:81], v[16:19], v[164:167], v[120:123]
	v_mfma_f32_16x16x32_bf16 v[70:73], v[16:19], v[168:171], v[96:99]
	s_waitcnt lgkmcnt(2)
	v_mfma_f32_16x16x32_bf16 v[62:65], v[20:23], v[12:15], v[124:127]
	s_nop 0
	v_cvt_pk_bf16_f32 v96, v186, v187
	v_cvt_pk_bf16_f32 v97, v188, v189
	v_cvt_pk_bf16_f32 v98, v190, v191
	v_mfma_f32_16x16x32_bf16 v[54:57], v[20:23], v[160:163], v[128:131]
	v_cvt_pk_bf16_f32 v99, v192, v193
	v_mfma_f32_16x16x32_bf16 v[46:49], v[20:23], v[164:167], v[132:135]
	v_mfma_f32_16x16x32_bf16 v[38:41], v[20:23], v[168:171], v[100:103]
	s_waitcnt lgkmcnt(1)
; DI void st_bf4(u16* p, float a, float b, float c, float d) { *(uint2*)p = make_uint2(pk2(a, b), pk2(c, d)); }
;   template <int NT, int MT> DI void run(f32x4 (&acc)[NT][MT], int mb, int nb) const {
; #pragma unroll
;     for (int nt = 0; nt < NT; ++nt)
; #pragma unroll
;       for (int mt = 0; mt < MT; ++mt) {
;         f32x4 v = acc[nt][mt];
;         st_bf4(C + (size_t)(mb + mt * 16) * ldc + nb + nt * 16, v[0], v[1], v[2], v[3]);
;       }
;   }
	v_mfma_f32_16x16x32_bf16 v[30:33], v[92:95], v[12:15], v[108:111]
	v_mfma_f32_16x16x32_bf16 v[26:29], v[92:95], v[160:163], v[136:139]
	v_mfma_f32_16x16x32_bf16 v[22:25], v[92:95], v[164:167], v[140:143]
	s_nop 5
	v_cvt_pk_bf16_f32 v30, v30, v31
	v_cvt_pk_bf16_f32 v31, v32, v33
	v_cvt_pk_bf16_f32 v26, v26, v27
	v_mfma_f32_16x16x32_bf16 v[18:21], v[92:95], v[168:171], v[104:107]
	v_or_b32_e32 v94, v91, v90
	v_ashrrev_i32_e32 v95, 31, v94
	v_lshlrev_b64 v[90:91], 11, v[94:95]
	v_lshl_add_u64 v[90:91], s[92:93], 0, v[90:91]
	v_bfe_u32 v1, v185, 4, 1
	v_mad_u32_u24 v182, v1, 24, v182
	v_lshl_add_u64 v[90:91], v[90:91], 0, v[182:183]
	v_cvt_pk_bf16_f32 v92, v176, v177
	v_cvt_pk_bf16_f32 v93, v178, v179
	v_mov_b32_e32 v100, v92
	v_mov_b32_e32 v101, v93
	v_or_b32_e32 v92, 16, v94
	v_ashrrev_i32_e32 v93, 31, v92
	v_lshlrev_b64 v[92:93], 11, v[92:93]
	v_lshl_add_u64 v[92:93], s[92:93], 0, v[92:93]
	v_lshl_add_u64 v[92:93], v[92:93], 0, v[182:183]
	v_mov_b32_e32 v104, v96
	v_mov_b32_e32 v105, v97
	v_or_b32_e32 v96, 32, v94
	v_or_b32_e32 v94, 48, v94
	v_ashrrev_i32_e32 v95, 31, v94
	v_lshlrev_b64 v[94:95], 11, v[94:95]
	v_ashrrev_i32_e32 v97, 31, v96
	v_lshl_add_u64 v[94:95], s[92:93], 0, v[94:95]
	v_lshlrev_b64 v[96:97], 11, v[96:97]
	v_lshl_add_u64 v[94:95], v[94:95], 0, v[182:183]
	v_lshl_add_u64 v[96:97], s[92:93], 0, v[96:97]
	v_mov_b32_e32 v110, v34
	v_mov_b32_e32 v111, v35
	v_cvt_pk_bf16_f32 v34, v112, v113
	v_cvt_pk_bf16_f32 v35, v114, v115
	v_lshl_add_u64 v[96:97], v[96:97], 0, v[182:183]
	v_mov_b32_e32 v116, v34
	v_mov_b32_e32 v117, v35
	v_cvt_pk_bf16_f32 v34, v86, v87
	v_cvt_pk_bf16_f32 v35, v88, v89
	v_mov_b32_e32 v120, v98
	v_mov_b32_e32 v121, v99
	v_cvt_pk_bf16_f32 v98, v194, v195
	v_cvt_pk_bf16_f32 v99, v196, v197
	v_mov_b32_e32 v124, v34
	v_mov_b32_e32 v125, v35
	v_cvt_pk_bf16_f32 v34, v78, v79
	v_cvt_pk_bf16_f32 v35, v80, v81
	v_mfma_f32_16x16x32_bf16 v[58:61], v[172:175], v[12:15], v[156:159]
	v_mov_b32_e32 v112, v98
	v_mov_b32_e32 v113, v99
	v_cvt_pk_bf16_f32 v98, v224, v225
	v_cvt_pk_bf16_f32 v99, v226, v227
	s_waitcnt lgkmcnt(0)
	v_mfma_f32_16x16x32_bf16 v[14:17], v[152:155], v[12:15], v[6:9]
	v_mov_b32_e32 v84, v34
	v_mov_b32_e32 v85, v35
	v_cvt_pk_bf16_f32 v34, v70, v71
	v_cvt_pk_bf16_f32 v35, v72, v73
	v_mfma_f32_16x16x32_bf16 v[10:13], v[152:155], v[160:163], v[144:147]
	v_mov_b32_e32 v102, v98
	v_mov_b32_e32 v103, v99
	s_nop 1
	v_permlane16_swap_b32_e32 v100, v102
	v_permlane16_swap_b32_e32 v101, v103
	global_store_dwordx4 v[90:91], v[100:103], off
	v_cvt_pk_bf16_f32 v98, v228, v229
	v_cvt_pk_bf16_f32 v99, v230, v231
	v_mfma_f32_16x16x32_bf16 v[6:9], v[152:155], v[164:167], v[148:151]
	v_mov_b32_e32 v76, v34
	v_mov_b32_e32 v77, v35
	v_cvt_pk_bf16_f32 v34, v62, v63
	v_cvt_pk_bf16_f32 v35, v64, v65
	v_mfma_f32_16x16x32_bf16 v[2:5], v[152:155], v[168:171], v[2:5]
	v_mov_b32_e32 v106, v98
	v_mov_b32_e32 v107, v99
	s_nop 1
	v_permlane16_swap_b32_e32 v104, v106
	v_permlane16_swap_b32_e32 v105, v107
	global_store_dwordx4 v[92:93], v[104:107], off
	v_cvt_pk_bf16_f32 v98, v232, v233
	v_cvt_pk_bf16_f32 v99, v234, v235
	v_mov_b32_e32 v118, v34
	v_mov_b32_e32 v119, v35
	s_nop 1
	v_permlane16_swap_b32_e32 v116, v118
	v_permlane16_swap_b32_e32 v117, v119
	global_store_dwordx4 v[90:91], v[116:119], off offset:128
	v_cvt_pk_bf16_f32 v34, v54, v55
	v_cvt_pk_bf16_f32 v35, v56, v57
	v_mov_b32_e32 v122, v98
	v_mov_b32_e32 v123, v99
	s_nop 1
	v_permlane16_swap_b32_e32 v120, v122
	v_permlane16_swap_b32_e32 v121, v123
	global_store_dwordx4 v[96:97], v[120:123], off
	v_cvt_pk_bf16_f32 v98, v236, v237
	v_cvt_pk_bf16_f32 v99, v238, v239
	v_mov_b32_e32 v126, v34
	v_mov_b32_e32 v127, v35
	s_nop 1
	v_permlane16_swap_b32_e32 v124, v126
	v_permlane16_swap_b32_e32 v125, v127
	global_store_dwordx4 v[92:93], v[124:127], off offset:128
	v_cvt_pk_bf16_f32 v34, v46, v47
	v_cvt_pk_bf16_f32 v35, v48, v49
	v_mov_b32_e32 v114, v98
	v_mov_b32_e32 v115, v99
	s_nop 1
	v_permlane16_swap_b32_e32 v112, v114
	v_permlane16_swap_b32_e32 v113, v115
	global_store_dwordx4 v[94:95], v[112:115], off
	v_cvt_pk_bf16_f32 v98, v240, v241
	v_cvt_pk_bf16_f32 v99, v242, v243
	v_cvt_pk_bf16_f32 v58, v58, v59
	v_cvt_pk_bf16_f32 v59, v60, v61
	v_mov_b32_e32 v86, v34
	v_mov_b32_e32 v87, v35
	s_nop 1
	v_permlane16_swap_b32_e32 v84, v86
	v_permlane16_swap_b32_e32 v85, v87
	global_store_dwordx4 v[96:97], v[84:87], off offset:128
	v_cvt_pk_bf16_f32 v34, v38, v39
	v_cvt_pk_bf16_f32 v35, v40, v41
	v_cvt_pk_bf16_f32 v27, v28, v29
	v_cvt_pk_bf16_f32 v22, v22, v23
	v_cvt_pk_bf16_f32 v23, v24, v25
	v_cvt_pk_bf16_f32 v18, v18, v19
	v_cvt_pk_bf16_f32 v19, v20, v21
	v_cvt_pk_bf16_f32 v14, v14, v15
	v_cvt_pk_bf16_f32 v15, v16, v17
	v_cvt_pk_bf16_f32 v10, v10, v11
	v_cvt_pk_bf16_f32 v11, v12, v13
	v_cvt_pk_bf16_f32 v6, v6, v7
	v_cvt_pk_bf16_f32 v7, v8, v9
	v_cvt_pk_bf16_f32 v2, v2, v3
	v_cvt_pk_bf16_f32 v3, v4, v5
	v_mov_b32_e32 v108, v66
	v_mov_b32_e32 v109, v67
	s_nop 1
	v_permlane16_swap_b32_e32 v108, v110
	v_permlane16_swap_b32_e32 v109, v111
	global_store_dwordx4 v[94:95], v[108:111], off offset:64
	v_mov_b32_e32 v100, v58
	v_mov_b32_e32 v101, v59
	s_nop 1
	v_permlane16_swap_b32_e32 v98, v100
	v_permlane16_swap_b32_e32 v99, v101
	global_store_dwordx4 v[90:91], v[98:101], off offset:64
	v_mov_b32_e32 v84, v50
	v_mov_b32_e32 v85, v51
	s_nop 1
	v_permlane16_swap_b32_e32 v82, v84
	v_permlane16_swap_b32_e32 v83, v85
	global_store_dwordx4 v[92:93], v[82:85], off offset:64
	v_mov_b32_e32 v40, v74
	v_mov_b32_e32 v41, v75
	s_nop 1
	v_permlane16_swap_b32_e32 v40, v42
	v_permlane16_swap_b32_e32 v41, v43
	global_store_dwordx4 v[96:97], v[40:43], off offset:64
	v_mov_b32_e32 v78, v34
	v_mov_b32_e32 v79, v35
	s_nop 1
	v_permlane16_swap_b32_e32 v76, v78
	v_permlane16_swap_b32_e32 v77, v79
	global_store_dwordx4 v[94:95], v[76:79], off offset:128
	v_mov_b32_e32 v32, v14
	v_mov_b32_e32 v33, v15
	s_nop 1
	v_permlane16_swap_b32_e32 v30, v32
	v_permlane16_swap_b32_e32 v31, v33
	global_store_dwordx4 v[90:91], v[30:33], off offset:192
	v_mov_b32_e32 v28, v10
	v_mov_b32_e32 v29, v11
	s_nop 1
	v_permlane16_swap_b32_e32 v26, v28
	v_permlane16_swap_b32_e32 v27, v29
	global_store_dwordx4 v[92:93], v[26:29], off offset:192
	v_mov_b32_e32 v24, v6
	v_mov_b32_e32 v25, v7
	s_nop 1
	v_permlane16_swap_b32_e32 v22, v24
	v_permlane16_swap_b32_e32 v23, v25
	global_store_dwordx4 v[96:97], v[22:25], off offset:192
	v_mov_b32_e32 v20, v2
	v_mov_b32_e32 v21, v3
	s_nop 1
	v_permlane16_swap_b32_e32 v18, v20
	v_permlane16_swap_b32_e32 v19, v21
	global_store_dwordx4 v[94:95], v[18:21], off offset:192

; template <int BM, class Epi>
; DI void gemm_dma(const u16* __restrict__ X, long ldx, const u16* __restrict__ W, long ldw, int K, char* smem,
;                  int m0, int n0, const Epi& epi) {
;     ...
;   const int tid = get_tid(), lane = tid & 63, wave = tid >> 6;
;   const int lr = lane & 15, g = lane >> 4;
;   const int rd = lr * 64 + ((g ^ ((4 - (lr >> 2)) & 3)) << 4);
;   const int xrow0 = BIG ? wave * 64 : (wave & 1) * (BM / 2);
;   const int wrow0 = BIG ? 0 : (wave >> 1) * 64;
;   f32x4 acc[NT][MT];
;   { const float z = zero_f();
; #pragma unroll
;   for (int a = 0; a < NT; ++a)
; #pragma unroll
;     for (int b = 0; b < MT; ++b) acc[a][b] = (f32x4){z, z, z, z}; }
;   const int wu = __builtin_amdgcn_readfirstlane(wave);
;   const unsigned sbase = (unsigned)__builtin_amdgcn_readfirstlane((int)(unsigned)(size_t)smem);
;   const int r16 = lane >> 2, chunk = (lane & 3) ^ ((4 - (r16 >> 2)) & 3);
;   const u16* xs = X + (long)(wu * XD * 16 + r16) * ldx + (chunk << 3);
;   const u16* ws = W + (long)(wu * 32 + r16) * ldw + (chunk << 3);
;   const long ldx16 = 16 * ldx, ldw16 = 16 * ldw;
;   const unsigned xdst = sbase + wu * XD * 1024, wdst = sbase + BM * 64 + wu * 2048;
;     ...
;   const int nk = K >> 5;
;   __syncthreads();
; #pragma unroll
;   for (int s = 0; s < D - 1; ++s) GD_ISSUE(s)
;   int cur = 0, nxt = D - 1, kt = 0;
;   do {
;     if (kt + D - 2 < nk) wait_vm<PW * (D - 2)>(); else wait_vm<0>();
;     __syncthreads();
;     if (kt + D - 1 < nk) GD_ISSUE(nxt)
;     nxt = (nxt + 1 == D) ? 0 : nxt + 1;
;     const char* base = smem + cur * STG;
;     cur = (cur + 1 == D) ? 0 : cur + 1;
;     bf16x8 xf[MT];
; #pragma unroll
;     for (int i = 0; i < MT; ++i) xf[i] = *(const bf16x8*)(base + (xrow0 + i * 16) * 64 + rd);
; #pragma unroll
;     for (int nh = 0; nh < NT / 4; ++nh) {
;       bf16x8 wf[4];
; #pragma unroll
;       for (int i = 0; i < 4; ++i) wf[i] = *(const bf16x8*)(base + BM * 64 + (wrow0 + (nh * 4 + i) * 16) * 64 + rd);
; DI void knope_tile(const Params& p, int u, char* smem) {
;   const u16* W = (const u16*)(p.ws + OFF_W);
;   const u16* ckvb = (const u16*)(p.ws + OFF_CKVB);
;   EpiBF16 ek{(u16*)(p.ws + OFF_KN), 1024};
;   const int tm = u >> 3, tn = u & 7;
;   gemm_dma<256>(ckvb + (size_t)tm * 256 * 256, 256, W + WO_KV + (size_t)tn * 128 * 256, 256, 256, smem, tm * 256, tn * 128, ek);
; }
.LBB0_99:
	s_cmpk_gt_i32 s5, 0x62f
	s_mov_b64 s[38:39], -1
	s_cbranch_scc0 .LBB0_101
	s_add_i32 s4, s5, 0xfffff9d0
	s_bfe_u32 s98, s4, 0x30003
	s_and_b32 s99, s4, 7
	s_lshl_b32 s99, s99, 3
	s_andn2_b32 s4, s4, 63
	s_or_b32 s4, s4, s99
	s_or_b32 s4, s4, s98
	s_lshr_b32 s6, s4, 3
	s_and_b32 s4, s4, 7
	s_lshl_b32 s7, s6, 17
	s_add_u32 s8, s0, s7
	s_addc_u32 s9, s1, 0
	s_lshl_b32 s7, s4, 16
	v_mov_b32_e32 v11, v185
	s_add_u32 s10, s87, s7
	s_addc_u32 s11, s90, 0
	v_readfirstlane_b32 s7, v11
	v_lshrrev_b32_e32 v6, 4, v11
	s_ashr_i32 s12, s7, 6
	v_bfe_u32 v8, v11, 2, 4
	v_sub_u32_e32 v6, 0, v6
	s_andn2_b32 s7, s7, 63
	v_lshrrev_b32_e32 v3, 2, v11
	v_xor_b32_e32 v9, v11, v6
	v_or_b32_e32 v6, s7, v8
	v_and_b32_e32 v90, 15, v11
	v_bfe_u32 v1, v11, 4, 2
	v_sub_u32_e32 v3, 0, v3
	v_ashrrev_i32_e32 v7, 31, v6
	v_lshlrev_b32_e32 v2, 6, v90
	v_bitop3_b32 v3, v1, v3, 3 bitop3:0x78
	v_lshlrev_b64 v[6:7], 9, v[6:7]
	v_lshlrev_b32_e32 v9, 4, v9
	v_lshl_or_b32 v8, s12, 5, v8
	v_lshl_or_b32 v10, v3, 4, v2
	v_mov_b32_e32 v2, v183
	v_lshl_add_u64 v[6:7], s[8:9], 0, v[6:7]
	v_and_b32_e32 v182, 48, v9
	v_ashrrev_i32_e32 v9, 31, v8
	v_lshl_add_u64 v[6:7], v[6:7], 0, v[182:183]
	v_lshlrev_b64 v[8:9], 9, v[8:9]
	s_lshl_b32 s14, s12, 12
	s_barrier
	s_mov_b32 m0, s14
	s_nop 0
	global_load_lds_dwordx4 v[6:7], off
	s_mov_b64 s[8:9], 0x2000
	v_lshl_add_u64 v[8:9], s[10:11], 0, v[8:9]
	v_lshl_add_u64 v[12:13], v[6:7], 0, s[8:9]
	s_or_b32 s15, s14, 0x400
	s_mov_b32 m0, s15
	s_nop 0
	global_load_lds_dwordx4 v[12:13], off
	s_mov_b64 s[10:11], 0x4000
	v_lshl_add_u64 v[12:13], v[6:7], 0, s[10:11]
	s_or_b32 s16, s14, 0x800
	s_mov_b32 m0, s16
	s_nop 0
	global_load_lds_dwordx4 v[12:13], off
	s_mov_b64 s[10:11], 0x6000
	s_lshl_b32 s42, s12, 11
	v_lshl_add_u64 v[12:13], v[6:7], 0, s[10:11]
	s_or_b32 s17, s14, 0xc00
	s_mov_b32 m0, s17
	s_nop 0
	global_load_lds_dwordx4 v[12:13], off
	v_lshl_add_u64 v[8:9], v[8:9], 0, v[182:183]
	s_add_i32 s13, s42, 0x4000
	s_mov_b32 m0, s13
	s_nop 0
	global_load_lds_dwordx4 v[8:9], off
	v_lshl_add_u64 v[12:13], v[8:9], 0, s[8:9]
	s_add_i32 s18, s42, 0x4400
	s_mov_b32 m0, s18
	s_nop 0
	global_load_lds_dwordx4 v[12:13], off
	v_lshl_add_u64 v[12:13], v[6:7], 0, 64
	s_add_i32 s7, s14, 0x6000
	s_mov_b32 m0, s7
	s_nop 0
	global_load_lds_dwordx4 v[12:13], off
	s_mov_b64 s[20:21], 0x2040
	v_lshl_add_u64 v[12:13], v[6:7], 0, s[20:21]
	s_add_i32 s8, s14, 0x6400
	s_mov_b32 m0, s8
	s_nop 0
	global_load_lds_dwordx4 v[12:13], off
	s_mov_b64 s[10:11], 0x4040
	v_lshl_add_u64 v[12:13], v[6:7], 0, s[10:11]
	s_add_i32 s9, s14, 0x6800
	s_mov_b32 m0, s9
	s_nop 0
	global_load_lds_dwordx4 v[12:13], off
	s_mov_b64 s[10:11], 0x6040
	v_lshl_add_u64 v[12:13], v[6:7], 0, s[10:11]
	s_add_i32 s10, s14, 0x6c00
	s_mov_b32 m0, s10
	s_nop 0
	global_load_lds_dwordx4 v[12:13], off
	v_lshl_add_u64 v[14:15], v[8:9], 0, 64
	s_add_i32 s11, s42, 0xa000
	s_mov_b32 m0, s11
	s_nop 0
	global_load_lds_dwordx4 v[14:15], off
	v_lshl_add_u64 v[12:13], v[8:9], 0, s[20:21]
	s_add_i32 s12, s42, 0xa400
	s_mov_b32 m0, s12
	s_nop 0
	global_load_lds_dwordx4 v[12:13], off
	s_waitcnt vmcnt(6)
	s_barrier
	v_lshl_add_u64 v[14:15], v[6:7], 0, s[28:29]
	s_add_i32 s19, s14, 0xc000
	s_mov_b32 m0, s19
	s_nop 0
	global_load_lds_dwordx4 v[14:15], off
	s_mov_b64 s[20:21], 0x2080
	v_lshl_add_u64 v[14:15], v[6:7], 0, s[20:21]
	s_add_i32 s34, s14, 0xc400
	s_mov_b32 m0, s34
	s_nop 0
	global_load_lds_dwordx4 v[14:15], off
	v_lshl_add_u64 v[14:15], v[6:7], 0, s[94:95]
	s_add_i32 s38, s14, 0xc800
	s_mov_b32 m0, s38
	s_nop 0
	global_load_lds_dwordx4 v[14:15], off
	s_mov_b64 s[22:23], 0x6080
	v_lshl_add_u64 v[14:15], v[6:7], 0, s[22:23]
	s_add_i32 s43, s14, 0xcc00
	s_mov_b32 m0, s43
	s_nop 0
	global_load_lds_dwordx4 v[14:15], off
	v_and_b32_e32 v91, 0xffffffc0, v11
	v_lshl_add_u64 v[12:13], v[8:9], 0, s[28:29]
	s_add_i32 s39, s42, 0x10000
	s_mov_b32 m0, s39
	s_nop 0
	global_load_lds_dwordx4 v[12:13], off
	v_lshl_add_u64 v[12:13], v[8:9], 0, s[20:21]
	s_add_i32 s42, s42, 0x10400
	s_mov_b32 m0, s42
	s_nop 0
	global_load_lds_dwordx4 v[12:13], off
	v_lshl_or_b32 v11, v91, 6, v10
	ds_read_b128 v[12:15], v11
	s_waitcnt vmcnt(7)
	ds_read_b128 v[16:19], v11 offset:1024
	s_waitcnt vmcnt(5)
	ds_read_b128 v[20:23], v11 offset:2048
	ds_read_b128 v[24:27], v11 offset:3072
	s_waitcnt vmcnt(4)
	ds_read_b128 v[28:31], v10 offset:16384
	ds_read_b128 v[32:35], v10 offset:17408
	ds_read_b128 v[36:39], v10 offset:18432
	ds_read_b128 v[40:43], v10 offset:19456
	s_waitcnt vmcnt(0)
	ds_read_b128 v[96:99], v10 offset:20480
	ds_read_b128 v[100:103], v10 offset:21504
	ds_read_b128 v[104:107], v10 offset:22528
	ds_read_b128 v[108:111], v10 offset:23552
	s_mov_b64 s[20:21], 0xc0
	v_mov_b32_e32 v3, v2
	v_mov_b32_e32 v4, v2
	v_mov_b32_e32 v5, v2
	v_lshl_add_u64 v[88:89], v[6:7], 0, s[20:21]
	v_lshl_add_u64 v[148:149], v[8:9], 0, s[20:21]
	s_waitcnt vmcnt(6)
	s_waitcnt lgkmcnt(0)
	s_barrier
; template <int N> DI void wait_vm() { asm volatile("s_waitcnt vmcnt(%0)" ::"n"(N) : "memory"); }
; template <int BM, class Epi>
; DI void gemm_dma(const u16* __restrict__ X, long ldx, const u16* __restrict__ W, long ldw, int K, char* smem,
;                  int m0, int n0, const Epi& epi) {
;     ...
;   __syncthreads();
; #pragma unroll
;   for (int s = 0; s < D - 1; ++s) GD_ISSUE(s)
;   int cur = 0, nxt = D - 1, kt = 0;
;   do {
;     if (kt + D - 2 < nk) wait_vm<PW * (D - 2)>(); else wait_vm<0>();
;     __syncthreads();
;     if (kt + D - 1 < nk) GD_ISSUE(nxt)
;     nxt = (nxt + 1 == D) ? 0 : nxt + 1;
;     const char* base = smem + cur * STG;
;     cur = (cur + 1 == D) ? 0 : cur + 1;
;     bf16x8 xf[MT];
; #pragma unroll
;     for (int i = 0; i < MT; ++i) xf[i] = *(const bf16x8*)(base + (xrow0 + i * 16) * 64 + rd);
; #pragma unroll
;     for (int nh = 0; nh < NT / 4; ++nh) {
;       bf16x8 wf[4];
; #pragma unroll
;       for (int i = 0; i < 4; ++i) wf[i] = *(const bf16x8*)(base + BM * 64 + (wrow0 + (nh * 4 + i) * 16) * 64 + rd);
; #pragma unroll
;       for (int i = 0; i < 4; ++i)
; #pragma unroll
;         for (int mt = 0; mt < MT; ++mt)
;           acc[nh * 4 + i][mt] = __builtin_amdgcn_mfma_f32_16x16x32_bf16(wf[i], xf[mt], acc[nh * 4 + i][mt], 0, 0, 0);
;     }
;   } while (++kt < nk);
	s_mov_b32 m0, s14
	s_nop 0
	global_load_lds_dwordx4 v[88:89], off
	s_mov_b64 s[20:21], 0x20c0
	v_mfma_f32_16x16x32_bf16 v[44:47], v[28:31], v[12:15], v[2:5]
	s_mov_b64 s[22:23], 0x40c0
	v_or_b32_e32 v174, 0x10000, v10
	v_or_b32_e32 v175, 0x10400, v10
	v_mfma_f32_16x16x32_bf16 v[48:51], v[28:31], v[16:19], v[2:5]
	v_or_b32_e32 v176, 0x10800, v10
	v_or_b32_e32 v177, 0x10c00, v10
	v_or_b32_e32 v178, 0x11000, v10
	v_mfma_f32_16x16x32_bf16 v[52:55], v[28:31], v[20:23], v[2:5]
	v_or_b32_e32 v179, 0x11400, v10
	v_or_b32_e32 v180, 0x11800, v10
	v_or_b32_e32 v181, 0x11c00, v10
	v_mfma_f32_16x16x32_bf16 v[28:31], v[28:31], v[24:27], v[2:5]
	v_lshl_add_u32 v91, s6, 8, v91
	s_lshl_b32 s4, s4, 8
	v_lshl_or_b32 v182, v1, 3, s4
	v_mfma_f32_16x16x32_bf16 v[56:59], v[32:35], v[12:15], v[2:5]
	v_mfma_f32_16x16x32_bf16 v[60:63], v[32:35], v[16:19], v[2:5]
	v_mfma_f32_16x16x32_bf16 v[64:67], v[32:35], v[20:23], v[2:5]
	v_mfma_f32_16x16x32_bf16 v[32:35], v[32:35], v[24:27], v[2:5]
	v_mfma_f32_16x16x32_bf16 v[68:71], v[36:39], v[12:15], v[2:5]
	v_mfma_f32_16x16x32_bf16 v[72:75], v[36:39], v[16:19], v[2:5]
	v_mfma_f32_16x16x32_bf16 v[76:79], v[36:39], v[20:23], v[2:5]
	v_mfma_f32_16x16x32_bf16 v[36:39], v[36:39], v[24:27], v[2:5]
	v_mfma_f32_16x16x32_bf16 v[80:83], v[40:43], v[12:15], v[2:5]
	v_mfma_f32_16x16x32_bf16 v[84:87], v[40:43], v[16:19], v[2:5]
	v_mfma_f32_16x16x32_bf16 v[92:95], v[40:43], v[20:23], v[2:5]
	v_mfma_f32_16x16x32_bf16 v[40:43], v[40:43], v[24:27], v[2:5]
	v_mfma_f32_16x16x32_bf16 v[112:115], v[96:99], v[12:15], v[2:5]
	v_mfma_f32_16x16x32_bf16 v[116:119], v[96:99], v[16:19], v[2:5]
	v_mfma_f32_16x16x32_bf16 v[120:123], v[96:99], v[20:23], v[2:5]
	v_mfma_f32_16x16x32_bf16 v[96:99], v[96:99], v[24:27], v[2:5]
	v_mfma_f32_16x16x32_bf16 v[124:127], v[100:103], v[12:15], v[2:5]
	v_mfma_f32_16x16x32_bf16 v[128:131], v[100:103], v[16:19], v[2:5]
	v_mfma_f32_16x16x32_bf16 v[132:135], v[100:103], v[20:23], v[2:5]
	v_mfma_f32_16x16x32_bf16 v[100:103], v[100:103], v[24:27], v[2:5]
	v_mfma_f32_16x16x32_bf16 v[136:139], v[104:107], v[12:15], v[2:5]
	v_mfma_f32_16x16x32_bf16 v[140:143], v[104:107], v[16:19], v[2:5]
	v_mfma_f32_16x16x32_bf16 v[144:147], v[104:107], v[20:23], v[2:5]
	v_mfma_f32_16x16x32_bf16 v[104:107], v[104:107], v[24:27], v[2:5]
	v_mfma_f32_16x16x32_bf16 v[12:15], v[108:111], v[12:15], v[2:5]
	v_mfma_f32_16x16x32_bf16 v[16:19], v[108:111], v[16:19], v[2:5]
	v_mfma_f32_16x16x32_bf16 v[20:23], v[108:111], v[20:23], v[2:5]
	v_mfma_f32_16x16x32_bf16 v[2:5], v[108:111], v[24:27], v[2:5]
	v_lshl_add_u64 v[24:25], v[6:7], 0, s[20:21]
	s_mov_b32 m0, s15
	s_nop 0
	global_load_lds_dwordx4 v[24:25], off
	v_lshl_add_u64 v[24:25], v[6:7], 0, s[22:23]
	s_mov_b32 m0, s16
	s_nop 0
	global_load_lds_dwordx4 v[24:25], off
	s_mov_b64 s[22:23], 0x60c0
	v_lshl_add_u64 v[24:25], v[6:7], 0, s[22:23]
	s_mov_b32 m0, s17
	s_nop 0
	global_load_lds_dwordx4 v[24:25], off
	v_lshl_add_u64 v[24:25], v[8:9], 0, s[20:21]
	s_mov_b32 m0, s13
	s_nop 0
	global_load_lds_dwordx4 v[148:149], off
	s_mov_b64 s[20:21], 0x100
	s_mov_b32 m0, s18
	s_nop 0
	global_load_lds_dwordx4 v[24:25], off
	ds_read_b128 v[24:27], v11 offset:24576
	ds_read_b128 v[108:111], v11 offset:25600
	ds_read_b128 v[148:151], v11 offset:26624
	ds_read_b128 v[152:155], v11 offset:27648
	ds_read_b128 v[156:159], v10 offset:40960
	ds_read_b128 v[160:163], v10 offset:41984
	ds_read_b128 v[164:167], v10 offset:43008
	ds_read_b128 v[168:171], v10 offset:44032
	s_waitcnt lgkmcnt(3)
	v_mfma_f32_16x16x32_bf16 v[44:47], v[156:159], v[24:27], v[44:47]
	v_lshl_add_u64 v[88:89], v[6:7], 0, s[20:21]
	v_lshl_add_u64 v[172:173], v[8:9], 0, s[20:21]
	s_mov_b64 s[20:21], 0x2100
	v_mfma_f32_16x16x32_bf16 v[48:51], v[156:159], v[108:111], v[48:51]
	s_mov_b64 s[22:23], 0x4100
	v_mfma_f32_16x16x32_bf16 v[52:55], v[156:159], v[148:151], v[52:55]
	v_mfma_f32_16x16x32_bf16 v[28:31], v[156:159], v[152:155], v[28:31]
	s_waitcnt lgkmcnt(2)
	v_mfma_f32_16x16x32_bf16 v[56:59], v[160:163], v[24:27], v[56:59]
	v_mfma_f32_16x16x32_bf16 v[60:63], v[160:163], v[108:111], v[60:63]
	v_mfma_f32_16x16x32_bf16 v[64:67], v[160:163], v[148:151], v[64:67]
	v_mfma_f32_16x16x32_bf16 v[32:35], v[160:163], v[152:155], v[32:35]
	s_waitcnt lgkmcnt(1)
	v_mfma_f32_16x16x32_bf16 v[68:71], v[164:167], v[24:27], v[68:71]
	v_mfma_f32_16x16x32_bf16 v[72:75], v[164:167], v[108:111], v[72:75]
	v_mfma_f32_16x16x32_bf16 v[76:79], v[164:167], v[148:151], v[76:79]
	v_mfma_f32_16x16x32_bf16 v[36:39], v[164:167], v[152:155], v[36:39]
	s_waitcnt lgkmcnt(0)
	v_mfma_f32_16x16x32_bf16 v[80:83], v[168:171], v[24:27], v[80:83]
	v_mfma_f32_16x16x32_bf16 v[84:87], v[168:171], v[108:111], v[84:87]
	v_mfma_f32_16x16x32_bf16 v[92:95], v[168:171], v[148:151], v[92:95]
	v_mfma_f32_16x16x32_bf16 v[40:43], v[168:171], v[152:155], v[40:43]
	ds_read_b128 v[156:159], v10 offset:45056
	ds_read_b128 v[160:163], v10 offset:46080
	ds_read_b128 v[164:167], v10 offset:47104
	ds_read_b128 v[168:171], v10 offset:48128
	s_waitcnt vmcnt(6)
	s_waitcnt lgkmcnt(0)
	s_barrier
; template <int N> DI void wait_vm() { asm volatile("s_waitcnt vmcnt(%0)" ::"n"(N) : "memory"); }
; template <int BM, class Epi>
; DI void gemm_dma(const u16* __restrict__ X, long ldx, const u16* __restrict__ W, long ldw, int K, char* smem,
;                  int m0, int n0, const Epi& epi) {
;     ...
;   const int nk = K >> 5;
;   __syncthreads();
; #pragma unroll
;   for (int s = 0; s < D - 1; ++s) GD_ISSUE(s)
;   int cur = 0, nxt = D - 1, kt = 0;
;   do {
;     if (kt + D - 2 < nk) wait_vm<PW * (D - 2)>(); else wait_vm<0>();
;     __syncthreads();
;     if (kt + D - 1 < nk) GD_ISSUE(nxt)
;     nxt = (nxt + 1 == D) ? 0 : nxt + 1;
;     const char* base = smem + cur * STG;
;     cur = (cur + 1 == D) ? 0 : cur + 1;
;     bf16x8 xf[MT];
; #pragma unroll
;     for (int i = 0; i < MT; ++i) xf[i] = *(const bf16x8*)(base + (xrow0 + i * 16) * 64 + rd);
; #pragma unroll
;     for (int nh = 0; nh < NT / 4; ++nh) {
;       bf16x8 wf[4];
; #pragma unroll
;       for (int i = 0; i < 4; ++i) wf[i] = *(const bf16x8*)(base + BM * 64 + (wrow0 + (nh * 4 + i) * 16) * 64 + rd);
; #pragma unroll
;       for (int i = 0; i < 4; ++i)
; #pragma unroll
;         for (int mt = 0; mt < MT; ++mt)
;           acc[nh * 4 + i][mt] = __builtin_amdgcn_mfma_f32_16x16x32_bf16(wf[i], xf[mt], acc[nh * 4 + i][mt], 0, 0, 0);
;     }
;   } while (++kt < nk);
	s_mov_b32 m0, s7
	s_nop 0
	global_load_lds_dwordx4 v[88:89], off
	v_mfma_f32_16x16x32_bf16 v[112:115], v[156:159], v[24:27], v[112:115]
	v_mfma_f32_16x16x32_bf16 v[124:127], v[160:163], v[24:27], v[124:127]
	v_mfma_f32_16x16x32_bf16 v[136:139], v[164:167], v[24:27], v[136:139]
	v_mfma_f32_16x16x32_bf16 v[12:15], v[168:171], v[24:27], v[12:15]
	v_lshl_add_u64 v[24:25], v[6:7], 0, s[20:21]
	s_mov_b32 m0, s8
	s_nop 0
	global_load_lds_dwordx4 v[24:25], off
	v_lshl_add_u64 v[24:25], v[6:7], 0, s[22:23]
	s_mov_b32 m0, s9
	s_nop 0
	global_load_lds_dwordx4 v[24:25], off
	s_mov_b64 s[22:23], 0x6100
	v_lshl_add_u64 v[24:25], v[6:7], 0, s[22:23]
	s_mov_b32 m0, s10
	s_nop 0
	global_load_lds_dwordx4 v[24:25], off
	v_lshl_add_u64 v[24:25], v[8:9], 0, s[20:21]
	s_mov_b32 m0, s11
	s_nop 0
	global_load_lds_dwordx4 v[172:173], off
	v_mfma_f32_16x16x32_bf16 v[116:119], v[156:159], v[108:111], v[116:119]
	s_mov_b32 m0, s12
	s_nop 0
	global_load_lds_dwordx4 v[24:25], off
	s_mov_b64 s[20:21], 0x140
	v_lshl_add_u64 v[88:89], v[6:7], 0, s[20:21]
	v_mfma_f32_16x16x32_bf16 v[120:123], v[156:159], v[148:151], v[120:123]
	v_lshl_add_u64 v[172:173], v[8:9], 0, s[20:21]
	s_mov_b64 s[20:21], 0x2140
	s_mov_b64 s[22:23], 0x4140
	v_mfma_f32_16x16x32_bf16 v[96:99], v[156:159], v[152:155], v[96:99]
	v_mfma_f32_16x16x32_bf16 v[128:131], v[160:163], v[108:111], v[128:131]
	v_mfma_f32_16x16x32_bf16 v[132:135], v[160:163], v[148:151], v[132:135]
	v_mfma_f32_16x16x32_bf16 v[100:103], v[160:163], v[152:155], v[100:103]
	v_mfma_f32_16x16x32_bf16 v[140:143], v[164:167], v[108:111], v[140:143]
	v_mfma_f32_16x16x32_bf16 v[144:147], v[164:167], v[148:151], v[144:147]
	v_mfma_f32_16x16x32_bf16 v[104:107], v[164:167], v[152:155], v[104:107]
	v_mfma_f32_16x16x32_bf16 v[16:19], v[168:171], v[108:111], v[16:19]
	v_mfma_f32_16x16x32_bf16 v[20:23], v[168:171], v[148:151], v[20:23]
	v_mfma_f32_16x16x32_bf16 v[2:5], v[168:171], v[152:155], v[2:5]
	ds_read_b128 v[24:27], v11 offset:49152
	ds_read_b128 v[108:111], v11 offset:50176
	ds_read_b128 v[148:151], v11 offset:51200
	ds_read_b128 v[152:155], v11 offset:52224
	ds_read_b128 v[156:159], v174
	ds_read_b128 v[160:163], v175
	ds_read_b128 v[164:167], v176
	ds_read_b128 v[168:171], v177
	s_waitcnt lgkmcnt(3)
	v_mfma_f32_16x16x32_bf16 v[44:47], v[156:159], v[24:27], v[44:47]
	v_mfma_f32_16x16x32_bf16 v[48:51], v[156:159], v[108:111], v[48:51]
	v_mfma_f32_16x16x32_bf16 v[52:55], v[156:159], v[148:151], v[52:55]
	v_mfma_f32_16x16x32_bf16 v[28:31], v[156:159], v[152:155], v[28:31]
	ds_read_b128 v[156:159], v178
	s_waitcnt lgkmcnt(3)
	v_mfma_f32_16x16x32_bf16 v[56:59], v[160:163], v[24:27], v[56:59]
	v_mfma_f32_16x16x32_bf16 v[60:63], v[160:163], v[108:111], v[60:63]
	v_mfma_f32_16x16x32_bf16 v[64:67], v[160:163], v[148:151], v[64:67]
	v_mfma_f32_16x16x32_bf16 v[32:35], v[160:163], v[152:155], v[32:35]
	ds_read_b128 v[160:163], v179
	s_waitcnt lgkmcnt(3)
	v_mfma_f32_16x16x32_bf16 v[68:71], v[164:167], v[24:27], v[68:71]
	v_mfma_f32_16x16x32_bf16 v[72:75], v[164:167], v[108:111], v[72:75]
	v_mfma_f32_16x16x32_bf16 v[76:79], v[164:167], v[148:151], v[76:79]
	v_mfma_f32_16x16x32_bf16 v[36:39], v[164:167], v[152:155], v[36:39]
	ds_read_b128 v[164:167], v180
	s_waitcnt lgkmcnt(3)
	v_mfma_f32_16x16x32_bf16 v[80:83], v[168:171], v[24:27], v[80:83]
	v_mfma_f32_16x16x32_bf16 v[84:87], v[168:171], v[108:111], v[84:87]
	v_mfma_f32_16x16x32_bf16 v[92:95], v[168:171], v[148:151], v[92:95]
	v_mfma_f32_16x16x32_bf16 v[40:43], v[168:171], v[152:155], v[40:43]
	ds_read_b128 v[168:171], v181
	s_waitcnt vmcnt(6)
	s_waitcnt lgkmcnt(0)
	s_barrier
	s_mov_b32 m0, s19
	s_nop 0
	global_load_lds_dwordx4 v[88:89], off
	v_mfma_f32_16x16x32_bf16 v[112:115], v[156:159], v[24:27], v[112:115]
	v_mfma_f32_16x16x32_bf16 v[124:127], v[160:163], v[24:27], v[124:127]
	v_mfma_f32_16x16x32_bf16 v[136:139], v[164:167], v[24:27], v[136:139]
	v_mfma_f32_16x16x32_bf16 v[12:15], v[168:171], v[24:27], v[12:15]
	v_lshl_add_u64 v[24:25], v[6:7], 0, s[20:21]
	s_mov_b32 m0, s34
	s_nop 0
	global_load_lds_dwordx4 v[24:25], off
	v_lshl_add_u64 v[24:25], v[6:7], 0, s[22:23]
	s_mov_b32 m0, s38
	s_nop 0
	global_load_lds_dwordx4 v[24:25], off
	s_mov_b64 s[22:23], 0x6140
	v_lshl_add_u64 v[24:25], v[6:7], 0, s[22:23]
	s_mov_b32 m0, s43
	s_nop 0
	global_load_lds_dwordx4 v[24:25], off
	v_lshl_add_u64 v[24:25], v[8:9], 0, s[20:21]
	s_mov_b32 m0, s39
	s_nop 0
	global_load_lds_dwordx4 v[172:173], off
	v_mfma_f32_16x16x32_bf16 v[116:119], v[156:159], v[108:111], v[116:119]
	s_mov_b32 m0, s42
	s_nop 0
	global_load_lds_dwordx4 v[24:25], off
	s_mov_b64 s[20:21], 0x180
	v_lshl_add_u64 v[88:89], v[6:7], 0, s[20:21]
	v_mfma_f32_16x16x32_bf16 v[120:123], v[156:159], v[148:151], v[120:123]
	v_lshl_add_u64 v[172:173], v[8:9], 0, s[20:21]
	s_mov_b64 s[20:21], 0x2180
	s_mov_b64 s[38:39], 0
	v_mfma_f32_16x16x32_bf16 v[96:99], v[156:159], v[152:155], v[96:99]
	v_mfma_f32_16x16x32_bf16 v[128:131], v[160:163], v[108:111], v[128:131]
	v_mfma_f32_16x16x32_bf16 v[132:135], v[160:163], v[148:151], v[132:135]
	v_mfma_f32_16x16x32_bf16 v[100:103], v[160:163], v[152:155], v[100:103]
	v_mfma_f32_16x16x32_bf16 v[140:143], v[164:167], v[108:111], v[140:143]
	v_mfma_f32_16x16x32_bf16 v[144:147], v[164:167], v[148:151], v[144:147]
	v_mfma_f32_16x16x32_bf16 v[104:107], v[164:167], v[152:155], v[104:107]
	v_mfma_f32_16x16x32_bf16 v[16:19], v[168:171], v[108:111], v[16:19]
	v_mfma_f32_16x16x32_bf16 v[20:23], v[168:171], v[148:151], v[20:23]
	v_mfma_f32_16x16x32_bf16 v[2:5], v[168:171], v[152:155], v[2:5]
	ds_read_b128 v[24:27], v11
	ds_read_b128 v[108:111], v11 offset:1024
	ds_read_b128 v[148:151], v11 offset:2048
	ds_read_b128 v[152:155], v11 offset:3072
	ds_read_b128 v[156:159], v10 offset:16384
	ds_read_b128 v[160:163], v10 offset:17408
	ds_read_b128 v[164:167], v10 offset:18432
	ds_read_b128 v[168:171], v10 offset:19456
	s_waitcnt lgkmcnt(3)
; template <int N> DI void wait_vm() { asm volatile("s_waitcnt vmcnt(%0)" ::"n"(N) : "memory"); }
; template <int BM, class Epi>
; DI void gemm_dma(const u16* __restrict__ X, long ldx, const u16* __restrict__ W, long ldw, int K, char* smem,
;                  int m0, int n0, const Epi& epi) {
;     ...
;   const int nk = K >> 5;
;   __syncthreads();
; #pragma unroll
;   for (int s = 0; s < D - 1; ++s) GD_ISSUE(s)
;   int cur = 0, nxt = D - 1, kt = 0;
;   do {
;     if (kt + D - 2 < nk) wait_vm<PW * (D - 2)>(); else wait_vm<0>();
;     __syncthreads();
;     if (kt + D - 1 < nk) GD_ISSUE(nxt)
;     nxt = (nxt + 1 == D) ? 0 : nxt + 1;
;     const char* base = smem + cur * STG;
;     cur = (cur + 1 == D) ? 0 : cur + 1;
;     bf16x8 xf[MT];
; #pragma unroll
;     for (int i = 0; i < MT; ++i) xf[i] = *(const bf16x8*)(base + (xrow0 + i * 16) * 64 + rd);
; #pragma unroll
;     for (int nh = 0; nh < NT / 4; ++nh) {
;       bf16x8 wf[4];
; #pragma unroll
;       for (int i = 0; i < 4; ++i) wf[i] = *(const bf16x8*)(base + BM * 64 + (wrow0 + (nh * 4 + i) * 16) * 64 + rd);
; #pragma unroll
;       for (int i = 0; i < 4; ++i)
; #pragma unroll
;         for (int mt = 0; mt < MT; ++mt)
;           acc[nh * 4 + i][mt] = __builtin_amdgcn_mfma_f32_16x16x32_bf16(wf[i], xf[mt], acc[nh * 4 + i][mt], 0, 0, 0);
;     }
;   } while (++kt < nk);
	v_mfma_f32_16x16x32_bf16 v[44:47], v[156:159], v[24:27], v[44:47]
	v_mfma_f32_16x16x32_bf16 v[48:51], v[156:159], v[108:111], v[48:51]
	v_mfma_f32_16x16x32_bf16 v[52:55], v[156:159], v[148:151], v[52:55]
	v_mfma_f32_16x16x32_bf16 v[28:31], v[156:159], v[152:155], v[28:31]
	s_waitcnt lgkmcnt(2)
	v_mfma_f32_16x16x32_bf16 v[56:59], v[160:163], v[24:27], v[56:59]
	v_mfma_f32_16x16x32_bf16 v[60:63], v[160:163], v[108:111], v[60:63]
	v_mfma_f32_16x16x32_bf16 v[64:67], v[160:163], v[148:151], v[64:67]
	v_mfma_f32_16x16x32_bf16 v[32:35], v[160:163], v[152:155], v[32:35]
	s_waitcnt lgkmcnt(1)
	v_mfma_f32_16x16x32_bf16 v[68:71], v[164:167], v[24:27], v[68:71]
	v_mfma_f32_16x16x32_bf16 v[72:75], v[164:167], v[108:111], v[72:75]
	v_mfma_f32_16x16x32_bf16 v[76:79], v[164:167], v[148:151], v[76:79]
	v_mfma_f32_16x16x32_bf16 v[36:39], v[164:167], v[152:155], v[36:39]
	s_waitcnt lgkmcnt(0)
	v_mfma_f32_16x16x32_bf16 v[80:83], v[168:171], v[24:27], v[80:83]
	v_mfma_f32_16x16x32_bf16 v[84:87], v[168:171], v[108:111], v[84:87]
	v_mfma_f32_16x16x32_bf16 v[92:95], v[168:171], v[148:151], v[92:95]
	v_mfma_f32_16x16x32_bf16 v[40:43], v[168:171], v[152:155], v[40:43]
	ds_read_b128 v[156:159], v10 offset:20480
	ds_read_b128 v[160:163], v10 offset:21504
	ds_read_b128 v[164:167], v10 offset:22528
	ds_read_b128 v[168:171], v10 offset:23552
	s_waitcnt vmcnt(6)
	s_waitcnt lgkmcnt(0)
	s_barrier
	s_mov_b32 m0, s14
	s_nop 0
	global_load_lds_dwordx4 v[88:89], off
	v_mfma_f32_16x16x32_bf16 v[112:115], v[156:159], v[24:27], v[112:115]
	v_mfma_f32_16x16x32_bf16 v[124:127], v[160:163], v[24:27], v[124:127]
	v_mfma_f32_16x16x32_bf16 v[136:139], v[164:167], v[24:27], v[136:139]
	v_mfma_f32_16x16x32_bf16 v[12:15], v[168:171], v[24:27], v[12:15]
	v_lshl_add_u64 v[24:25], v[6:7], 0, s[20:21]
	s_mov_b32 m0, s15
	s_nop 0
	global_load_lds_dwordx4 v[24:25], off
	s_mov_b64 s[14:15], 0x4180
	v_lshl_add_u64 v[24:25], v[6:7], 0, s[14:15]
	s_mov_b32 m0, s16
	s_nop 0
	global_load_lds_dwordx4 v[24:25], off
	s_mov_b64 s[14:15], 0x6180
	v_lshl_add_u64 v[24:25], v[6:7], 0, s[14:15]
	s_mov_b32 m0, s17
	s_nop 0
	global_load_lds_dwordx4 v[24:25], off
	v_lshl_add_u64 v[24:25], v[8:9], 0, s[20:21]
	s_mov_b32 m0, s13
	s_nop 0
	global_load_lds_dwordx4 v[172:173], off
	s_mov_b32 m0, s18
	s_nop 0
	global_load_lds_dwordx4 v[24:25], off
	v_mfma_f32_16x16x32_bf16 v[116:119], v[156:159], v[108:111], v[116:119]
	s_mov_b64 s[14:15], 0x1c0
	v_lshl_add_u64 v[88:89], v[6:7], 0, s[14:15]
	v_lshl_add_u64 v[172:173], v[8:9], 0, s[14:15]
	v_mfma_f32_16x16x32_bf16 v[120:123], v[156:159], v[148:151], v[120:123]
	s_mov_b64 s[14:15], 0x21c0
	s_mov_b64 s[16:17], 0x41c0
	v_mfma_f32_16x16x32_bf16 v[96:99], v[156:159], v[152:155], v[96:99]
	v_mfma_f32_16x16x32_bf16 v[128:131], v[160:163], v[108:111], v[128:131]
	v_mfma_f32_16x16x32_bf16 v[132:135], v[160:163], v[148:151], v[132:135]
	v_mfma_f32_16x16x32_bf16 v[100:103], v[160:163], v[152:155], v[100:103]
	v_mfma_f32_16x16x32_bf16 v[140:143], v[164:167], v[108:111], v[140:143]
	v_mfma_f32_16x16x32_bf16 v[144:147], v[164:167], v[148:151], v[144:147]
	v_mfma_f32_16x16x32_bf16 v[104:107], v[164:167], v[152:155], v[104:107]
	v_mfma_f32_16x16x32_bf16 v[16:19], v[168:171], v[108:111], v[16:19]
	v_mfma_f32_16x16x32_bf16 v[20:23], v[168:171], v[148:151], v[20:23]
	v_mfma_f32_16x16x32_bf16 v[2:5], v[168:171], v[152:155], v[2:5]
	ds_read_b128 v[24:27], v11 offset:24576
	ds_read_b128 v[108:111], v11 offset:25600
	ds_read_b128 v[148:151], v11 offset:26624
	ds_read_b128 v[152:155], v11 offset:27648
	ds_read_b128 v[156:159], v10 offset:40960
	ds_read_b128 v[160:163], v10 offset:41984
	ds_read_b128 v[164:167], v10 offset:43008
	ds_read_b128 v[168:171], v10 offset:44032
	s_waitcnt lgkmcnt(3)
	v_mfma_f32_16x16x32_bf16 v[44:47], v[156:159], v[24:27], v[44:47]
	v_mfma_f32_16x16x32_bf16 v[48:51], v[156:159], v[108:111], v[48:51]
	v_mfma_f32_16x16x32_bf16 v[52:55], v[156:159], v[148:151], v[52:55]
	v_mfma_f32_16x16x32_bf16 v[28:31], v[156:159], v[152:155], v[28:31]
	s_waitcnt lgkmcnt(2)
	v_mfma_f32_16x16x32_bf16 v[56:59], v[160:163], v[24:27], v[56:59]
	v_mfma_f32_16x16x32_bf16 v[60:63], v[160:163], v[108:111], v[60:63]
	v_mfma_f32_16x16x32_bf16 v[64:67], v[160:163], v[148:151], v[64:67]
	v_mfma_f32_16x16x32_bf16 v[32:35], v[160:163], v[152:155], v[32:35]
	s_waitcnt lgkmcnt(1)
	v_mfma_f32_16x16x32_bf16 v[68:71], v[164:167], v[24:27], v[68:71]
	v_mfma_f32_16x16x32_bf16 v[72:75], v[164:167], v[108:111], v[72:75]
	v_mfma_f32_16x16x32_bf16 v[76:79], v[164:167], v[148:151], v[76:79]
	v_mfma_f32_16x16x32_bf16 v[36:39], v[164:167], v[152:155], v[36:39]
	s_waitcnt lgkmcnt(0)
	v_mfma_f32_16x16x32_bf16 v[80:83], v[168:171], v[24:27], v[80:83]
	v_mfma_f32_16x16x32_bf16 v[84:87], v[168:171], v[108:111], v[84:87]
	v_mfma_f32_16x16x32_bf16 v[92:95], v[168:171], v[148:151], v[92:95]
	v_mfma_f32_16x16x32_bf16 v[40:43], v[168:171], v[152:155], v[40:43]
	ds_read_b128 v[156:159], v10 offset:45056
	ds_read_b128 v[160:163], v10 offset:46080
	ds_read_b128 v[164:167], v10 offset:47104
	ds_read_b128 v[168:171], v10 offset:48128
	s_waitcnt vmcnt(6)
	s_waitcnt lgkmcnt(0)
	s_barrier
; template <int N> DI void wait_vm() { asm volatile("s_waitcnt vmcnt(%0)" ::"n"(N) : "memory"); }
; template <int BM, class Epi>
; DI void gemm_dma(const u16* __restrict__ X, long ldx, const u16* __restrict__ W, long ldw, int K, char* smem,
;                  int m0, int n0, const Epi& epi) {
;     ...
;   const int nk = K >> 5;
;   __syncthreads();
; #pragma unroll
;   for (int s = 0; s < D - 1; ++s) GD_ISSUE(s)
;   int cur = 0, nxt = D - 1, kt = 0;
;   do {
;     if (kt + D - 2 < nk) wait_vm<PW * (D - 2)>(); else wait_vm<0>();
;     __syncthreads();
;     if (kt + D - 1 < nk) GD_ISSUE(nxt)
;     nxt = (nxt + 1 == D) ? 0 : nxt + 1;
;     const char* base = smem + cur * STG;
;     cur = (cur + 1 == D) ? 0 : cur + 1;
;     bf16x8 xf[MT];
; #pragma unroll
;     for (int i = 0; i < MT; ++i) xf[i] = *(const bf16x8*)(base + (xrow0 + i * 16) * 64 + rd);
; #pragma unroll
;     for (int nh = 0; nh < NT / 4; ++nh) {
;       bf16x8 wf[4];
; #pragma unroll
;       for (int i = 0; i < 4; ++i) wf[i] = *(const bf16x8*)(base + BM * 64 + (wrow0 + (nh * 4 + i) * 16) * 64 + rd);
; #pragma unroll
;       for (int i = 0; i < 4; ++i)
; #pragma unroll
;         for (int mt = 0; mt < MT; ++mt)
;           acc[nh * 4 + i][mt] = __builtin_amdgcn_mfma_f32_16x16x32_bf16(wf[i], xf[mt], acc[nh * 4 + i][mt], 0, 0, 0);
;     }
;   } while (++kt < nk);
	s_mov_b32 m0, s7
	s_nop 0
	global_load_lds_dwordx4 v[88:89], off
	v_mfma_f32_16x16x32_bf16 v[112:115], v[156:159], v[24:27], v[112:115]
	v_mfma_f32_16x16x32_bf16 v[124:127], v[160:163], v[24:27], v[124:127]
	v_mfma_f32_16x16x32_bf16 v[136:139], v[164:167], v[24:27], v[136:139]
	v_mfma_f32_16x16x32_bf16 v[12:15], v[168:171], v[24:27], v[12:15]
	v_lshl_add_u64 v[24:25], v[6:7], 0, s[14:15]
	s_mov_b32 m0, s8
	s_nop 0
	global_load_lds_dwordx4 v[24:25], off
	v_lshl_add_u64 v[24:25], v[6:7], 0, s[16:17]
	s_mov_b32 m0, s9
	s_nop 0
	global_load_lds_dwordx4 v[24:25], off
	s_mov_b64 s[8:9], 0x61c0
	v_lshl_add_u64 v[6:7], v[6:7], 0, s[8:9]
	s_mov_b32 m0, s10
	s_nop 0
	global_load_lds_dwordx4 v[6:7], off
	v_lshl_add_u64 v[6:7], v[8:9], 0, s[14:15]
	s_mov_b32 m0, s11
	s_nop 0
	global_load_lds_dwordx4 v[172:173], off
	v_mfma_f32_16x16x32_bf16 v[116:119], v[156:159], v[108:111], v[116:119]
	s_mov_b32 m0, s12
	s_nop 0
	global_load_lds_dwordx4 v[6:7], off
	v_readlane_b32 s8, v255, 5
	v_readlane_b32 s14, v255, 11
	v_mfma_f32_16x16x32_bf16 v[120:123], v[156:159], v[148:151], v[120:123]
	v_readlane_b32 s9, v255, 6
	v_readlane_b32 s10, v255, 7
	v_readlane_b32 s11, v255, 8
	v_mfma_f32_16x16x32_bf16 v[96:99], v[156:159], v[152:155], v[96:99]
	v_readlane_b32 s12, v255, 9
	v_readlane_b32 s13, v255, 10
	v_readlane_b32 s15, v255, 12
	v_mfma_f32_16x16x32_bf16 v[128:131], v[160:163], v[108:111], v[128:131]
	s_add_i32 s4, s5, s14
	v_mfma_f32_16x16x32_bf16 v[132:135], v[160:163], v[148:151], v[132:135]
	v_mfma_f32_16x16x32_bf16 v[100:103], v[160:163], v[152:155], v[100:103]
	v_mfma_f32_16x16x32_bf16 v[140:143], v[164:167], v[108:111], v[140:143]
	v_mfma_f32_16x16x32_bf16 v[144:147], v[164:167], v[148:151], v[144:147]
	v_mfma_f32_16x16x32_bf16 v[104:107], v[164:167], v[152:155], v[104:107]
	v_mfma_f32_16x16x32_bf16 v[16:19], v[168:171], v[108:111], v[16:19]
	v_mfma_f32_16x16x32_bf16 v[20:23], v[168:171], v[148:151], v[20:23]
	v_mfma_f32_16x16x32_bf16 v[2:5], v[168:171], v[152:155], v[2:5]
	ds_read_b128 v[6:9], v11 offset:49152
	ds_read_b128 v[24:27], v11 offset:50176
	ds_read_b128 v[108:111], v11 offset:51200
	ds_read_b128 v[148:151], v11 offset:52224
	ds_read_b128 v[152:155], v174
	ds_read_b128 v[156:159], v175
	ds_read_b128 v[160:163], v176
	ds_read_b128 v[164:167], v177
	s_waitcnt lgkmcnt(3)
	v_mfma_f32_16x16x32_bf16 v[44:47], v[152:155], v[6:9], v[44:47]
	v_mfma_f32_16x16x32_bf16 v[48:51], v[152:155], v[24:27], v[48:51]
	v_mfma_f32_16x16x32_bf16 v[52:55], v[152:155], v[108:111], v[52:55]
	v_mfma_f32_16x16x32_bf16 v[28:31], v[152:155], v[148:151], v[28:31]
	s_waitcnt lgkmcnt(2)
	v_mfma_f32_16x16x32_bf16 v[56:59], v[156:159], v[6:9], v[56:59]
	v_mfma_f32_16x16x32_bf16 v[60:63], v[156:159], v[24:27], v[60:63]
	v_mfma_f32_16x16x32_bf16 v[64:67], v[156:159], v[108:111], v[64:67]
	v_mfma_f32_16x16x32_bf16 v[32:35], v[156:159], v[148:151], v[32:35]
	s_waitcnt lgkmcnt(1)
	v_mfma_f32_16x16x32_bf16 v[68:71], v[160:163], v[6:9], v[68:71]
	v_mfma_f32_16x16x32_bf16 v[72:75], v[160:163], v[24:27], v[72:75]
	v_mfma_f32_16x16x32_bf16 v[76:79], v[160:163], v[108:111], v[76:79]
	v_mfma_f32_16x16x32_bf16 v[36:39], v[160:163], v[148:151], v[36:39]
	s_waitcnt lgkmcnt(0)
	v_mfma_f32_16x16x32_bf16 v[80:83], v[164:167], v[6:9], v[80:83]
	v_mfma_f32_16x16x32_bf16 v[84:87], v[164:167], v[24:27], v[84:87]
	v_mfma_f32_16x16x32_bf16 v[92:95], v[164:167], v[108:111], v[92:95]
	v_mfma_f32_16x16x32_bf16 v[40:43], v[164:167], v[148:151], v[40:43]
	ds_read_b128 v[152:155], v178
	ds_read_b128 v[156:159], v179
	ds_read_b128 v[160:163], v180
	ds_read_b128 v[164:167], v181
	s_waitcnt vmcnt(6)
	s_waitcnt lgkmcnt(0)
	v_mfma_f32_16x16x32_bf16 v[112:115], v[152:155], v[6:9], v[112:115]
	s_barrier
	v_mfma_f32_16x16x32_bf16 v[116:119], v[152:155], v[24:27], v[116:119]
	v_mfma_f32_16x16x32_bf16 v[120:123], v[152:155], v[108:111], v[120:123]
	v_mfma_f32_16x16x32_bf16 v[96:99], v[152:155], v[148:151], v[96:99]
	v_mfma_f32_16x16x32_bf16 v[124:127], v[156:159], v[6:9], v[124:127]
	v_mfma_f32_16x16x32_bf16 v[128:131], v[156:159], v[24:27], v[128:131]
	v_mfma_f32_16x16x32_bf16 v[132:135], v[156:159], v[108:111], v[132:135]
	v_mfma_f32_16x16x32_bf16 v[100:103], v[156:159], v[148:151], v[100:103]
	v_mfma_f32_16x16x32_bf16 v[136:139], v[160:163], v[6:9], v[136:139]
	v_mfma_f32_16x16x32_bf16 v[140:143], v[160:163], v[24:27], v[140:143]
	v_mfma_f32_16x16x32_bf16 v[144:147], v[160:163], v[108:111], v[144:147]
	v_mfma_f32_16x16x32_bf16 v[104:107], v[160:163], v[148:151], v[104:107]
	v_mfma_f32_16x16x32_bf16 v[6:9], v[164:167], v[6:9], v[12:15]
	v_mfma_f32_16x16x32_bf16 v[12:15], v[164:167], v[24:27], v[16:19]
	v_mfma_f32_16x16x32_bf16 v[16:19], v[164:167], v[108:111], v[20:23]
	v_mfma_f32_16x16x32_bf16 v[2:5], v[164:167], v[148:151], v[2:5]
	s_nop 1
	ds_read_b128 v[20:23], v10 offset:23552
	ds_read_b128 v[24:27], v10 offset:22528
	ds_read_b128 v[108:111], v10 offset:21504
	ds_read_b128 v[148:151], v10 offset:20480
	ds_read_b128 v[152:155], v10 offset:19456
	ds_read_b128 v[156:159], v10 offset:18432
	ds_read_b128 v[160:163], v10 offset:17408
	ds_read_b128 v[164:167], v10 offset:16384
	ds_read_b128 v[168:171], v11 offset:3072
	ds_read_b128 v[172:175], v11 offset:2048
	ds_read_b128 v[176:179], v11 offset:1024
	ds_read_b128 v[186:189], v11
	s_waitcnt vmcnt(0)
	s_waitcnt lgkmcnt(0)
	v_mfma_f32_16x16x32_bf16 v[44:47], v[164:167], v[186:189], v[44:47]
	s_barrier
; template <int N> DI void wait_vm() { asm volatile("s_waitcnt vmcnt(%0)" ::"n"(N) : "memory"); }
; DI void st_bf4(u16* p, float a, float b, float c, float d) { *(uint2*)p = make_uint2(pk2(a, b), pk2(c, d)); }
; template <int BM, class Epi>
; DI void gemm_dma(const u16* __restrict__ X, long ldx, const u16* __restrict__ W, long ldw, int K, char* smem,
;                  int m0, int n0, const Epi& epi) {
;     ...
;   do {
;     if (kt + D - 2 < nk) wait_vm<PW * (D - 2)>(); else wait_vm<0>();
;     __syncthreads();
;     if (kt + D - 1 < nk) GD_ISSUE(nxt)
;     nxt = (nxt + 1 == D) ? 0 : nxt + 1;
;     const char* base = smem + cur * STG;
;     cur = (cur + 1 == D) ? 0 : cur + 1;
;     bf16x8 xf[MT];
; #pragma unroll
;     for (int i = 0; i < MT; ++i) xf[i] = *(const bf16x8*)(base + (xrow0 + i * 16) * 64 + rd);
; #pragma unroll
;     for (int nh = 0; nh < NT / 4; ++nh) {
;       bf16x8 wf[4];
; #pragma unroll
;       for (int i = 0; i < 4; ++i) wf[i] = *(const bf16x8*)(base + BM * 64 + (wrow0 + (nh * 4 + i) * 16) * 64 + rd);
; #pragma unroll
;       for (int i = 0; i < 4; ++i)
; #pragma unroll
;         for (int mt = 0; mt < MT; ++mt)
;           acc[nh * 4 + i][mt] = __builtin_amdgcn_mfma_f32_16x16x32_bf16(wf[i], xf[mt], acc[nh * 4 + i][mt], 0, 0, 0);
;     }
;   } while (++kt < nk);
;   template <int NT, int MT> DI void run(f32x4 (&acc)[NT][MT], int mb, int nb) const {
; #pragma unroll
;     for (int nt = 0; nt < NT; ++nt)
; #pragma unroll
;       for (int mt = 0; mt < MT; ++mt) {
;         f32x4 v = acc[nt][mt];
;         st_bf4(C + (size_t)(mb + mt * 16) * ldc + nb + nt * 16, v[0], v[1], v[2], v[3]);
;       }
;   }
	v_mfma_f32_16x16x32_bf16 v[48:51], v[164:167], v[176:179], v[48:51]
	v_mfma_f32_16x16x32_bf16 v[52:55], v[164:167], v[172:175], v[52:55]
	v_mfma_f32_16x16x32_bf16 v[28:31], v[164:167], v[168:171], v[28:31]
	v_mfma_f32_16x16x32_bf16 v[56:59], v[160:163], v[186:189], v[56:59]
	v_mfma_f32_16x16x32_bf16 v[60:63], v[160:163], v[176:179], v[60:63]
	v_mfma_f32_16x16x32_bf16 v[64:67], v[160:163], v[172:175], v[64:67]
	v_mfma_f32_16x16x32_bf16 v[32:35], v[160:163], v[168:171], v[32:35]
	v_mfma_f32_16x16x32_bf16 v[68:71], v[156:159], v[186:189], v[68:71]
	v_mfma_f32_16x16x32_bf16 v[72:75], v[156:159], v[176:179], v[72:75]
	v_mfma_f32_16x16x32_bf16 v[76:79], v[156:159], v[172:175], v[76:79]
	v_mfma_f32_16x16x32_bf16 v[36:39], v[156:159], v[168:171], v[36:39]
	v_mfma_f32_16x16x32_bf16 v[156:159], v[152:155], v[186:189], v[80:83]
	v_mfma_f32_16x16x32_bf16 v[86:89], v[152:155], v[176:179], v[84:87]
	v_mfma_f32_16x16x32_bf16 v[92:95], v[152:155], v[172:175], v[92:95]
	v_mfma_f32_16x16x32_bf16 v[152:155], v[152:155], v[168:171], v[40:43]
	v_mfma_f32_16x16x32_bf16 v[112:115], v[148:151], v[186:189], v[112:115]
	v_mfma_f32_16x16x32_bf16 v[116:119], v[148:151], v[176:179], v[116:119]
	v_mfma_f32_16x16x32_bf16 v[120:123], v[148:151], v[172:175], v[120:123]
	v_mfma_f32_16x16x32_bf16 v[96:99], v[148:151], v[168:171], v[96:99]
	v_mfma_f32_16x16x32_bf16 v[124:127], v[108:111], v[186:189], v[124:127]
	v_mfma_f32_16x16x32_bf16 v[128:131], v[108:111], v[176:179], v[128:131]
	v_mfma_f32_16x16x32_bf16 v[132:135], v[108:111], v[172:175], v[132:135]
	v_mfma_f32_16x16x32_bf16 v[100:103], v[108:111], v[168:171], v[100:103]
	v_mfma_f32_16x16x32_bf16 v[108:111], v[24:27], v[186:189], v[136:139]
	v_mfma_f32_16x16x32_bf16 v[136:139], v[24:27], v[176:179], v[140:143]
	v_mfma_f32_16x16x32_bf16 v[140:143], v[24:27], v[172:175], v[144:147]
	v_mfma_f32_16x16x32_bf16 v[104:107], v[24:27], v[168:171], v[104:107]
	v_mfma_f32_16x16x32_bf16 v[6:9], v[20:23], v[186:189], v[6:9]
	v_mfma_f32_16x16x32_bf16 v[144:147], v[20:23], v[176:179], v[12:15]
	v_mfma_f32_16x16x32_bf16 v[148:151], v[20:23], v[172:175], v[16:19]
	v_mfma_f32_16x16x32_bf16 v[2:5], v[20:23], v[168:171], v[2:5]
	s_nop 0
	ds_read_b128 v[12:15], v11 offset:24576
	ds_read_b128 v[160:163], v11 offset:25600
	ds_read_b128 v[164:167], v11 offset:26624
	ds_read_b128 v[168:171], v11 offset:27648
	ds_read_b128 v[16:19], v10 offset:40960
	ds_read_b128 v[20:23], v10 offset:41984
	ds_read_b128 v[24:27], v10 offset:43008
	ds_read_b128 v[172:175], v10 offset:44032
	s_waitcnt lgkmcnt(3)
	v_mfma_f32_16x16x32_bf16 v[176:179], v[16:19], v[12:15], v[44:47]
	v_mfma_f32_16x16x32_bf16 v[186:189], v[16:19], v[160:163], v[48:51]
	v_mfma_f32_16x16x32_bf16 v[190:193], v[16:19], v[164:167], v[52:55]
	v_mfma_f32_16x16x32_bf16 v[194:197], v[16:19], v[168:171], v[28:31]
	s_waitcnt lgkmcnt(2)
	v_mfma_f32_16x16x32_bf16 v[224:227], v[20:23], v[12:15], v[56:59]
	v_mfma_f32_16x16x32_bf16 v[228:231], v[20:23], v[160:163], v[60:63]
	v_mfma_f32_16x16x32_bf16 v[232:235], v[20:23], v[164:167], v[64:67]
	v_mfma_f32_16x16x32_bf16 v[236:239], v[20:23], v[168:171], v[32:35]
	s_waitcnt lgkmcnt(1)
	v_mfma_f32_16x16x32_bf16 v[240:243], v[24:27], v[12:15], v[68:71]
	v_mfma_f32_16x16x32_bf16 v[66:69], v[24:27], v[168:171], v[36:39]
	s_waitcnt lgkmcnt(0)
	v_mfma_f32_16x16x32_bf16 v[42:45], v[172:175], v[164:167], v[92:95]
	v_mfma_f32_16x16x32_bf16 v[34:37], v[172:175], v[168:171], v[152:155]
	ds_read_b128 v[16:19], v10 offset:45056
	ds_read_b128 v[20:23], v10 offset:46080
	ds_read_b128 v[92:95], v10 offset:47104
	ds_read_b128 v[152:155], v10 offset:48128
	s_nop 0
	v_cvt_pk_bf16_f32 v66, v66, v67
	v_cvt_pk_bf16_f32 v67, v68, v69
	v_mfma_f32_16x16x32_bf16 v[82:85], v[24:27], v[160:163], v[72:75]
	v_cvt_pk_bf16_f32 v34, v34, v35
	v_cvt_pk_bf16_f32 v35, v36, v37
	v_cvt_pk_bf16_f32 v42, v42, v43
	v_mfma_f32_16x16x32_bf16 v[74:77], v[24:27], v[164:167], v[76:79]
	v_cvt_pk_bf16_f32 v43, v44, v45
	s_nop 2
	v_cvt_pk_bf16_f32 v82, v82, v83
	v_cvt_pk_bf16_f32 v83, v84, v85
	v_mfma_f32_16x16x32_bf16 v[50:53], v[172:175], v[160:163], v[86:89]
	s_waitcnt lgkmcnt(3)
	v_mfma_f32_16x16x32_bf16 v[112:115], v[16:19], v[12:15], v[112:115]
	v_cvt_pk_bf16_f32 v74, v74, v75
	v_cvt_pk_bf16_f32 v75, v76, v77
	s_nop 3
	v_cvt_pk_bf16_f32 v50, v50, v51
	v_mfma_f32_16x16x32_bf16 v[86:89], v[16:19], v[160:163], v[116:119]
	v_cvt_pk_bf16_f32 v51, v52, v53
	v_mfma_f32_16x16x32_bf16 v[78:81], v[16:19], v[164:167], v[120:123]
	v_mfma_f32_16x16x32_bf16 v[70:73], v[16:19], v[168:171], v[96:99]
	s_waitcnt lgkmcnt(2)
	v_mfma_f32_16x16x32_bf16 v[62:65], v[20:23], v[12:15], v[124:127]
	s_nop 0
	v_cvt_pk_bf16_f32 v96, v186, v187
	v_cvt_pk_bf16_f32 v97, v188, v189
	v_cvt_pk_bf16_f32 v98, v190, v191
	v_mfma_f32_16x16x32_bf16 v[54:57], v[20:23], v[160:163], v[128:131]
	v_cvt_pk_bf16_f32 v99, v192, v193
	v_mfma_f32_16x16x32_bf16 v[46:49], v[20:23], v[164:167], v[132:135]
	v_mfma_f32_16x16x32_bf16 v[38:41], v[20:23], v[168:171], v[100:103]
	s_waitcnt lgkmcnt(1)
; DI void st_bf4(u16* p, float a, float b, float c, float d) { *(uint2*)p = make_uint2(pk2(a, b), pk2(c, d)); }
;   template <int NT, int MT> DI void run(f32x4 (&acc)[NT][MT], int mb, int nb) const {
; #pragma unroll
;     for (int nt = 0; nt < NT; ++nt)
; #pragma unroll
;       for (int mt = 0; mt < MT; ++mt) {
;         f32x4 v = acc[nt][mt];
;         st_bf4(C + (size_t)(mb + mt * 16) * ldc + nb + nt * 16, v[0], v[1], v[2], v[3]);
;       }
;   }
	v_mfma_f32_16x16x32_bf16 v[30:33], v[92:95], v[12:15], v[108:111]
	v_mfma_f32_16x16x32_bf16 v[26:29], v[92:95], v[160:163], v[136:139]
	v_mfma_f32_16x16x32_bf16 v[22:25], v[92:95], v[164:167], v[140:143]
	s_nop 5
	v_cvt_pk_bf16_f32 v30, v30, v31
	v_cvt_pk_bf16_f32 v31, v32, v33
	v_cvt_pk_bf16_f32 v26, v26, v27
	v_mfma_f32_16x16x32_bf16 v[18:21], v[92:95], v[168:171], v[104:107]
	v_or_b32_e32 v94, v91, v90
	v_ashrrev_i32_e32 v95, 31, v94
	v_lshlrev_b64 v[90:91], 11, v[94:95]
	v_lshl_add_u64 v[90:91], s[92:93], 0, v[90:91]
	v_bfe_u32 v1, v185, 4, 1
	v_mad_u32_u24 v182, v1, 24, v182
	v_lshl_add_u64 v[90:91], v[90:91], 0, v[182:183]
	v_cvt_pk_bf16_f32 v92, v176, v177
	v_cvt_pk_bf16_f32 v93, v178, v179
	v_mov_b32_e32 v100, v92
	v_mov_b32_e32 v101, v93
	v_or_b32_e32 v92, 16, v94
	v_ashrrev_i32_e32 v93, 31, v92
	v_lshlrev_b64 v[92:93], 11, v[92:93]
	v_lshl_add_u64 v[92:93], s[92:93], 0, v[92:93]
	v_lshl_add_u64 v[92:93], v[92:93], 0, v[182:183]
	v_mov_b32_e32 v104, v96
	v_mov_b32_e32 v105, v97
	v_or_b32_e32 v96, 32, v94
	v_or_b32_e32 v94, 48, v94
	v_ashrrev_i32_e32 v95, 31, v94
	v_lshlrev_b64 v[94:95], 11, v[94:95]
	v_ashrrev_i32_e32 v97, 31, v96
	v_lshl_add_u64 v[94:95], s[92:93], 0, v[94:95]
	v_lshlrev_b64 v[96:97], 11, v[96:97]
	v_lshl_add_u64 v[94:95], v[94:95], 0, v[182:183]
	v_lshl_add_u64 v[96:97], s[92:93], 0, v[96:97]
	v_mov_b32_e32 v110, v34
	v_mov_b32_e32 v111, v35
	v_cvt_pk_bf16_f32 v34, v112, v113
	v_cvt_pk_bf16_f32 v35, v114, v115
	v_lshl_add_u64 v[96:97], v[96:97], 0, v[182:183]
	v_mov_b32_e32 v116, v34
	v_mov_b32_e32 v117, v35
	v_cvt_pk_bf16_f32 v34, v86, v87
	v_cvt_pk_bf16_f32 v35, v88, v89
	v_mov_b32_e32 v120, v98
	v_mov_b32_e32 v121, v99
	v_cvt_pk_bf16_f32 v98, v194, v195
	v_cvt_pk_bf16_f32 v99, v196, v197
	v_mov_b32_e32 v124, v34
	v_mov_b32_e32 v125, v35
	v_cvt_pk_bf16_f32 v34, v78, v79
	v_cvt_pk_bf16_f32 v35, v80, v81
	v_mfma_f32_16x16x32_bf16 v[58:61], v[172:175], v[12:15], v[156:159]
	v_mov_b32_e32 v112, v98
	v_mov_b32_e32 v113, v99
	v_cvt_pk_bf16_f32 v98, v224, v225
	v_cvt_pk_bf16_f32 v99, v226, v227
	s_waitcnt lgkmcnt(0)
	v_mfma_f32_16x16x32_bf16 v[14:17], v[152:155], v[12:15], v[6:9]
	v_mov_b32_e32 v84, v34
	v_mov_b32_e32 v85, v35
	v_cvt_pk_bf16_f32 v34, v70, v71
	v_cvt_pk_bf16_f32 v35, v72, v73
	v_mfma_f32_16x16x32_bf16 v[10:13], v[152:155], v[160:163], v[144:147]
	v_mov_b32_e32 v102, v98
	v_mov_b32_e32 v103, v99
	s_nop 1
	v_permlane16_swap_b32_e32 v100, v102
	v_permlane16_swap_b32_e32 v101, v103
	global_store_dwordx4 v[90:91], v[100:103], off
	v_cvt_pk_bf16_f32 v98, v228, v229
	v_cvt_pk_bf16_f32 v99, v230, v231
	v_mfma_f32_16x16x32_bf16 v[6:9], v[152:155], v[164:167], v[148:151]
	v_mov_b32_e32 v76, v34
	v_mov_b32_e32 v77, v35
	v_cvt_pk_bf16_f32 v34, v62, v63
	v_cvt_pk_bf16_f32 v35, v64, v65
	v_mfma_f32_16x16x32_bf16 v[2:5], v[152:155], v[168:171], v[2:5]
	v_mov_b32_e32 v106, v98
	v_mov_b32_e32 v107, v99
	s_nop 1
	v_permlane16_swap_b32_e32 v104, v106
	v_permlane16_swap_b32_e32 v105, v107
	global_store_dwordx4 v[92:93], v[104:107], off
	v_cvt_pk_bf16_f32 v98, v232, v233
	v_cvt_pk_bf16_f32 v99, v234, v235
	v_mov_b32_e32 v118, v34
	v_mov_b32_e32 v119, v35
	s_nop 1
	v_permlane16_swap_b32_e32 v116, v118
	v_permlane16_swap_b32_e32 v117, v119
	global_store_dwordx4 v[90:91], v[116:119], off offset:128
	v_cvt_pk_bf16_f32 v34, v54, v55
	v_cvt_pk_bf16_f32 v35, v56, v57
	v_mov_b32_e32 v122, v98
	v_mov_b32_e32 v123, v99
	s_nop 1
	v_permlane16_swap_b32_e32 v120, v122
	v_permlane16_swap_b32_e32 v121, v123
	global_store_dwordx4 v[96:97], v[120:123], off
	v_cvt_pk_bf16_f32 v98, v236, v237
	v_cvt_pk_bf16_f32 v99, v238, v239
	v_mov_b32_e32 v126, v34
	v_mov_b32_e32 v127, v35
	s_nop 1
	v_permlane16_swap_b32_e32 v124, v126
	v_permlane16_swap_b32_e32 v125, v127
	global_store_dwordx4 v[92:93], v[124:127], off offset:128
	v_cvt_pk_bf16_f32 v34, v46, v47
	v_cvt_pk_bf16_f32 v35, v48, v49
	v_mov_b32_e32 v114, v98
	v_mov_b32_e32 v115, v99
	s_nop 1
	v_permlane16_swap_b32_e32 v112, v114
	v_permlane16_swap_b32_e32 v113, v115
	global_store_dwordx4 v[94:95], v[112:115], off
	v_cvt_pk_bf16_f32 v98, v240, v241
	v_cvt_pk_bf16_f32 v99, v242, v243
	v_cvt_pk_bf16_f32 v58, v58, v59
	v_cvt_pk_bf16_f32 v59, v60, v61
	v_mov_b32_e32 v86, v34
	v_mov_b32_e32 v87, v35
	s_nop 1
	v_permlane16_swap_b32_e32 v84, v86
	v_permlane16_swap_b32_e32 v85, v87
	global_store_dwordx4 v[96:97], v[84:87], off offset:128
	v_cvt_pk_bf16_f32 v34, v38, v39
	v_cvt_pk_bf16_f32 v35, v40, v41
	v_cvt_pk_bf16_f32 v27, v28, v29
	v_cvt_pk_bf16_f32 v22, v22, v23
	v_cvt_pk_bf16_f32 v23, v24, v25
	v_cvt_pk_bf16_f32 v18, v18, v19
	v_cvt_pk_bf16_f32 v19, v20, v21
	v_cvt_pk_bf16_f32 v14, v14, v15
	v_cvt_pk_bf16_f32 v15, v16, v17
	v_cvt_pk_bf16_f32 v10, v10, v11
	v_cvt_pk_bf16_f32 v11, v12, v13
	v_cvt_pk_bf16_f32 v6, v6, v7
	v_cvt_pk_bf16_f32 v7, v8, v9
	v_cvt_pk_bf16_f32 v2, v2, v3
	v_cvt_pk_bf16_f32 v3, v4, v5
	v_mov_b32_e32 v108, v66
	v_mov_b32_e32 v109, v67
	s_nop 1
	v_permlane16_swap_b32_e32 v108, v110
	v_permlane16_swap_b32_e32 v109, v111
	global_store_dwordx4 v[94:95], v[108:111], off offset:64
	v_mov_b32_e32 v100, v58
	v_mov_b32_e32 v101, v59
	s_nop 1
	v_permlane16_swap_b32_e32 v98, v100
	v_permlane16_swap_b32_e32 v99, v101
	global_store_dwordx4 v[90:91], v[98:101], off offset:64
	v_mov_b32_e32 v84, v50
	v_mov_b32_e32 v85, v51
	s_nop 1
	v_permlane16_swap_b32_e32 v82, v84
	v_permlane16_swap_b32_e32 v83, v85
	global_store_dwordx4 v[92:93], v[82:85], off offset:64
	v_mov_b32_e32 v40, v74
	v_mov_b32_e32 v41, v75
	s_nop 1
	v_permlane16_swap_b32_e32 v40, v42
	v_permlane16_swap_b32_e32 v41, v43
	global_store_dwordx4 v[96:97], v[40:43], off offset:64
	v_mov_b32_e32 v78, v34
	v_mov_b32_e32 v79, v35
	s_nop 1
	v_permlane16_swap_b32_e32 v76, v78
	v_permlane16_swap_b32_e32 v77, v79
	global_store_dwordx4 v[94:95], v[76:79], off offset:128
	v_mov_b32_e32 v32, v14
	v_mov_b32_e32 v33, v15
	s_nop 1
	v_permlane16_swap_b32_e32 v30, v32
	v_permlane16_swap_b32_e32 v31, v33
	global_store_dwordx4 v[90:91], v[30:33], off offset:192
	v_mov_b32_e32 v28, v10
	v_mov_b32_e32 v29, v11
	s_nop 1
	v_permlane16_swap_b32_e32 v26, v28
	v_permlane16_swap_b32_e32 v27, v29
	global_store_dwordx4 v[92:93], v[26:29], off offset:192
	v_mov_b32_e32 v24, v6
	v_mov_b32_e32 v25, v7
	s_nop 1
	v_permlane16_swap_b32_e32 v22, v24
	v_permlane16_swap_b32_e32 v23, v25
	global_store_dwordx4 v[96:97], v[22:25], off offset:192
	v_mov_b32_e32 v20, v2
	v_mov_b32_e32 v21, v3
	s_nop 1
	v_permlane16_swap_b32_e32 v18, v20
	v_permlane16_swap_b32_e32 v19, v21
	global_store_dwordx4 v[94:95], v[18:21], off offset:192

; template <int N> DI void wait_vm() { asm volatile("s_waitcnt vmcnt(%0)" ::"n"(N) : "memory"); }
; template <int BM, class Epi>
; DI void gemm_dma(const u16* __restrict__ X, long ldx, const u16* __restrict__ W, long ldw, int K, char* smem,
;                  int m0, int n0, const Epi& epi) {
;     ...
;   const int nk = K >> 5;
;   __syncthreads();
; #pragma unroll
;   for (int s = 0; s < D - 1; ++s) GD_ISSUE(s)
;   int cur = 0, nxt = D - 1, kt = 0;
;   do {
;     if (kt + D - 2 < nk) wait_vm<PW * (D - 2)>(); else wait_vm<0>();
;     __syncthreads();
;     if (kt + D - 1 < nk) GD_ISSUE(nxt)
;     nxt = (nxt + 1 == D) ? 0 : nxt + 1;
;     const char* base = smem + cur * STG;
;     cur = (cur + 1 == D) ? 0 : cur + 1;
;     bf16x8 xf[MT];
; #pragma unroll
;     for (int i = 0; i < MT; ++i) xf[i] = *(const bf16x8*)(base + (xrow0 + i * 16) * 64 + rd);
; #pragma unroll
;     for (int nh = 0; nh < NT / 4; ++nh) {
;       bf16x8 wf[4];
; #pragma unroll
;       for (int i = 0; i < 4; ++i) wf[i] = *(const bf16x8*)(base + BM * 64 + (wrow0 + (nh * 4 + i) * 16) * 64 + rd);
; #pragma unroll
;       for (int i = 0; i < 4; ++i)
; #pragma unroll
;         for (int mt = 0; mt < MT; ++mt)
;           acc[nh * 4 + i][mt] = __builtin_amdgcn_mfma_f32_16x16x32_bf16(wf[i], xf[mt], acc[nh * 4 + i][mt], 0, 0, 0);
;     }
;   } while (++kt < nk);
.LBB0_292:
	s_mul_i32 s12, s10, 0x6000
	v_lshl_add_u64 v[196:197], v[132:133], 0, s[40:41]
	s_waitcnt vmcnt(6)
	s_barrier
	s_mul_i32 s98, s11, 0x6000
	v_or_b32_e32 v170, s98, v135
	v_add_u32_e32 v150, v170, v137
	ds_read_b128 v[138:141], v150
	ds_read_b128 v[142:145], v150 offset:1024
	ds_read_b128 v[146:149], v150 offset:2048
	ds_read_b128 v[150:153], v150 offset:3072
	ds_read_b128 v[154:157], v170 offset:16384
	ds_read_b128 v[158:161], v170 offset:17408
	ds_read_b128 v[162:165], v170 offset:18432
	ds_read_b128 v[166:169], v170 offset:19456
	ds_read_b128 v[226:229], v170 offset:20480
	ds_read_b128 v[230:233], v170 offset:21504
	ds_read_b128 v[234:237], v170 offset:22528
	ds_read_b128 v[238:241], v170 offset:23552
	s_add_i32 s13, s12, s8
	s_mov_b32 m0, s13
	s_nop 0
	global_load_lds_dwordx4 v[196:197], off
	v_lshl_add_u64 v[224:225], v[196:197], 0, s[16:17]
	s_add_i32 s14, s13, 0x400
	s_mov_b32 m0, s14
	s_nop 0
	global_load_lds_dwordx4 v[224:225], off
	v_lshl_add_u64 v[224:225], v[196:197], 0, s[20:21]
	s_add_i32 s14, s13, 0x800
	s_mov_b32 m0, s14
	s_nop 0
	global_load_lds_dwordx4 v[224:225], off
	v_lshl_add_u64 v[196:197], v[196:197], 0, s[22:23]
	s_addk_i32 s13, 0xc00
	s_mov_b32 m0, s13
	s_nop 0
	global_load_lds_dwordx4 v[196:197], off
	s_add_i32 s12, s12, s9
	v_lshl_add_u64 v[194:195], v[130:131], 0, s[40:41]
	s_mov_b32 m0, s12
	s_nop 0
	global_load_lds_dwordx4 v[194:195], off
	s_addk_i32 s12, 0x400
	v_lshl_add_u64 v[194:195], v[194:195], 0, s[16:17]
	s_mov_b32 m0, s12
	s_nop 0
	global_load_lds_dwordx4 v[194:195], off
	s_waitcnt lgkmcnt(7)
	v_mfma_f32_16x16x32_bf16 v[126:129], v[154:157], v[138:141], v[126:129]
	s_add_i32 s10, s10, 1
	s_add_i32 s11, s11, 1
	s_cmp_lg_u32 s10, 3
	v_mfma_f32_16x16x32_bf16 v[122:125], v[154:157], v[142:145], v[122:125]
	s_cselect_b32 s10, s10, 0
	s_cmp_lg_u32 s11, 3
	s_cselect_b32 s11, s11, 0
	v_mfma_f32_16x16x32_bf16 v[118:121], v[154:157], v[146:149], v[118:121]
	s_add_u32 s40, s40, 64
	s_addc_u32 s41, s41, 0
	s_cmpk_lg_i32 s40, 0xf80
	v_mfma_f32_16x16x32_bf16 v[114:117], v[154:157], v[150:153], v[114:117]
	s_waitcnt lgkmcnt(6)
	v_mfma_f32_16x16x32_bf16 v[110:113], v[158:161], v[138:141], v[110:113]
	v_mfma_f32_16x16x32_bf16 v[106:109], v[158:161], v[142:145], v[106:109]
	v_mfma_f32_16x16x32_bf16 v[102:105], v[158:161], v[146:149], v[102:105]
	v_mfma_f32_16x16x32_bf16 v[98:101], v[158:161], v[150:153], v[98:101]
	s_waitcnt lgkmcnt(5)
	v_mfma_f32_16x16x32_bf16 v[94:97], v[162:165], v[138:141], v[94:97]
	v_mfma_f32_16x16x32_bf16 v[90:93], v[162:165], v[142:145], v[90:93]
	v_mfma_f32_16x16x32_bf16 v[86:89], v[162:165], v[146:149], v[86:89]
	v_mfma_f32_16x16x32_bf16 v[82:85], v[162:165], v[150:153], v[82:85]
	s_waitcnt lgkmcnt(4)
	v_mfma_f32_16x16x32_bf16 v[78:81], v[166:169], v[138:141], v[78:81]
	v_mfma_f32_16x16x32_bf16 v[74:77], v[166:169], v[142:145], v[74:77]
	v_mfma_f32_16x16x32_bf16 v[70:73], v[166:169], v[146:149], v[70:73]
	v_mfma_f32_16x16x32_bf16 v[66:69], v[166:169], v[150:153], v[66:69]
	s_waitcnt lgkmcnt(3)
	v_mfma_f32_16x16x32_bf16 v[62:65], v[226:229], v[138:141], v[62:65]
	v_mfma_f32_16x16x32_bf16 v[58:61], v[226:229], v[142:145], v[58:61]
	v_mfma_f32_16x16x32_bf16 v[54:57], v[226:229], v[146:149], v[54:57]
	v_mfma_f32_16x16x32_bf16 v[50:53], v[226:229], v[150:153], v[50:53]
	s_waitcnt lgkmcnt(2)
	v_mfma_f32_16x16x32_bf16 v[46:49], v[230:233], v[138:141], v[46:49]
	v_mfma_f32_16x16x32_bf16 v[42:45], v[230:233], v[142:145], v[42:45]
	v_mfma_f32_16x16x32_bf16 v[38:41], v[230:233], v[146:149], v[38:41]
	v_mfma_f32_16x16x32_bf16 v[34:37], v[230:233], v[150:153], v[34:37]
	s_waitcnt lgkmcnt(1)
	v_mfma_f32_16x16x32_bf16 v[30:33], v[234:237], v[138:141], v[30:33]
	v_mfma_f32_16x16x32_bf16 v[26:29], v[234:237], v[142:145], v[26:29]
	v_mfma_f32_16x16x32_bf16 v[22:25], v[234:237], v[146:149], v[22:25]
	v_mfma_f32_16x16x32_bf16 v[18:21], v[234:237], v[150:153], v[18:21]
	s_waitcnt lgkmcnt(0)
	v_mfma_f32_16x16x32_bf16 v[14:17], v[238:241], v[138:141], v[14:17]
	v_mfma_f32_16x16x32_bf16 v[10:13], v[238:241], v[142:145], v[10:13]
	v_mfma_f32_16x16x32_bf16 v[6:9], v[238:241], v[146:149], v[6:9]
	v_mfma_f32_16x16x32_bf16 v[2:5], v[238:241], v[150:153], v[2:5]
	s_cbranch_scc1 .LBB0_292
	v_add_u32_e32 v137, v135, v137
	v_or_b32_e32 v150, 0x10000, v135
	v_or_b32_e32 v154, 0x10400, v135
	v_or_b32_e32 v158, 0x10800, v135
	v_or_b32_e32 v162, 0x10c00, v135
	s_waitcnt vmcnt(6)
	s_barrier
	ds_read_b128 v[130:133], v137 offset:49152
	ds_read_b128 v[138:141], v137 offset:50176
	ds_read_b128 v[142:145], v137 offset:51200
	ds_read_b128 v[146:149], v137 offset:52224
	ds_read_b128 v[150:153], v150
	ds_read_b128 v[154:157], v154
	ds_read_b128 v[158:161], v158
	ds_read_b128 v[162:165], v162
	s_waitcnt lgkmcnt(3)
	v_mfma_f32_16x16x32_bf16 v[126:129], v[150:153], v[130:133], v[126:129]
	v_readlane_b32 s8, v252, 33
	v_readlane_b32 s9, v252, 34
	s_lshl_b32 s7, s7, 8
	v_mfma_f32_16x16x32_bf16 v[122:125], v[150:153], v[138:141], v[122:125]
	v_lshl_or_b32 v182, v1, 3, s7
	v_mfma_f32_16x16x32_bf16 v[118:121], v[150:153], v[142:145], v[118:121]
	v_mfma_f32_16x16x32_bf16 v[114:117], v[150:153], v[146:149], v[114:117]
	s_waitcnt lgkmcnt(2)
	v_mfma_f32_16x16x32_bf16 v[110:113], v[154:157], v[130:133], v[110:113]
	v_mfma_f32_16x16x32_bf16 v[106:109], v[154:157], v[138:141], v[106:109]
	v_mfma_f32_16x16x32_bf16 v[102:105], v[154:157], v[142:145], v[102:105]
	v_mfma_f32_16x16x32_bf16 v[98:101], v[154:157], v[146:149], v[98:101]
	s_waitcnt lgkmcnt(1)
	v_mfma_f32_16x16x32_bf16 v[94:97], v[158:161], v[130:133], v[94:97]
	v_mfma_f32_16x16x32_bf16 v[150:153], v[158:161], v[138:141], v[90:93]
	v_mfma_f32_16x16x32_bf16 v[86:89], v[158:161], v[142:145], v[86:89]
	s_nop 1
	v_or_b32_e32 v90, 0x11c00, v135
	ds_read_b128 v[90:93], v90
	v_mfma_f32_16x16x32_bf16 v[154:157], v[158:161], v[146:149], v[82:85]
	s_waitcnt lgkmcnt(1)
	v_mfma_f32_16x16x32_bf16 v[78:81], v[162:165], v[130:133], v[78:81]
	s_nop 0
	v_or_b32_e32 v82, 0x11800, v135
	ds_read_b128 v[82:85], v82
	v_mfma_f32_16x16x32_bf16 v[158:161], v[162:165], v[138:141], v[74:77]
	v_mfma_f32_16x16x32_bf16 v[70:73], v[162:165], v[142:145], v[70:73]
	s_nop 1
	v_or_b32_e32 v74, 0x11400, v135
	ds_read_b128 v[74:77], v74
	v_mfma_f32_16x16x32_bf16 v[162:165], v[162:165], v[146:149], v[66:69]
	s_nop 2
	v_or_b32_e32 v66, 0x11000, v135
	ds_read_b128 v[66:69], v66
	s_waitcnt lgkmcnt(1)
	v_mfma_f32_16x16x32_bf16 v[46:49], v[74:77], v[130:133], v[46:49]
	s_waitcnt vmcnt(0)
	s_waitcnt lgkmcnt(0)
	s_barrier
; template <int N> DI void wait_vm() { asm volatile("s_waitcnt vmcnt(%0)" ::"n"(N) : "memory"); }
; template <int BM, class Epi>
; DI void gemm_dma(const u16* __restrict__ X, long ldx, const u16* __restrict__ W, long ldw, int K, char* smem,
;                  int m0, int n0, const Epi& epi) {
;     ...
;   do {
;     if (kt + D - 2 < nk) wait_vm<PW * (D - 2)>(); else wait_vm<0>();
;     __syncthreads();
;     if (kt + D - 1 < nk) GD_ISSUE(nxt)
;     nxt = (nxt + 1 == D) ? 0 : nxt + 1;
;     const char* base = smem + cur * STG;
;     cur = (cur + 1 == D) ? 0 : cur + 1;
;     bf16x8 xf[MT];
; #pragma unroll
;     for (int i = 0; i < MT; ++i) xf[i] = *(const bf16x8*)(base + (xrow0 + i * 16) * 64 + rd);
; #pragma unroll
;     for (int nh = 0; nh < NT / 4; ++nh) {
;       bf16x8 wf[4];
; #pragma unroll
;       for (int i = 0; i < 4; ++i) wf[i] = *(const bf16x8*)(base + BM * 64 + (wrow0 + (nh * 4 + i) * 16) * 64 + rd);
; #pragma unroll
;       for (int i = 0; i < 4; ++i)
; #pragma unroll
;         for (int mt = 0; mt < MT; ++mt)
;           acc[nh * 4 + i][mt] = __builtin_amdgcn_mfma_f32_16x16x32_bf16(wf[i], xf[mt], acc[nh * 4 + i][mt], 0, 0, 0);
;     }
;   } while (++kt < nk);
;     ...
;   epi.run(acc, m0 + xrow0 + lr, n0 + wrow0 + 4 * g);
	v_mfma_f32_16x16x32_bf16 v[62:65], v[66:69], v[130:133], v[62:65]
	v_mfma_f32_16x16x32_bf16 v[166:169], v[66:69], v[138:141], v[58:61]
	v_mfma_f32_16x16x32_bf16 v[54:57], v[66:69], v[142:145], v[54:57]
	v_mfma_f32_16x16x32_bf16 v[170:173], v[66:69], v[146:149], v[50:53]
	v_mfma_f32_16x16x32_bf16 v[174:177], v[74:77], v[138:141], v[42:45]
	v_mfma_f32_16x16x32_bf16 v[38:41], v[74:77], v[142:145], v[38:41]
	v_mfma_f32_16x16x32_bf16 v[178:181], v[74:77], v[146:149], v[34:37]
	v_mfma_f32_16x16x32_bf16 v[30:33], v[82:85], v[130:133], v[30:33]
	v_mfma_f32_16x16x32_bf16 v[26:29], v[82:85], v[138:141], v[26:29]
	v_mfma_f32_16x16x32_bf16 v[22:25], v[82:85], v[142:145], v[22:25]
	v_mfma_f32_16x16x32_bf16 v[18:21], v[82:85], v[146:149], v[18:21]
	v_mfma_f32_16x16x32_bf16 v[14:17], v[90:93], v[130:133], v[14:17]
	v_mfma_f32_16x16x32_bf16 v[10:13], v[90:93], v[138:141], v[10:13]
	v_mfma_f32_16x16x32_bf16 v[6:9], v[90:93], v[142:145], v[6:9]
	v_mfma_f32_16x16x32_bf16 v[2:5], v[90:93], v[146:149], v[2:5]
	ds_read_b128 v[130:133], v137
	ds_read_b128 v[138:141], v137 offset:1024
	ds_read_b128 v[142:145], v137 offset:2048
	ds_read_b128 v[146:149], v137 offset:3072
	ds_read_b128 v[34:37], v135 offset:16384
	ds_read_b128 v[42:45], v135 offset:17408
	ds_read_b128 v[50:53], v135 offset:18432
	ds_read_b128 v[186:189], v135 offset:19456
	s_waitcnt lgkmcnt(2)
	v_mfma_f32_16x16x32_bf16 v[110:113], v[42:45], v[130:133], v[110:113]
	v_mfma_f32_16x16x32_bf16 v[106:109], v[42:45], v[138:141], v[106:109]
	v_mfma_f32_16x16x32_bf16 v[102:105], v[42:45], v[142:145], v[102:105]
	s_nop 5
	v_cvt_pk_bf16_f32 v110, v110, v111
	v_cvt_pk_bf16_f32 v111, v112, v113
	v_cvt_pk_bf16_f32 v106, v106, v107
	v_mfma_f32_16x16x32_bf16 v[190:193], v[42:45], v[146:149], v[98:101]
	v_cvt_pk_bf16_f32 v107, v108, v109
	v_cvt_pk_bf16_f32 v102, v102, v103
	v_cvt_pk_bf16_f32 v103, v104, v105
	s_waitcnt lgkmcnt(1)
	v_mfma_f32_16x16x32_bf16 v[82:85], v[50:53], v[138:141], v[150:153]
	v_mfma_f32_16x16x32_bf16 v[66:69], v[50:53], v[146:149], v[154:157]
	s_waitcnt lgkmcnt(0)
	v_mfma_f32_16x16x32_bf16 v[42:45], v[186:189], v[142:145], v[70:73]
	s_nop 2
	ds_read_b128 v[70:73], v135 offset:20480
	ds_read_b128 v[98:101], v135 offset:21504
	ds_read_b128 v[150:153], v135 offset:22528
	ds_read_b128 v[154:157], v135 offset:23552
	v_cvt_pk_bf16_f32 v82, v82, v83
	v_cvt_pk_bf16_f32 v83, v84, v85
	v_mfma_f32_16x16x32_bf16 v[90:93], v[50:53], v[130:133], v[94:97]
	v_cvt_pk_bf16_f32 v66, v66, v67
	v_cvt_pk_bf16_f32 v67, v68, v69
	v_cvt_pk_bf16_f32 v42, v42, v43
	v_mfma_f32_16x16x32_bf16 v[58:61], v[186:189], v[130:133], v[78:81]
	v_cvt_pk_bf16_f32 v43, v44, v45
	s_nop 2
	v_cvt_pk_bf16_f32 v90, v90, v91
	v_cvt_pk_bf16_f32 v91, v92, v93
	s_waitcnt lgkmcnt(3)
	v_mfma_f32_16x16x32_bf16 v[94:97], v[70:73], v[130:133], v[62:65]
	v_mfma_f32_16x16x32_bf16 v[78:81], v[70:73], v[142:145], v[54:57]
	v_cvt_pk_bf16_f32 v58, v58, v59
	v_cvt_pk_bf16_f32 v59, v60, v61
	s_waitcnt lgkmcnt(2)
	v_mfma_f32_16x16x32_bf16 v[62:65], v[98:101], v[130:133], v[46:49]
	v_mfma_f32_16x16x32_bf16 v[54:57], v[98:101], v[138:141], v[174:177]
	v_mfma_f32_16x16x32_bf16 v[46:49], v[98:101], v[142:145], v[38:41]
	v_mfma_f32_16x16x32_bf16 v[38:41], v[98:101], v[146:149], v[178:181]
	v_lshl_add_u32 v98, s38, 8, v136
	v_mfma_f32_16x16x32_bf16 v[126:129], v[34:37], v[130:133], v[126:129]
	s_waitcnt lgkmcnt(1)
	v_mfma_f32_16x16x32_bf16 v[30:33], v[150:153], v[130:133], v[30:33]
	s_waitcnt lgkmcnt(0)
; DI void st_bf4(u16* p, float a, float b, float c, float d) { *(uint2*)p = make_uint2(pk2(a, b), pk2(c, d)); }
;   template <int NT, int MT> DI void run(f32x4 (&acc)[NT][MT], int mb, int nb) const {
; #pragma unroll
;     for (int nt = 0; nt < NT; ++nt)
; #pragma unroll
;       for (int mt = 0; mt < MT; ++mt) {
;         f32x4 v = acc[nt][mt];
;         st_bf4(C + (size_t)(mb + mt * 16) * ldc + nb + nt * 16, v[0], v[1], v[2], v[3]);
;       }
;   }
	v_mfma_f32_16x16x32_bf16 v[14:17], v[154:157], v[130:133], v[14:17]
	v_or_b32_e32 v130, v98, v134
	v_ashrrev_i32_e32 v131, 31, v130
	v_lshlrev_b64 v[98:99], 11, v[130:131]
	v_lshl_add_u64 v[98:99], s[8:9], 0, v[98:99]
	v_bfe_u32 v132, v185, 4, 1
	v_mad_u32_u24 v182, v132, 24, v182
	v_lshl_add_u64 v[98:99], v[98:99], 0, v[182:183]
	v_cvt_pk_bf16_f32 v100, v126, v127
	v_cvt_pk_bf16_f32 v101, v128, v129
	v_mfma_f32_16x16x32_bf16 v[122:125], v[34:37], v[138:141], v[122:125]
	v_mov_b32_e32 v174, v100
	v_mov_b32_e32 v175, v101
	v_or_b32_e32 v100, 16, v130
	v_ashrrev_i32_e32 v101, 31, v100
	v_lshlrev_b64 v[100:101], 11, v[100:101]
	v_lshl_add_u64 v[100:101], s[8:9], 0, v[100:101]
	v_lshl_add_u64 v[100:101], v[100:101], 0, v[182:183]
	s_nop 1
	v_cvt_pk_bf16_f32 v122, v122, v123
	v_cvt_pk_bf16_f32 v123, v124, v125
	v_mfma_f32_16x16x32_bf16 v[118:121], v[34:37], v[142:145], v[118:121]
	v_mov_b32_e32 v178, v122
	v_mov_b32_e32 v179, v123
	v_or_b32_e32 v122, 32, v130
	v_ashrrev_i32_e32 v123, 31, v122
	v_lshlrev_b64 v[122:123], 11, v[122:123]
	v_lshl_add_u64 v[122:123], s[8:9], 0, v[122:123]
	v_lshl_add_u64 v[122:123], v[122:123], 0, v[182:183]
	s_nop 1
	v_cvt_pk_bf16_f32 v118, v118, v119
	v_cvt_pk_bf16_f32 v119, v120, v121
	v_mfma_f32_16x16x32_bf16 v[114:117], v[34:37], v[146:149], v[114:117]
	v_mov_b32_e32 v194, v118
	v_mov_b32_e32 v195, v119
	v_or_b32_e32 v118, 48, v130
	v_ashrrev_i32_e32 v119, 31, v118
	v_mfma_f32_16x16x32_bf16 v[34:37], v[186:189], v[146:149], v[162:165]
	v_lshlrev_b64 v[118:119], 11, v[118:119]
	v_lshl_add_u64 v[118:119], s[8:9], 0, v[118:119]
	v_lshl_add_u64 v[118:119], v[118:119], 0, v[182:183]
	v_mfma_f32_16x16x32_bf16 v[74:77], v[50:53], v[142:145], v[86:89]
	v_cvt_pk_bf16_f32 v114, v114, v115
	s_nop 2
	v_cvt_pk_bf16_f32 v34, v34, v35
	v_cvt_pk_bf16_f32 v35, v36, v37
	v_mfma_f32_16x16x32_bf16 v[86:89], v[70:73], v[138:141], v[166:169]
	v_mov_b32_e32 v132, v34
	v_mov_b32_e32 v133, v35
	v_cvt_pk_bf16_f32 v34, v94, v95
	v_cvt_pk_bf16_f32 v35, v96, v97
	v_mfma_f32_16x16x32_bf16 v[70:73], v[70:73], v[146:149], v[170:173]
	v_mov_b32_e32 v162, v34
	v_mov_b32_e32 v163, v35
	s_nop 2
	v_cvt_pk_bf16_f32 v34, v86, v87
	v_cvt_pk_bf16_f32 v35, v88, v89
	v_mov_b32_e32 v224, v34
	v_mov_b32_e32 v225, v35
	v_cvt_pk_bf16_f32 v34, v78, v79
	v_cvt_pk_bf16_f32 v35, v80, v81
	v_mfma_f32_16x16x32_bf16 v[50:53], v[186:189], v[138:141], v[158:161]
	v_mov_b32_e32 v166, v34
	v_mov_b32_e32 v167, v35
	v_cvt_pk_bf16_f32 v34, v70, v71
	v_cvt_pk_bf16_f32 v35, v72, v73
	v_mfma_f32_16x16x32_bf16 v[26:29], v[150:153], v[138:141], v[26:29]
	v_mov_b32_e32 v170, v34
	v_mov_b32_e32 v171, v35
	v_cvt_pk_bf16_f32 v34, v62, v63
	v_cvt_pk_bf16_f32 v35, v64, v65
	v_mfma_f32_16x16x32_bf16 v[22:25], v[150:153], v[142:145], v[22:25]
	v_mov_b32_e32 v164, v34
	v_mov_b32_e32 v165, v35
	s_nop 1
	v_permlane16_swap_b32_e32 v162, v164
	v_permlane16_swap_b32_e32 v163, v165
	global_store_dwordx4 v[98:99], v[162:165], off offset:128
	v_cvt_pk_bf16_f32 v34, v54, v55
	v_cvt_pk_bf16_f32 v35, v56, v57
	v_mfma_f32_16x16x32_bf16 v[18:21], v[150:153], v[146:149], v[18:21]
	v_mov_b32_e32 v226, v34
	v_mov_b32_e32 v227, v35
	s_nop 1
	v_permlane16_swap_b32_e32 v224, v226
	v_permlane16_swap_b32_e32 v225, v227
	global_store_dwordx4 v[100:101], v[224:227], off offset:128
	v_cvt_pk_bf16_f32 v34, v46, v47
	v_cvt_pk_bf16_f32 v35, v48, v49
	v_mfma_f32_16x16x32_bf16 v[10:13], v[154:157], v[138:141], v[10:13]
	v_cvt_pk_bf16_f32 v115, v116, v117
	v_mov_b32_e32 v196, v102
	v_mov_b32_e32 v197, v103
	s_nop 1
	v_permlane16_swap_b32_e32 v194, v196
	v_permlane16_swap_b32_e32 v195, v197
	global_store_dwordx4 v[122:123], v[194:197], off
	v_cvt_pk_bf16_f32 v102, v190, v191
	v_mfma_f32_16x16x32_bf16 v[6:9], v[154:157], v[142:145], v[6:9]
	v_cvt_pk_bf16_f32 v103, v192, v193
	v_cvt_pk_bf16_f32 v74, v74, v75
	v_cvt_pk_bf16_f32 v75, v76, v77
	v_mfma_f32_16x16x32_bf16 v[2:5], v[154:157], v[146:149], v[2:5]
	v_cvt_pk_bf16_f32 v50, v50, v51
	v_cvt_pk_bf16_f32 v51, v52, v53
	v_mov_b32_e32 v168, v34
	v_mov_b32_e32 v169, v35
	s_nop 1
	v_permlane16_swap_b32_e32 v166, v168
	v_permlane16_swap_b32_e32 v167, v169
	global_store_dwordx4 v[122:123], v[166:169], off offset:128
	v_cvt_pk_bf16_f32 v34, v38, v39
	v_cvt_pk_bf16_f32 v35, v40, v41
	v_cvt_pk_bf16_f32 v30, v30, v31
	v_cvt_pk_bf16_f32 v31, v32, v33
	v_cvt_pk_bf16_f32 v26, v26, v27
	v_cvt_pk_bf16_f32 v27, v28, v29
	v_cvt_pk_bf16_f32 v22, v22, v23
	v_cvt_pk_bf16_f32 v23, v24, v25
	v_cvt_pk_bf16_f32 v18, v18, v19
	v_cvt_pk_bf16_f32 v19, v20, v21
	v_cvt_pk_bf16_f32 v14, v14, v15
	v_cvt_pk_bf16_f32 v15, v16, v17
	v_cvt_pk_bf16_f32 v10, v10, v11
	v_cvt_pk_bf16_f32 v11, v12, v13
	v_cvt_pk_bf16_f32 v6, v6, v7
	v_cvt_pk_bf16_f32 v7, v8, v9
	v_cvt_pk_bf16_f32 v2, v2, v3
	v_cvt_pk_bf16_f32 v3, v4, v5
	v_mov_b32_e32 v176, v110
	v_mov_b32_e32 v177, v111
	s_nop 1
	v_permlane16_swap_b32_e32 v174, v176
	v_permlane16_swap_b32_e32 v175, v177
	global_store_dwordx4 v[98:99], v[174:177], off
	v_mov_b32_e32 v180, v106
	v_mov_b32_e32 v181, v107
	s_nop 1
	v_permlane16_swap_b32_e32 v178, v180
	v_permlane16_swap_b32_e32 v179, v181
	global_store_dwordx4 v[100:101], v[178:181], off
	v_mov_b32_e32 v116, v102
	v_mov_b32_e32 v117, v103
	s_nop 1
	v_permlane16_swap_b32_e32 v114, v116
	v_permlane16_swap_b32_e32 v115, v117
	global_store_dwordx4 v[118:119], v[114:117], off
	v_mov_b32_e32 v130, v66
	v_mov_b32_e32 v131, v67
	s_nop 1
	v_permlane16_swap_b32_e32 v130, v132
	v_permlane16_swap_b32_e32 v131, v133
	global_store_dwordx4 v[118:119], v[130:133], off offset:64
	v_mov_b32_e32 v92, v58
	v_mov_b32_e32 v93, v59
	s_nop 1
	v_permlane16_swap_b32_e32 v90, v92
	v_permlane16_swap_b32_e32 v91, v93
	global_store_dwordx4 v[98:99], v[90:93], off offset:64
	v_mov_b32_e32 v84, v50
	v_mov_b32_e32 v85, v51
	s_nop 1
	v_permlane16_swap_b32_e32 v82, v84
	v_permlane16_swap_b32_e32 v83, v85
	global_store_dwordx4 v[100:101], v[82:85], off offset:64
	v_mov_b32_e32 v76, v42
	v_mov_b32_e32 v77, v43
	s_nop 1
	v_permlane16_swap_b32_e32 v74, v76
	v_permlane16_swap_b32_e32 v75, v77
	global_store_dwordx4 v[122:123], v[74:77], off offset:64
	v_mov_b32_e32 v172, v34
	v_mov_b32_e32 v173, v35
	s_nop 1
	v_permlane16_swap_b32_e32 v170, v172
	v_permlane16_swap_b32_e32 v171, v173
	global_store_dwordx4 v[118:119], v[170:173], off offset:128
	v_mov_b32_e32 v32, v14
	v_mov_b32_e32 v33, v15
	s_nop 1
	v_permlane16_swap_b32_e32 v30, v32
	v_permlane16_swap_b32_e32 v31, v33
	global_store_dwordx4 v[98:99], v[30:33], off offset:192
	v_mov_b32_e32 v28, v10
	v_mov_b32_e32 v29, v11
	s_nop 1
	v_permlane16_swap_b32_e32 v26, v28
	v_permlane16_swap_b32_e32 v27, v29
	global_store_dwordx4 v[100:101], v[26:29], off offset:192
	v_mov_b32_e32 v24, v6
	v_mov_b32_e32 v25, v7
	s_nop 1
	v_permlane16_swap_b32_e32 v22, v24
	v_permlane16_swap_b32_e32 v23, v25
	global_store_dwordx4 v[122:123], v[22:25], off offset:192
	v_mov_b32_e32 v20, v2
	v_mov_b32_e32 v21, v3
	s_nop 1
	v_permlane16_swap_b32_e32 v18, v20
	v_permlane16_swap_b32_e32 v19, v21
	global_store_dwordx4 v[118:119], v[18:21], off offset:192
	s_branch .LBB0_285

; DI int get_tid() { int t = threadIdx.x; asm volatile("" : "+v"(t)); return t; }
; DI float zero_f() { float z = 0.f; asm volatile("" : "+v"(z)); return z; }
; template <int BM, class Epi>
; DI void gemm_dma(const u16* __restrict__ X, long ldx, const u16* __restrict__ W, long ldw, int K, char* smem,
;                  int m0, int n0, const Epi& epi) {
;     ...
;   const int tid = get_tid(), lane = tid & 63, wave = tid >> 6;
;   const int lr = lane & 15, g = lane >> 4;
;   const int rd = lr * 64 + ((g ^ ((4 - (lr >> 2)) & 3)) << 4);
;   const int xrow0 = BIG ? wave * 64 : (wave & 1) * (BM / 2);
;   const int wrow0 = BIG ? 0 : (wave >> 1) * 64;
;   f32x4 acc[NT][MT];
;   { const float z = zero_f();
; #pragma unroll
;   for (int a = 0; a < NT; ++a)
; #pragma unroll
;     for (int b = 0; b < MT; ++b) acc[a][b] = (f32x4){z, z, z, z}; }
;   const int wu = __builtin_amdgcn_readfirstlane(wave);
;   const unsigned sbase = (unsigned)__builtin_amdgcn_readfirstlane((int)(unsigned)(size_t)smem);
;   const int r16 = lane >> 2, chunk = (lane & 3) ^ ((4 - (r16 >> 2)) & 3);
;   const u16* xs = X + (long)(wu * XD * 16 + r16) * ldx + (chunk << 3);
;   const u16* ws = W + (long)(wu * 32 + r16) * ldw + (chunk << 3);
;   const long ldx16 = 16 * ldx, ldw16 = 16 * ldw;
;   const unsigned xdst = sbase + wu * XD * 1024, wdst = sbase + BM * 64 + wu * 2048;
;     ...
;   const int nk = K >> 5;
;   __syncthreads();
; #pragma unroll
;   for (int s = 0; s < D - 1; ++s) GD_ISSUE(s)
;   int cur = 0, nxt = D - 1, kt = 0;
; DI void knope_tile(const Params& p, int u, char* smem) {
;   const u16* W = (const u16*)(p.ws + OFF_W);
;   const u16* ckvb = (const u16*)(p.ws + OFF_CKVB);
;   EpiBF16 ek{(u16*)(p.ws + OFF_KN), 1024};
;   const int tm = u >> 3, tn = u & 7;
;   gemm_dma<256>(ckvb + (size_t)tm * 256 * 256, 256, W + WO_KV + (size_t)tn * 128 * 256, 256, 256, smem, tm * 256, tn * 128, ek);
; }
.LBB0_966:
	s_cmpk_gt_i32 s4, 0x77f
	s_cbranch_scc1 .LBB0_974
	s_cmpk_gt_i32 s4, 0x43f
	s_mov_b64 s[38:39], -1
	s_cbranch_scc0 .LBB0_969
	s_add_i32 s5, s4, 0xfffffcc0
	s_bfe_u32 s98, s5, 0x30003
	s_and_b32 s99, s5, 7
	s_lshl_b32 s99, s99, 3
	s_andn2_b32 s5, s5, 63
	s_or_b32 s5, s5, s99
	s_or_b32 s5, s5, s98
	s_lshr_b32 s6, s5, 3
	s_and_b32 s5, s5, 7
	s_lshl_b32 s7, s6, 17
	s_add_u32 s8, s0, s7
	s_addc_u32 s9, s1, 0
	s_lshl_b32 s7, s5, 16
	v_mov_b32_e32 v9, v185
	s_add_u32 s10, s87, s7
	s_addc_u32 s11, s90, 0
	v_readfirstlane_b32 s7, v9
	v_lshrrev_b32_e32 v4, 4, v9
	s_ashr_i32 s12, s7, 6
	v_bfe_u32 v6, v9, 2, 4
	v_sub_u32_e32 v4, 0, v4
	s_andn2_b32 s7, s7, 63
	v_lshrrev_b32_e32 v1, 2, v9
	v_xor_b32_e32 v7, v9, v4
	v_or_b32_e32 v4, s7, v6
	v_and_b32_e32 v89, 15, v9
	v_bfe_u32 v88, v9, 4, 2
	v_sub_u32_e32 v1, 0, v1
	v_ashrrev_i32_e32 v5, 31, v4
	v_lshlrev_b32_e32 v0, 6, v89
	v_bitop3_b32 v1, v88, v1, 3 bitop3:0x78
	v_lshlrev_b64 v[4:5], 9, v[4:5]
	v_lshlrev_b32_e32 v7, 4, v7
	v_lshl_or_b32 v6, s12, 5, v6
	v_lshl_or_b32 v8, v1, 4, v0
	v_mov_b32_e32 v0, v183
	v_lshl_add_u64 v[4:5], s[8:9], 0, v[4:5]
	v_and_b32_e32 v182, 48, v7
	v_ashrrev_i32_e32 v7, 31, v6
	v_lshl_add_u64 v[4:5], v[4:5], 0, v[182:183]
	v_lshlrev_b64 v[6:7], 9, v[6:7]
	s_lshl_b32 s14, s12, 12
	s_waitcnt lgkmcnt(0)
	s_barrier
	s_mov_b32 m0, s14
	s_nop 0
	global_load_lds_dwordx4 v[4:5], off
	s_mov_b64 s[8:9], 0x2000
	v_lshl_add_u64 v[6:7], s[10:11], 0, v[6:7]
	v_lshl_add_u64 v[10:11], v[4:5], 0, s[8:9]
	s_or_b32 s15, s14, 0x400
	s_mov_b32 m0, s15
	s_nop 0
	global_load_lds_dwordx4 v[10:11], off
	s_mov_b64 s[10:11], 0x4000
	v_lshl_add_u64 v[10:11], v[4:5], 0, s[10:11]
	s_or_b32 s16, s14, 0x800
	s_mov_b32 m0, s16
	s_nop 0
	global_load_lds_dwordx4 v[10:11], off
	s_mov_b64 s[10:11], 0x6000
	s_lshl_b32 s41, s12, 11
	v_lshl_add_u64 v[10:11], v[4:5], 0, s[10:11]
	s_or_b32 s17, s14, 0xc00
	s_mov_b32 m0, s17
	s_nop 0
	global_load_lds_dwordx4 v[10:11], off
	v_lshl_add_u64 v[6:7], v[6:7], 0, v[182:183]
	s_add_i32 s13, s41, 0x4000
	s_mov_b32 m0, s13
	s_nop 0
	global_load_lds_dwordx4 v[6:7], off
	v_lshl_add_u64 v[10:11], v[6:7], 0, s[8:9]
	s_add_i32 s18, s41, 0x4400
	s_mov_b32 m0, s18
	s_nop 0
	global_load_lds_dwordx4 v[10:11], off
	v_lshl_add_u64 v[10:11], v[4:5], 0, 64
	s_add_i32 s7, s14, 0x6000
	s_mov_b32 m0, s7
	s_nop 0
	global_load_lds_dwordx4 v[10:11], off
	s_mov_b64 s[20:21], 0x2040
	v_lshl_add_u64 v[10:11], v[4:5], 0, s[20:21]
	s_add_i32 s8, s14, 0x6400
	s_mov_b32 m0, s8
	s_nop 0
	global_load_lds_dwordx4 v[10:11], off
	s_mov_b64 s[10:11], 0x4040
	v_lshl_add_u64 v[10:11], v[4:5], 0, s[10:11]
	s_add_i32 s9, s14, 0x6800
	s_mov_b32 m0, s9
	s_nop 0
	global_load_lds_dwordx4 v[10:11], off
	s_mov_b64 s[10:11], 0x6040
	v_lshl_add_u64 v[10:11], v[4:5], 0, s[10:11]
	s_add_i32 s10, s14, 0x6c00
	s_mov_b32 m0, s10
	s_nop 0
	global_load_lds_dwordx4 v[10:11], off
	v_lshl_add_u64 v[12:13], v[6:7], 0, 64
	s_add_i32 s11, s41, 0xa000
	s_mov_b32 m0, s11
	s_nop 0
	global_load_lds_dwordx4 v[12:13], off
	v_lshl_add_u64 v[10:11], v[6:7], 0, s[20:21]
	s_add_i32 s12, s41, 0xa400
	s_mov_b32 m0, s12
	s_nop 0
	global_load_lds_dwordx4 v[10:11], off
	s_waitcnt vmcnt(6)
	s_barrier
	v_lshl_add_u64 v[12:13], v[4:5], 0, s[28:29]
	s_add_i32 s19, s14, 0xc000
	s_mov_b32 m0, s19
	s_nop 0
	global_load_lds_dwordx4 v[12:13], off
	s_mov_b64 s[20:21], 0x2080
	v_lshl_add_u64 v[12:13], v[4:5], 0, s[20:21]
	s_add_i32 s34, s14, 0xc400
	s_mov_b32 m0, s34
	s_nop 0
	global_load_lds_dwordx4 v[12:13], off
	v_lshl_add_u64 v[12:13], v[4:5], 0, s[94:95]
	s_add_i32 s38, s14, 0xc800
	s_mov_b32 m0, s38
	s_nop 0
	global_load_lds_dwordx4 v[12:13], off
	s_mov_b64 s[22:23], 0x6080
	v_lshl_add_u64 v[12:13], v[4:5], 0, s[22:23]
	s_add_i32 s39, s14, 0xcc00
	s_mov_b32 m0, s39
	s_nop 0
	global_load_lds_dwordx4 v[12:13], off
	v_and_b32_e32 v90, 0xffffffc0, v9
	v_lshl_add_u64 v[10:11], v[6:7], 0, s[28:29]
	s_add_i32 s40, s41, 0x10000
	s_mov_b32 m0, s40
	s_nop 0
	global_load_lds_dwordx4 v[10:11], off
	v_lshl_add_u64 v[10:11], v[6:7], 0, s[20:21]
	s_add_i32 s41, s41, 0x10400
	s_mov_b32 m0, s41
	s_nop 0
	global_load_lds_dwordx4 v[10:11], off
	v_lshl_or_b32 v9, v90, 6, v8
	ds_read_b128 v[10:13], v9
	ds_read_b128 v[14:17], v9 offset:1024
	ds_read_b128 v[18:21], v9 offset:2048
	ds_read_b128 v[22:25], v9 offset:3072
	ds_read_b128 v[26:29], v8 offset:16384
	ds_read_b128 v[30:33], v8 offset:17408
	ds_read_b128 v[34:37], v8 offset:18432
	ds_read_b128 v[38:41], v8 offset:19456
	ds_read_b128 v[96:99], v8 offset:20480
	ds_read_b128 v[100:103], v8 offset:21504
	ds_read_b128 v[104:107], v8 offset:22528
	ds_read_b128 v[108:111], v8 offset:23552
	s_mov_b64 s[20:21], 0xc0
	v_mov_b32_e32 v1, v0
	v_mov_b32_e32 v2, v0
	v_mov_b32_e32 v3, v0
	v_lshl_add_u64 v[86:87], v[4:5], 0, s[20:21]
	v_lshl_add_u64 v[148:149], v[6:7], 0, s[20:21]
	s_waitcnt vmcnt(6)
	s_waitcnt lgkmcnt(0)
	s_barrier
; template <int N> DI void wait_vm() { asm volatile("s_waitcnt vmcnt(%0)" ::"n"(N) : "memory"); }
; template <int BM, class Epi>
; DI void gemm_dma(const u16* __restrict__ X, long ldx, const u16* __restrict__ W, long ldw, int K, char* smem,
;                  int m0, int n0, const Epi& epi) {
;     ...
;   do {
;     if (kt + D - 2 < nk) wait_vm<PW * (D - 2)>(); else wait_vm<0>();
;     __syncthreads();
;     if (kt + D - 1 < nk) GD_ISSUE(nxt)
;     nxt = (nxt + 1 == D) ? 0 : nxt + 1;
;     const char* base = smem + cur * STG;
;     cur = (cur + 1 == D) ? 0 : cur + 1;
;     bf16x8 xf[MT];
; #pragma unroll
;     for (int i = 0; i < MT; ++i) xf[i] = *(const bf16x8*)(base + (xrow0 + i * 16) * 64 + rd);
; #pragma unroll
;     for (int nh = 0; nh < NT / 4; ++nh) {
;       bf16x8 wf[4];
; #pragma unroll
;       for (int i = 0; i < 4; ++i) wf[i] = *(const bf16x8*)(base + BM * 64 + (wrow0 + (nh * 4 + i) * 16) * 64 + rd);
; #pragma unroll
;       for (int i = 0; i < 4; ++i)
; #pragma unroll
;         for (int mt = 0; mt < MT; ++mt)
;           acc[nh * 4 + i][mt] = __builtin_amdgcn_mfma_f32_16x16x32_bf16(wf[i], xf[mt], acc[nh * 4 + i][mt], 0, 0, 0);
;     }
;   } while (++kt < nk);
	s_mov_b32 m0, s14
	s_nop 0
	global_load_lds_dwordx4 v[86:87], off
	s_mov_b64 s[20:21], 0x20c0
	v_mfma_f32_16x16x32_bf16 v[42:45], v[26:29], v[10:13], v[0:3]
	s_mov_b64 s[22:23], 0x40c0
	v_or_b32_e32 v91, 0x10000, v8
	v_or_b32_e32 v174, 0x10400, v8
	v_mfma_f32_16x16x32_bf16 v[46:49], v[26:29], v[14:17], v[0:3]
	v_or_b32_e32 v175, 0x10800, v8
	v_or_b32_e32 v176, 0x10c00, v8
	v_or_b32_e32 v177, 0x11000, v8
	v_mfma_f32_16x16x32_bf16 v[50:53], v[26:29], v[18:21], v[0:3]
	v_or_b32_e32 v178, 0x11400, v8
	v_or_b32_e32 v179, 0x11800, v8
	v_or_b32_e32 v180, 0x11c00, v8
	v_mfma_f32_16x16x32_bf16 v[26:29], v[26:29], v[22:25], v[0:3]
	v_lshl_add_u32 v90, s6, 8, v90
	s_lshl_b32 s5, s5, 8
	v_lshl_or_b32 v182, v88, 3, s5
	v_mfma_f32_16x16x32_bf16 v[54:57], v[30:33], v[10:13], v[0:3]
	v_mfma_f32_16x16x32_bf16 v[58:61], v[30:33], v[14:17], v[0:3]
	v_mfma_f32_16x16x32_bf16 v[62:65], v[30:33], v[18:21], v[0:3]
	v_mfma_f32_16x16x32_bf16 v[30:33], v[30:33], v[22:25], v[0:3]
	v_mfma_f32_16x16x32_bf16 v[66:69], v[34:37], v[10:13], v[0:3]
	v_mfma_f32_16x16x32_bf16 v[70:73], v[34:37], v[14:17], v[0:3]
	v_mfma_f32_16x16x32_bf16 v[74:77], v[34:37], v[18:21], v[0:3]
	v_mfma_f32_16x16x32_bf16 v[34:37], v[34:37], v[22:25], v[0:3]
	v_mfma_f32_16x16x32_bf16 v[78:81], v[38:41], v[10:13], v[0:3]
	v_mfma_f32_16x16x32_bf16 v[82:85], v[38:41], v[14:17], v[0:3]
	v_mfma_f32_16x16x32_bf16 v[92:95], v[38:41], v[18:21], v[0:3]
	v_mfma_f32_16x16x32_bf16 v[38:41], v[38:41], v[22:25], v[0:3]
	v_mfma_f32_16x16x32_bf16 v[112:115], v[96:99], v[10:13], v[0:3]
	v_mfma_f32_16x16x32_bf16 v[116:119], v[96:99], v[14:17], v[0:3]
	v_mfma_f32_16x16x32_bf16 v[120:123], v[96:99], v[18:21], v[0:3]
	v_mfma_f32_16x16x32_bf16 v[96:99], v[96:99], v[22:25], v[0:3]
	v_mfma_f32_16x16x32_bf16 v[124:127], v[100:103], v[10:13], v[0:3]
	v_mfma_f32_16x16x32_bf16 v[128:131], v[100:103], v[14:17], v[0:3]
	v_mfma_f32_16x16x32_bf16 v[132:135], v[100:103], v[18:21], v[0:3]
	v_mfma_f32_16x16x32_bf16 v[100:103], v[100:103], v[22:25], v[0:3]
	v_mfma_f32_16x16x32_bf16 v[136:139], v[104:107], v[10:13], v[0:3]
	v_mfma_f32_16x16x32_bf16 v[140:143], v[104:107], v[14:17], v[0:3]
	v_mfma_f32_16x16x32_bf16 v[144:147], v[104:107], v[18:21], v[0:3]
	v_mfma_f32_16x16x32_bf16 v[104:107], v[104:107], v[22:25], v[0:3]
	v_mfma_f32_16x16x32_bf16 v[10:13], v[108:111], v[10:13], v[0:3]
	v_mfma_f32_16x16x32_bf16 v[14:17], v[108:111], v[14:17], v[0:3]
	v_mfma_f32_16x16x32_bf16 v[18:21], v[108:111], v[18:21], v[0:3]
	v_mfma_f32_16x16x32_bf16 v[0:3], v[108:111], v[22:25], v[0:3]
	v_lshl_add_u64 v[22:23], v[4:5], 0, s[20:21]
	s_mov_b32 m0, s15
	s_nop 0
	global_load_lds_dwordx4 v[22:23], off
	v_lshl_add_u64 v[22:23], v[4:5], 0, s[22:23]
	s_mov_b32 m0, s16
	s_nop 0
	global_load_lds_dwordx4 v[22:23], off
	s_mov_b64 s[22:23], 0x60c0
	v_lshl_add_u64 v[22:23], v[4:5], 0, s[22:23]
	s_mov_b32 m0, s17
	s_nop 0
	global_load_lds_dwordx4 v[22:23], off
	v_lshl_add_u64 v[22:23], v[6:7], 0, s[20:21]
	s_mov_b32 m0, s13
	s_nop 0
	global_load_lds_dwordx4 v[148:149], off
	s_mov_b64 s[20:21], 0x100
	s_mov_b32 m0, s18
	s_nop 0
	global_load_lds_dwordx4 v[22:23], off
	ds_read_b128 v[22:25], v9 offset:24576
	ds_read_b128 v[108:111], v9 offset:25600
	ds_read_b128 v[148:151], v9 offset:26624
	ds_read_b128 v[152:155], v9 offset:27648
	ds_read_b128 v[156:159], v8 offset:40960
	ds_read_b128 v[160:163], v8 offset:41984
	ds_read_b128 v[164:167], v8 offset:43008
	ds_read_b128 v[168:171], v8 offset:44032
	s_waitcnt lgkmcnt(3)
	v_mfma_f32_16x16x32_bf16 v[42:45], v[156:159], v[22:25], v[42:45]
	v_lshl_add_u64 v[86:87], v[4:5], 0, s[20:21]
	v_lshl_add_u64 v[172:173], v[6:7], 0, s[20:21]
	s_mov_b64 s[20:21], 0x2100
	v_mfma_f32_16x16x32_bf16 v[46:49], v[156:159], v[108:111], v[46:49]
	s_mov_b64 s[22:23], 0x4100
	v_mfma_f32_16x16x32_bf16 v[50:53], v[156:159], v[148:151], v[50:53]
	v_mfma_f32_16x16x32_bf16 v[26:29], v[156:159], v[152:155], v[26:29]
	s_waitcnt lgkmcnt(2)
	v_mfma_f32_16x16x32_bf16 v[54:57], v[160:163], v[22:25], v[54:57]
	v_mfma_f32_16x16x32_bf16 v[58:61], v[160:163], v[108:111], v[58:61]
	v_mfma_f32_16x16x32_bf16 v[62:65], v[160:163], v[148:151], v[62:65]
	v_mfma_f32_16x16x32_bf16 v[30:33], v[160:163], v[152:155], v[30:33]
	s_waitcnt lgkmcnt(1)
	v_mfma_f32_16x16x32_bf16 v[66:69], v[164:167], v[22:25], v[66:69]
	v_mfma_f32_16x16x32_bf16 v[70:73], v[164:167], v[108:111], v[70:73]
	v_mfma_f32_16x16x32_bf16 v[74:77], v[164:167], v[148:151], v[74:77]
	v_mfma_f32_16x16x32_bf16 v[34:37], v[164:167], v[152:155], v[34:37]
	s_waitcnt lgkmcnt(0)
	v_mfma_f32_16x16x32_bf16 v[78:81], v[168:171], v[22:25], v[78:81]
	v_mfma_f32_16x16x32_bf16 v[82:85], v[168:171], v[108:111], v[82:85]
	v_mfma_f32_16x16x32_bf16 v[92:95], v[168:171], v[148:151], v[92:95]
	v_mfma_f32_16x16x32_bf16 v[38:41], v[168:171], v[152:155], v[38:41]
	ds_read_b128 v[156:159], v8 offset:45056
	ds_read_b128 v[160:163], v8 offset:46080
	ds_read_b128 v[164:167], v8 offset:47104
	ds_read_b128 v[168:171], v8 offset:48128
	s_waitcnt vmcnt(6)
	s_waitcnt lgkmcnt(0)
	s_barrier
; template <int N> DI void wait_vm() { asm volatile("s_waitcnt vmcnt(%0)" ::"n"(N) : "memory"); }
; template <int BM, class Epi>
; DI void gemm_dma(const u16* __restrict__ X, long ldx, const u16* __restrict__ W, long ldw, int K, char* smem,
;                  int m0, int n0, const Epi& epi) {
;     ...
;   const int nk = K >> 5;
;   __syncthreads();
; #pragma unroll
;   for (int s = 0; s < D - 1; ++s) GD_ISSUE(s)
;   int cur = 0, nxt = D - 1, kt = 0;
;   do {
;     if (kt + D - 2 < nk) wait_vm<PW * (D - 2)>(); else wait_vm<0>();
;     __syncthreads();
;     if (kt + D - 1 < nk) GD_ISSUE(nxt)
;     nxt = (nxt + 1 == D) ? 0 : nxt + 1;
;     const char* base = smem + cur * STG;
;     cur = (cur + 1 == D) ? 0 : cur + 1;
;     bf16x8 xf[MT];
; #pragma unroll
;     for (int i = 0; i < MT; ++i) xf[i] = *(const bf16x8*)(base + (xrow0 + i * 16) * 64 + rd);
; #pragma unroll
;     for (int nh = 0; nh < NT / 4; ++nh) {
;       bf16x8 wf[4];
; #pragma unroll
;       for (int i = 0; i < 4; ++i) wf[i] = *(const bf16x8*)(base + BM * 64 + (wrow0 + (nh * 4 + i) * 16) * 64 + rd);
; #pragma unroll
;       for (int i = 0; i < 4; ++i)
; #pragma unroll
;         for (int mt = 0; mt < MT; ++mt)
;           acc[nh * 4 + i][mt] = __builtin_amdgcn_mfma_f32_16x16x32_bf16(wf[i], xf[mt], acc[nh * 4 + i][mt], 0, 0, 0);
;     }
;   } while (++kt < nk);
	s_mov_b32 m0, s7
	s_nop 0
	global_load_lds_dwordx4 v[86:87], off
	v_mfma_f32_16x16x32_bf16 v[112:115], v[156:159], v[22:25], v[112:115]
	v_mfma_f32_16x16x32_bf16 v[124:127], v[160:163], v[22:25], v[124:127]
	v_mfma_f32_16x16x32_bf16 v[136:139], v[164:167], v[22:25], v[136:139]
	v_mfma_f32_16x16x32_bf16 v[10:13], v[168:171], v[22:25], v[10:13]
	v_lshl_add_u64 v[22:23], v[4:5], 0, s[20:21]
	s_mov_b32 m0, s8
	s_nop 0
	global_load_lds_dwordx4 v[22:23], off
	v_lshl_add_u64 v[22:23], v[4:5], 0, s[22:23]
	s_mov_b32 m0, s9
	s_nop 0
	global_load_lds_dwordx4 v[22:23], off
	s_mov_b64 s[22:23], 0x6100
	v_lshl_add_u64 v[22:23], v[4:5], 0, s[22:23]
	s_mov_b32 m0, s10
	s_nop 0
	global_load_lds_dwordx4 v[22:23], off
	v_lshl_add_u64 v[22:23], v[6:7], 0, s[20:21]
	s_mov_b32 m0, s11
	s_nop 0
	global_load_lds_dwordx4 v[172:173], off
	v_mfma_f32_16x16x32_bf16 v[116:119], v[156:159], v[108:111], v[116:119]
	s_mov_b32 m0, s12
	s_nop 0
	global_load_lds_dwordx4 v[22:23], off
	s_mov_b64 s[20:21], 0x140
	v_lshl_add_u64 v[86:87], v[4:5], 0, s[20:21]
	v_mfma_f32_16x16x32_bf16 v[120:123], v[156:159], v[148:151], v[120:123]
	v_lshl_add_u64 v[172:173], v[6:7], 0, s[20:21]
	s_mov_b64 s[20:21], 0x2140
	s_mov_b64 s[22:23], 0x4140
	v_mfma_f32_16x16x32_bf16 v[96:99], v[156:159], v[152:155], v[96:99]
	v_mfma_f32_16x16x32_bf16 v[128:131], v[160:163], v[108:111], v[128:131]
	v_mfma_f32_16x16x32_bf16 v[132:135], v[160:163], v[148:151], v[132:135]
	v_mfma_f32_16x16x32_bf16 v[100:103], v[160:163], v[152:155], v[100:103]
	v_mfma_f32_16x16x32_bf16 v[140:143], v[164:167], v[108:111], v[140:143]
	v_mfma_f32_16x16x32_bf16 v[144:147], v[164:167], v[148:151], v[144:147]
	v_mfma_f32_16x16x32_bf16 v[104:107], v[164:167], v[152:155], v[104:107]
	v_mfma_f32_16x16x32_bf16 v[14:17], v[168:171], v[108:111], v[14:17]
	v_mfma_f32_16x16x32_bf16 v[18:21], v[168:171], v[148:151], v[18:21]
	v_mfma_f32_16x16x32_bf16 v[0:3], v[168:171], v[152:155], v[0:3]
	ds_read_b128 v[22:25], v9 offset:49152
	ds_read_b128 v[108:111], v9 offset:50176
	ds_read_b128 v[148:151], v9 offset:51200
	ds_read_b128 v[152:155], v9 offset:52224
	ds_read_b128 v[156:159], v91
	ds_read_b128 v[160:163], v174
	ds_read_b128 v[164:167], v175
	ds_read_b128 v[168:171], v176
	s_waitcnt lgkmcnt(3)
	v_mfma_f32_16x16x32_bf16 v[42:45], v[156:159], v[22:25], v[42:45]
	v_mfma_f32_16x16x32_bf16 v[46:49], v[156:159], v[108:111], v[46:49]
	v_mfma_f32_16x16x32_bf16 v[50:53], v[156:159], v[148:151], v[50:53]
	v_mfma_f32_16x16x32_bf16 v[26:29], v[156:159], v[152:155], v[26:29]
	ds_read_b128 v[156:159], v177
	s_waitcnt lgkmcnt(3)
	v_mfma_f32_16x16x32_bf16 v[54:57], v[160:163], v[22:25], v[54:57]
	v_mfma_f32_16x16x32_bf16 v[58:61], v[160:163], v[108:111], v[58:61]
	v_mfma_f32_16x16x32_bf16 v[62:65], v[160:163], v[148:151], v[62:65]
	v_mfma_f32_16x16x32_bf16 v[30:33], v[160:163], v[152:155], v[30:33]
	ds_read_b128 v[160:163], v178
	s_waitcnt lgkmcnt(3)
	v_mfma_f32_16x16x32_bf16 v[66:69], v[164:167], v[22:25], v[66:69]
	v_mfma_f32_16x16x32_bf16 v[70:73], v[164:167], v[108:111], v[70:73]
	v_mfma_f32_16x16x32_bf16 v[74:77], v[164:167], v[148:151], v[74:77]
	v_mfma_f32_16x16x32_bf16 v[34:37], v[164:167], v[152:155], v[34:37]
	ds_read_b128 v[164:167], v179
	s_waitcnt lgkmcnt(3)
	v_mfma_f32_16x16x32_bf16 v[78:81], v[168:171], v[22:25], v[78:81]
	v_mfma_f32_16x16x32_bf16 v[82:85], v[168:171], v[108:111], v[82:85]
	v_mfma_f32_16x16x32_bf16 v[92:95], v[168:171], v[148:151], v[92:95]
	v_mfma_f32_16x16x32_bf16 v[38:41], v[168:171], v[152:155], v[38:41]
	ds_read_b128 v[168:171], v180
	s_waitcnt vmcnt(6)
	s_waitcnt lgkmcnt(0)
	s_barrier
	s_mov_b32 m0, s19
	s_nop 0
	global_load_lds_dwordx4 v[86:87], off
	v_mfma_f32_16x16x32_bf16 v[112:115], v[156:159], v[22:25], v[112:115]
	v_mfma_f32_16x16x32_bf16 v[124:127], v[160:163], v[22:25], v[124:127]
	v_mfma_f32_16x16x32_bf16 v[136:139], v[164:167], v[22:25], v[136:139]
	v_mfma_f32_16x16x32_bf16 v[10:13], v[168:171], v[22:25], v[10:13]
	v_lshl_add_u64 v[22:23], v[4:5], 0, s[20:21]
	s_mov_b32 m0, s34
	s_nop 0
	global_load_lds_dwordx4 v[22:23], off
	v_lshl_add_u64 v[22:23], v[4:5], 0, s[22:23]
	s_mov_b32 m0, s38
	s_nop 0
	global_load_lds_dwordx4 v[22:23], off
	s_mov_b64 s[22:23], 0x6140
	v_lshl_add_u64 v[22:23], v[4:5], 0, s[22:23]
	s_mov_b32 m0, s39
	s_nop 0
	global_load_lds_dwordx4 v[22:23], off
	v_lshl_add_u64 v[22:23], v[6:7], 0, s[20:21]
	s_mov_b32 m0, s40
	s_nop 0
	global_load_lds_dwordx4 v[172:173], off
	v_mfma_f32_16x16x32_bf16 v[116:119], v[156:159], v[108:111], v[116:119]
	s_mov_b32 m0, s41
	s_nop 0
	global_load_lds_dwordx4 v[22:23], off
	s_mov_b64 s[20:21], 0x180
	v_lshl_add_u64 v[86:87], v[4:5], 0, s[20:21]
	v_mfma_f32_16x16x32_bf16 v[120:123], v[156:159], v[148:151], v[120:123]
	v_lshl_add_u64 v[172:173], v[6:7], 0, s[20:21]
	s_mov_b64 s[20:21], 0x2180
	s_mov_b64 s[38:39], 0
	v_mfma_f32_16x16x32_bf16 v[96:99], v[156:159], v[152:155], v[96:99]
	v_mfma_f32_16x16x32_bf16 v[128:131], v[160:163], v[108:111], v[128:131]
	v_mfma_f32_16x16x32_bf16 v[132:135], v[160:163], v[148:151], v[132:135]
	v_mfma_f32_16x16x32_bf16 v[100:103], v[160:163], v[152:155], v[100:103]
	v_mfma_f32_16x16x32_bf16 v[140:143], v[164:167], v[108:111], v[140:143]
	v_mfma_f32_16x16x32_bf16 v[144:147], v[164:167], v[148:151], v[144:147]
	v_mfma_f32_16x16x32_bf16 v[104:107], v[164:167], v[152:155], v[104:107]
	v_mfma_f32_16x16x32_bf16 v[14:17], v[168:171], v[108:111], v[14:17]
	v_mfma_f32_16x16x32_bf16 v[18:21], v[168:171], v[148:151], v[18:21]
	v_mfma_f32_16x16x32_bf16 v[0:3], v[168:171], v[152:155], v[0:3]
	ds_read_b128 v[22:25], v9
	ds_read_b128 v[108:111], v9 offset:1024
	ds_read_b128 v[148:151], v9 offset:2048
	ds_read_b128 v[152:155], v9 offset:3072
	ds_read_b128 v[156:159], v8 offset:16384
	ds_read_b128 v[160:163], v8 offset:17408
	ds_read_b128 v[164:167], v8 offset:18432
	ds_read_b128 v[168:171], v8 offset:19456
	s_waitcnt lgkmcnt(3)
; template <int N> DI void wait_vm() { asm volatile("s_waitcnt vmcnt(%0)" ::"n"(N) : "memory"); }
; template <int BM, class Epi>
; DI void gemm_dma(const u16* __restrict__ X, long ldx, const u16* __restrict__ W, long ldw, int K, char* smem,
;                  int m0, int n0, const Epi& epi) {
;     ...
;   const int nk = K >> 5;
;   __syncthreads();
; #pragma unroll
;   for (int s = 0; s < D - 1; ++s) GD_ISSUE(s)
;   int cur = 0, nxt = D - 1, kt = 0;
;   do {
;     if (kt + D - 2 < nk) wait_vm<PW * (D - 2)>(); else wait_vm<0>();
;     __syncthreads();
;     if (kt + D - 1 < nk) GD_ISSUE(nxt)
;     nxt = (nxt + 1 == D) ? 0 : nxt + 1;
;     const char* base = smem + cur * STG;
;     cur = (cur + 1 == D) ? 0 : cur + 1;
;     bf16x8 xf[MT];
; #pragma unroll
;     for (int i = 0; i < MT; ++i) xf[i] = *(const bf16x8*)(base + (xrow0 + i * 16) * 64 + rd);
; #pragma unroll
;     for (int nh = 0; nh < NT / 4; ++nh) {
;       bf16x8 wf[4];
; #pragma unroll
;       for (int i = 0; i < 4; ++i) wf[i] = *(const bf16x8*)(base + BM * 64 + (wrow0 + (nh * 4 + i) * 16) * 64 + rd);
; #pragma unroll
;       for (int i = 0; i < 4; ++i)
; #pragma unroll
;         for (int mt = 0; mt < MT; ++mt)
;           acc[nh * 4 + i][mt] = __builtin_amdgcn_mfma_f32_16x16x32_bf16(wf[i], xf[mt], acc[nh * 4 + i][mt], 0, 0, 0);
;     }
;   } while (++kt < nk);
	v_mfma_f32_16x16x32_bf16 v[42:45], v[156:159], v[22:25], v[42:45]
	v_mfma_f32_16x16x32_bf16 v[46:49], v[156:159], v[108:111], v[46:49]
	v_mfma_f32_16x16x32_bf16 v[50:53], v[156:159], v[148:151], v[50:53]
	v_mfma_f32_16x16x32_bf16 v[26:29], v[156:159], v[152:155], v[26:29]
	s_waitcnt lgkmcnt(2)
	v_mfma_f32_16x16x32_bf16 v[54:57], v[160:163], v[22:25], v[54:57]
	v_mfma_f32_16x16x32_bf16 v[58:61], v[160:163], v[108:111], v[58:61]
	v_mfma_f32_16x16x32_bf16 v[62:65], v[160:163], v[148:151], v[62:65]
	v_mfma_f32_16x16x32_bf16 v[30:33], v[160:163], v[152:155], v[30:33]
	s_waitcnt lgkmcnt(1)
	v_mfma_f32_16x16x32_bf16 v[66:69], v[164:167], v[22:25], v[66:69]
	v_mfma_f32_16x16x32_bf16 v[70:73], v[164:167], v[108:111], v[70:73]
	v_mfma_f32_16x16x32_bf16 v[74:77], v[164:167], v[148:151], v[74:77]
	v_mfma_f32_16x16x32_bf16 v[34:37], v[164:167], v[152:155], v[34:37]
	s_waitcnt lgkmcnt(0)
	v_mfma_f32_16x16x32_bf16 v[78:81], v[168:171], v[22:25], v[78:81]
	v_mfma_f32_16x16x32_bf16 v[82:85], v[168:171], v[108:111], v[82:85]
	v_mfma_f32_16x16x32_bf16 v[92:95], v[168:171], v[148:151], v[92:95]
	v_mfma_f32_16x16x32_bf16 v[38:41], v[168:171], v[152:155], v[38:41]
	ds_read_b128 v[156:159], v8 offset:20480
	ds_read_b128 v[160:163], v8 offset:21504
	ds_read_b128 v[164:167], v8 offset:22528
	ds_read_b128 v[168:171], v8 offset:23552
	s_waitcnt vmcnt(6)
	s_waitcnt lgkmcnt(0)
	s_barrier
	s_mov_b32 m0, s14
	s_nop 0
	global_load_lds_dwordx4 v[86:87], off
	v_mfma_f32_16x16x32_bf16 v[112:115], v[156:159], v[22:25], v[112:115]
	v_mfma_f32_16x16x32_bf16 v[124:127], v[160:163], v[22:25], v[124:127]
	v_mfma_f32_16x16x32_bf16 v[136:139], v[164:167], v[22:25], v[136:139]
	v_mfma_f32_16x16x32_bf16 v[10:13], v[168:171], v[22:25], v[10:13]
	v_lshl_add_u64 v[22:23], v[4:5], 0, s[20:21]
	s_mov_b32 m0, s15
	s_nop 0
	global_load_lds_dwordx4 v[22:23], off
	s_mov_b64 s[14:15], 0x4180
	v_lshl_add_u64 v[22:23], v[4:5], 0, s[14:15]
	s_mov_b32 m0, s16
	s_nop 0
	global_load_lds_dwordx4 v[22:23], off
	s_mov_b64 s[14:15], 0x6180
	v_lshl_add_u64 v[22:23], v[4:5], 0, s[14:15]
	s_mov_b32 m0, s17
	s_nop 0
	global_load_lds_dwordx4 v[22:23], off
	v_lshl_add_u64 v[22:23], v[6:7], 0, s[20:21]
	s_mov_b32 m0, s13
	s_nop 0
	global_load_lds_dwordx4 v[172:173], off
	s_mov_b32 m0, s18
	s_nop 0
	global_load_lds_dwordx4 v[22:23], off
	v_mfma_f32_16x16x32_bf16 v[116:119], v[156:159], v[108:111], v[116:119]
	s_mov_b64 s[14:15], 0x1c0
	v_lshl_add_u64 v[86:87], v[4:5], 0, s[14:15]
	v_lshl_add_u64 v[172:173], v[6:7], 0, s[14:15]
	v_mfma_f32_16x16x32_bf16 v[120:123], v[156:159], v[148:151], v[120:123]
	s_mov_b64 s[14:15], 0x21c0
	s_mov_b64 s[16:17], 0x41c0
	v_mfma_f32_16x16x32_bf16 v[96:99], v[156:159], v[152:155], v[96:99]
	v_mfma_f32_16x16x32_bf16 v[128:131], v[160:163], v[108:111], v[128:131]
	v_mfma_f32_16x16x32_bf16 v[132:135], v[160:163], v[148:151], v[132:135]
	v_mfma_f32_16x16x32_bf16 v[100:103], v[160:163], v[152:155], v[100:103]
	v_mfma_f32_16x16x32_bf16 v[140:143], v[164:167], v[108:111], v[140:143]
	v_mfma_f32_16x16x32_bf16 v[144:147], v[164:167], v[148:151], v[144:147]
	v_mfma_f32_16x16x32_bf16 v[104:107], v[164:167], v[152:155], v[104:107]
	v_mfma_f32_16x16x32_bf16 v[14:17], v[168:171], v[108:111], v[14:17]
	v_mfma_f32_16x16x32_bf16 v[18:21], v[168:171], v[148:151], v[18:21]
	v_mfma_f32_16x16x32_bf16 v[0:3], v[168:171], v[152:155], v[0:3]
	ds_read_b128 v[22:25], v9 offset:24576
	ds_read_b128 v[108:111], v9 offset:25600
	ds_read_b128 v[148:151], v9 offset:26624
	ds_read_b128 v[152:155], v9 offset:27648
	ds_read_b128 v[156:159], v8 offset:40960
	ds_read_b128 v[160:163], v8 offset:41984
	ds_read_b128 v[164:167], v8 offset:43008
	ds_read_b128 v[168:171], v8 offset:44032
	s_waitcnt lgkmcnt(3)
	v_mfma_f32_16x16x32_bf16 v[42:45], v[156:159], v[22:25], v[42:45]
	v_mfma_f32_16x16x32_bf16 v[46:49], v[156:159], v[108:111], v[46:49]
	v_mfma_f32_16x16x32_bf16 v[50:53], v[156:159], v[148:151], v[50:53]
	v_mfma_f32_16x16x32_bf16 v[26:29], v[156:159], v[152:155], v[26:29]
	s_waitcnt lgkmcnt(2)
	v_mfma_f32_16x16x32_bf16 v[54:57], v[160:163], v[22:25], v[54:57]
	v_mfma_f32_16x16x32_bf16 v[58:61], v[160:163], v[108:111], v[58:61]
	v_mfma_f32_16x16x32_bf16 v[62:65], v[160:163], v[148:151], v[62:65]
	v_mfma_f32_16x16x32_bf16 v[30:33], v[160:163], v[152:155], v[30:33]
	s_waitcnt lgkmcnt(1)
	v_mfma_f32_16x16x32_bf16 v[66:69], v[164:167], v[22:25], v[66:69]
	v_mfma_f32_16x16x32_bf16 v[70:73], v[164:167], v[108:111], v[70:73]
	v_mfma_f32_16x16x32_bf16 v[74:77], v[164:167], v[148:151], v[74:77]
	v_mfma_f32_16x16x32_bf16 v[34:37], v[164:167], v[152:155], v[34:37]
	s_waitcnt lgkmcnt(0)
	v_mfma_f32_16x16x32_bf16 v[78:81], v[168:171], v[22:25], v[78:81]
	v_mfma_f32_16x16x32_bf16 v[82:85], v[168:171], v[108:111], v[82:85]
	v_mfma_f32_16x16x32_bf16 v[92:95], v[168:171], v[148:151], v[92:95]
	v_mfma_f32_16x16x32_bf16 v[38:41], v[168:171], v[152:155], v[38:41]
	ds_read_b128 v[156:159], v8 offset:45056
	ds_read_b128 v[160:163], v8 offset:46080
	ds_read_b128 v[164:167], v8 offset:47104
	ds_read_b128 v[168:171], v8 offset:48128
	s_waitcnt vmcnt(6)
	s_waitcnt lgkmcnt(0)
	s_barrier
; template <int N> DI void wait_vm() { asm volatile("s_waitcnt vmcnt(%0)" ::"n"(N) : "memory"); }
; template <int BM, class Epi>
; DI void gemm_dma(const u16* __restrict__ X, long ldx, const u16* __restrict__ W, long ldw, int K, char* smem,
;                  int m0, int n0, const Epi& epi) {
;     ...
;   const int nk = K >> 5;
;   __syncthreads();
; #pragma unroll
;   for (int s = 0; s < D - 1; ++s) GD_ISSUE(s)
;   int cur = 0, nxt = D - 1, kt = 0;
;   do {
;     if (kt + D - 2 < nk) wait_vm<PW * (D - 2)>(); else wait_vm<0>();
;     __syncthreads();
;     if (kt + D - 1 < nk) GD_ISSUE(nxt)
;     nxt = (nxt + 1 == D) ? 0 : nxt + 1;
;     const char* base = smem + cur * STG;
;     cur = (cur + 1 == D) ? 0 : cur + 1;
;     bf16x8 xf[MT];
; #pragma unroll
;     for (int i = 0; i < MT; ++i) xf[i] = *(const bf16x8*)(base + (xrow0 + i * 16) * 64 + rd);
; #pragma unroll
;     for (int nh = 0; nh < NT / 4; ++nh) {
;       bf16x8 wf[4];
; #pragma unroll
;       for (int i = 0; i < 4; ++i) wf[i] = *(const bf16x8*)(base + BM * 64 + (wrow0 + (nh * 4 + i) * 16) * 64 + rd);
; #pragma unroll
;       for (int i = 0; i < 4; ++i)
; #pragma unroll
;         for (int mt = 0; mt < MT; ++mt)
;           acc[nh * 4 + i][mt] = __builtin_amdgcn_mfma_f32_16x16x32_bf16(wf[i], xf[mt], acc[nh * 4 + i][mt], 0, 0, 0);
;     }
;   } while (++kt < nk);
	s_mov_b32 m0, s7
	s_nop 0
	global_load_lds_dwordx4 v[86:87], off
	v_mfma_f32_16x16x32_bf16 v[112:115], v[156:159], v[22:25], v[112:115]
	v_mfma_f32_16x16x32_bf16 v[124:127], v[160:163], v[22:25], v[124:127]
	v_mfma_f32_16x16x32_bf16 v[136:139], v[164:167], v[22:25], v[136:139]
	v_mfma_f32_16x16x32_bf16 v[10:13], v[168:171], v[22:25], v[10:13]
	v_lshl_add_u64 v[22:23], v[4:5], 0, s[14:15]
	s_mov_b32 m0, s8
	s_nop 0
	global_load_lds_dwordx4 v[22:23], off
	v_lshl_add_u64 v[22:23], v[4:5], 0, s[16:17]
	s_mov_b32 m0, s9
	s_nop 0
	global_load_lds_dwordx4 v[22:23], off
	s_mov_b64 s[8:9], 0x61c0
	v_lshl_add_u64 v[4:5], v[4:5], 0, s[8:9]
	s_mov_b32 m0, s10
	s_nop 0
	global_load_lds_dwordx4 v[4:5], off
	v_lshl_add_u64 v[4:5], v[6:7], 0, s[14:15]
	s_mov_b32 m0, s11
	s_nop 0
	global_load_lds_dwordx4 v[172:173], off
	v_mfma_f32_16x16x32_bf16 v[116:119], v[156:159], v[108:111], v[116:119]
	s_mov_b32 m0, s12
	s_nop 0
	global_load_lds_dwordx4 v[4:5], off
	v_mfma_f32_16x16x32_bf16 v[120:123], v[156:159], v[148:151], v[120:123]
	v_mfma_f32_16x16x32_bf16 v[96:99], v[156:159], v[152:155], v[96:99]
	v_mfma_f32_16x16x32_bf16 v[128:131], v[160:163], v[108:111], v[128:131]
	v_mfma_f32_16x16x32_bf16 v[132:135], v[160:163], v[148:151], v[132:135]
	v_mfma_f32_16x16x32_bf16 v[100:103], v[160:163], v[152:155], v[100:103]
	v_mfma_f32_16x16x32_bf16 v[140:143], v[164:167], v[108:111], v[140:143]
	v_mfma_f32_16x16x32_bf16 v[144:147], v[164:167], v[148:151], v[144:147]
	v_mfma_f32_16x16x32_bf16 v[104:107], v[164:167], v[152:155], v[104:107]
	v_mfma_f32_16x16x32_bf16 v[14:17], v[168:171], v[108:111], v[14:17]
	v_mfma_f32_16x16x32_bf16 v[18:21], v[168:171], v[148:151], v[18:21]
	v_mfma_f32_16x16x32_bf16 v[0:3], v[168:171], v[152:155], v[0:3]
	ds_read_b128 v[4:7], v9 offset:49152
	ds_read_b128 v[22:25], v9 offset:50176
	ds_read_b128 v[108:111], v9 offset:51200
	ds_read_b128 v[148:151], v9 offset:52224
	ds_read_b128 v[152:155], v91
	ds_read_b128 v[156:159], v174
	ds_read_b128 v[160:163], v175
	ds_read_b128 v[164:167], v176
	s_waitcnt lgkmcnt(3)
	v_mfma_f32_16x16x32_bf16 v[42:45], v[152:155], v[4:7], v[42:45]
	v_mfma_f32_16x16x32_bf16 v[46:49], v[152:155], v[22:25], v[46:49]
	v_mfma_f32_16x16x32_bf16 v[50:53], v[152:155], v[108:111], v[50:53]
	v_mfma_f32_16x16x32_bf16 v[26:29], v[152:155], v[148:151], v[26:29]
	s_waitcnt lgkmcnt(2)
	v_mfma_f32_16x16x32_bf16 v[54:57], v[156:159], v[4:7], v[54:57]
	v_mfma_f32_16x16x32_bf16 v[58:61], v[156:159], v[22:25], v[58:61]
	v_mfma_f32_16x16x32_bf16 v[62:65], v[156:159], v[108:111], v[62:65]
	v_mfma_f32_16x16x32_bf16 v[30:33], v[156:159], v[148:151], v[30:33]
	s_waitcnt lgkmcnt(1)
	v_mfma_f32_16x16x32_bf16 v[66:69], v[160:163], v[4:7], v[66:69]
	v_mfma_f32_16x16x32_bf16 v[70:73], v[160:163], v[22:25], v[70:73]
	v_mfma_f32_16x16x32_bf16 v[74:77], v[160:163], v[108:111], v[74:77]
	v_mfma_f32_16x16x32_bf16 v[34:37], v[160:163], v[148:151], v[34:37]
	s_waitcnt lgkmcnt(0)
	v_mfma_f32_16x16x32_bf16 v[78:81], v[164:167], v[4:7], v[78:81]
	v_mfma_f32_16x16x32_bf16 v[82:85], v[164:167], v[22:25], v[82:85]
	v_mfma_f32_16x16x32_bf16 v[92:95], v[164:167], v[108:111], v[92:95]
	v_mfma_f32_16x16x32_bf16 v[38:41], v[164:167], v[148:151], v[38:41]
	ds_read_b128 v[152:155], v177
	ds_read_b128 v[156:159], v178
	ds_read_b128 v[160:163], v179
	ds_read_b128 v[164:167], v180
	s_waitcnt vmcnt(6)
	s_waitcnt lgkmcnt(0)
	v_mfma_f32_16x16x32_bf16 v[112:115], v[152:155], v[4:7], v[112:115]
	s_barrier
	v_mfma_f32_16x16x32_bf16 v[116:119], v[152:155], v[22:25], v[116:119]
	v_mfma_f32_16x16x32_bf16 v[120:123], v[152:155], v[108:111], v[120:123]
	v_mfma_f32_16x16x32_bf16 v[96:99], v[152:155], v[148:151], v[96:99]
	v_mfma_f32_16x16x32_bf16 v[124:127], v[156:159], v[4:7], v[124:127]
	v_mfma_f32_16x16x32_bf16 v[128:131], v[156:159], v[22:25], v[128:131]
	v_mfma_f32_16x16x32_bf16 v[132:135], v[156:159], v[108:111], v[132:135]
	v_mfma_f32_16x16x32_bf16 v[100:103], v[156:159], v[148:151], v[100:103]
	v_mfma_f32_16x16x32_bf16 v[136:139], v[160:163], v[4:7], v[136:139]
	v_mfma_f32_16x16x32_bf16 v[140:143], v[160:163], v[22:25], v[140:143]
	v_mfma_f32_16x16x32_bf16 v[144:147], v[160:163], v[108:111], v[144:147]
	v_mfma_f32_16x16x32_bf16 v[104:107], v[160:163], v[148:151], v[104:107]
	v_mfma_f32_16x16x32_bf16 v[4:7], v[164:167], v[4:7], v[10:13]
	v_mfma_f32_16x16x32_bf16 v[10:13], v[164:167], v[22:25], v[14:17]
	v_mfma_f32_16x16x32_bf16 v[14:17], v[164:167], v[108:111], v[18:21]
	v_mfma_f32_16x16x32_bf16 v[0:3], v[164:167], v[148:151], v[0:3]
	s_nop 1
	ds_read_b128 v[18:21], v8 offset:23552
	ds_read_b128 v[22:25], v8 offset:22528
	ds_read_b128 v[108:111], v8 offset:21504
	ds_read_b128 v[148:151], v8 offset:20480
	ds_read_b128 v[152:155], v8 offset:19456
	ds_read_b128 v[156:159], v8 offset:18432
	ds_read_b128 v[160:163], v8 offset:17408
	ds_read_b128 v[164:167], v8 offset:16384
	ds_read_b128 v[168:171], v9 offset:3072
	ds_read_b128 v[172:175], v9 offset:2048
	ds_read_b128 v[176:179], v9 offset:1024
	ds_read_b128 v[186:189], v9
	s_waitcnt vmcnt(0)
	s_waitcnt lgkmcnt(0)
	v_mfma_f32_16x16x32_bf16 v[42:45], v[164:167], v[186:189], v[42:45]
	s_barrier
; template <int N> DI void wait_vm() { asm volatile("s_waitcnt vmcnt(%0)" ::"n"(N) : "memory"); }
; DI void st_bf4(u16* p, float a, float b, float c, float d) { *(uint2*)p = make_uint2(pk2(a, b), pk2(c, d)); }
; template <int BM, class Epi>
; DI void gemm_dma(const u16* __restrict__ X, long ldx, const u16* __restrict__ W, long ldw, int K, char* smem,
;                  int m0, int n0, const Epi& epi) {
;     ...
;   do {
;     if (kt + D - 2 < nk) wait_vm<PW * (D - 2)>(); else wait_vm<0>();
;     __syncthreads();
;     if (kt + D - 1 < nk) GD_ISSUE(nxt)
;     nxt = (nxt + 1 == D) ? 0 : nxt + 1;
;     const char* base = smem + cur * STG;
;     cur = (cur + 1 == D) ? 0 : cur + 1;
;     bf16x8 xf[MT];
; #pragma unroll
;     for (int i = 0; i < MT; ++i) xf[i] = *(const bf16x8*)(base + (xrow0 + i * 16) * 64 + rd);
; #pragma unroll
;     for (int nh = 0; nh < NT / 4; ++nh) {
;       bf16x8 wf[4];
; #pragma unroll
;       for (int i = 0; i < 4; ++i) wf[i] = *(const bf16x8*)(base + BM * 64 + (wrow0 + (nh * 4 + i) * 16) * 64 + rd);
; #pragma unroll
;       for (int i = 0; i < 4; ++i)
; #pragma unroll
;         for (int mt = 0; mt < MT; ++mt)
;           acc[nh * 4 + i][mt] = __builtin_amdgcn_mfma_f32_16x16x32_bf16(wf[i], xf[mt], acc[nh * 4 + i][mt], 0, 0, 0);
;     }
;   } while (++kt < nk);
;   template <int NT, int MT> DI void run(f32x4 (&acc)[NT][MT], int mb, int nb) const {
; #pragma unroll
;     for (int nt = 0; nt < NT; ++nt)
; #pragma unroll
;       for (int mt = 0; mt < MT; ++mt) {
;         f32x4 v = acc[nt][mt];
;         st_bf4(C + (size_t)(mb + mt * 16) * ldc + nb + nt * 16, v[0], v[1], v[2], v[3]);
;       }
;   }
	v_mfma_f32_16x16x32_bf16 v[46:49], v[164:167], v[176:179], v[46:49]
	v_mfma_f32_16x16x32_bf16 v[50:53], v[164:167], v[172:175], v[50:53]
	v_mfma_f32_16x16x32_bf16 v[26:29], v[164:167], v[168:171], v[26:29]
	v_mfma_f32_16x16x32_bf16 v[54:57], v[160:163], v[186:189], v[54:57]
	v_mfma_f32_16x16x32_bf16 v[58:61], v[160:163], v[176:179], v[58:61]
	v_mfma_f32_16x16x32_bf16 v[62:65], v[160:163], v[172:175], v[62:65]
	v_mfma_f32_16x16x32_bf16 v[30:33], v[160:163], v[168:171], v[30:33]
	v_mfma_f32_16x16x32_bf16 v[66:69], v[156:159], v[186:189], v[66:69]
	v_mfma_f32_16x16x32_bf16 v[70:73], v[156:159], v[176:179], v[70:73]
	v_mfma_f32_16x16x32_bf16 v[74:77], v[156:159], v[172:175], v[74:77]
	v_mfma_f32_16x16x32_bf16 v[34:37], v[156:159], v[168:171], v[34:37]
	v_mfma_f32_16x16x32_bf16 v[156:159], v[152:155], v[186:189], v[78:81]
	v_mfma_f32_16x16x32_bf16 v[84:87], v[152:155], v[176:179], v[82:85]
	v_mfma_f32_16x16x32_bf16 v[92:95], v[152:155], v[172:175], v[92:95]
	v_mfma_f32_16x16x32_bf16 v[152:155], v[152:155], v[168:171], v[38:41]
	v_mfma_f32_16x16x32_bf16 v[112:115], v[148:151], v[186:189], v[112:115]
	v_mfma_f32_16x16x32_bf16 v[116:119], v[148:151], v[176:179], v[116:119]
	v_mfma_f32_16x16x32_bf16 v[120:123], v[148:151], v[172:175], v[120:123]
	v_mfma_f32_16x16x32_bf16 v[96:99], v[148:151], v[168:171], v[96:99]
	v_mfma_f32_16x16x32_bf16 v[124:127], v[108:111], v[186:189], v[124:127]
	v_mfma_f32_16x16x32_bf16 v[128:131], v[108:111], v[176:179], v[128:131]
	v_mfma_f32_16x16x32_bf16 v[132:135], v[108:111], v[172:175], v[132:135]
	v_mfma_f32_16x16x32_bf16 v[100:103], v[108:111], v[168:171], v[100:103]
	v_mfma_f32_16x16x32_bf16 v[108:111], v[22:25], v[186:189], v[136:139]
	v_mfma_f32_16x16x32_bf16 v[136:139], v[22:25], v[176:179], v[140:143]
	v_mfma_f32_16x16x32_bf16 v[140:143], v[22:25], v[172:175], v[144:147]
	v_mfma_f32_16x16x32_bf16 v[104:107], v[22:25], v[168:171], v[104:107]
	v_mfma_f32_16x16x32_bf16 v[4:7], v[18:21], v[186:189], v[4:7]
	v_mfma_f32_16x16x32_bf16 v[144:147], v[18:21], v[176:179], v[10:13]
	v_mfma_f32_16x16x32_bf16 v[148:151], v[18:21], v[172:175], v[14:17]
	v_mfma_f32_16x16x32_bf16 v[0:3], v[18:21], v[168:171], v[0:3]
	s_nop 0
	ds_read_b128 v[10:13], v9 offset:24576
	ds_read_b128 v[160:163], v9 offset:25600
	ds_read_b128 v[164:167], v9 offset:26624
	ds_read_b128 v[168:171], v9 offset:27648
	ds_read_b128 v[14:17], v8 offset:40960
	ds_read_b128 v[18:21], v8 offset:41984
	ds_read_b128 v[22:25], v8 offset:43008
	ds_read_b128 v[172:175], v8 offset:44032
	s_waitcnt lgkmcnt(3)
	v_mfma_f32_16x16x32_bf16 v[176:179], v[14:17], v[10:13], v[42:45]
	v_mfma_f32_16x16x32_bf16 v[186:189], v[14:17], v[160:163], v[46:49]
	v_mfma_f32_16x16x32_bf16 v[190:193], v[14:17], v[164:167], v[50:53]
	v_mfma_f32_16x16x32_bf16 v[194:197], v[14:17], v[168:171], v[26:29]
	s_waitcnt lgkmcnt(2)
	v_mfma_f32_16x16x32_bf16 v[224:227], v[18:21], v[10:13], v[54:57]
	v_mfma_f32_16x16x32_bf16 v[228:231], v[18:21], v[160:163], v[58:61]
	v_mfma_f32_16x16x32_bf16 v[232:235], v[18:21], v[164:167], v[62:65]
	v_mfma_f32_16x16x32_bf16 v[236:239], v[18:21], v[168:171], v[30:33]
	s_waitcnt lgkmcnt(1)
	v_mfma_f32_16x16x32_bf16 v[240:243], v[22:25], v[10:13], v[66:69]
	v_mfma_f32_16x16x32_bf16 v[64:67], v[22:25], v[168:171], v[34:37]
	s_waitcnt lgkmcnt(0)
	v_mfma_f32_16x16x32_bf16 v[40:43], v[172:175], v[164:167], v[92:95]
	v_mfma_f32_16x16x32_bf16 v[32:35], v[172:175], v[168:171], v[152:155]
	ds_read_b128 v[14:17], v8 offset:45056
	ds_read_b128 v[18:21], v8 offset:46080
	ds_read_b128 v[92:95], v8 offset:47104
	ds_read_b128 v[152:155], v8 offset:48128
	s_nop 0
	v_cvt_pk_bf16_f32 v64, v64, v65
	v_cvt_pk_bf16_f32 v65, v66, v67
	v_mfma_f32_16x16x32_bf16 v[80:83], v[22:25], v[160:163], v[70:73]
	v_cvt_pk_bf16_f32 v32, v32, v33
	v_cvt_pk_bf16_f32 v33, v34, v35
	v_cvt_pk_bf16_f32 v40, v40, v41
	v_mfma_f32_16x16x32_bf16 v[72:75], v[22:25], v[164:167], v[74:77]
	v_cvt_pk_bf16_f32 v41, v42, v43
	s_nop 2
	v_cvt_pk_bf16_f32 v80, v80, v81
	v_cvt_pk_bf16_f32 v81, v82, v83
	v_mfma_f32_16x16x32_bf16 v[48:51], v[172:175], v[160:163], v[84:87]
	s_waitcnt lgkmcnt(3)
	v_mfma_f32_16x16x32_bf16 v[112:115], v[14:17], v[10:13], v[112:115]
	v_cvt_pk_bf16_f32 v72, v72, v73
	v_cvt_pk_bf16_f32 v73, v74, v75
	s_nop 3
	v_cvt_pk_bf16_f32 v48, v48, v49
	v_mfma_f32_16x16x32_bf16 v[84:87], v[14:17], v[160:163], v[116:119]
	v_cvt_pk_bf16_f32 v49, v50, v51
	v_mfma_f32_16x16x32_bf16 v[76:79], v[14:17], v[164:167], v[120:123]
	v_mfma_f32_16x16x32_bf16 v[68:71], v[14:17], v[168:171], v[96:99]
	s_waitcnt lgkmcnt(2)
	v_mfma_f32_16x16x32_bf16 v[60:63], v[18:21], v[10:13], v[124:127]
	s_nop 0
	v_cvt_pk_bf16_f32 v96, v190, v191
	v_cvt_pk_bf16_f32 v97, v192, v193
	v_mfma_f32_16x16x32_bf16 v[52:55], v[18:21], v[160:163], v[128:131]
	v_mfma_f32_16x16x32_bf16 v[44:47], v[18:21], v[164:167], v[132:135]
	v_mfma_f32_16x16x32_bf16 v[36:39], v[18:21], v[168:171], v[100:103]
	s_waitcnt lgkmcnt(1)
; DI void st_bf4(u16* p, float a, float b, float c, float d) { *(uint2*)p = make_uint2(pk2(a, b), pk2(c, d)); }
;   template <int NT, int MT> DI void run(f32x4 (&acc)[NT][MT], int mb, int nb) const {
; #pragma unroll
;     for (int nt = 0; nt < NT; ++nt)
; #pragma unroll
;       for (int mt = 0; mt < MT; ++mt) {
;         f32x4 v = acc[nt][mt];
;         st_bf4(C + (size_t)(mb + mt * 16) * ldc + nb + nt * 16, v[0], v[1], v[2], v[3]);
;       }
;   }
	v_mfma_f32_16x16x32_bf16 v[28:31], v[92:95], v[10:13], v[108:111]
	v_mfma_f32_16x16x32_bf16 v[24:27], v[92:95], v[160:163], v[136:139]
	v_mfma_f32_16x16x32_bf16 v[20:23], v[92:95], v[164:167], v[140:143]
	s_nop 5
	v_cvt_pk_bf16_f32 v28, v28, v29
	v_cvt_pk_bf16_f32 v29, v30, v31
	v_cvt_pk_bf16_f32 v24, v24, v25
	v_mfma_f32_16x16x32_bf16 v[16:19], v[92:95], v[168:171], v[104:107]
	v_or_b32_e32 v92, v90, v89
	v_ashrrev_i32_e32 v93, 31, v92
	v_lshlrev_b64 v[90:91], 11, v[92:93]
	v_lshl_add_u64 v[90:91], s[92:93], 0, v[90:91]
	v_bfe_u32 v34, v185, 4, 1
	v_mad_u32_u24 v182, v34, 24, v182
	v_lshl_add_u64 v[88:89], v[90:91], 0, v[182:183]
	v_cvt_pk_bf16_f32 v90, v176, v177
	v_cvt_pk_bf16_f32 v91, v178, v179
	v_mov_b32_e32 v98, v90
	v_mov_b32_e32 v99, v91
	v_or_b32_e32 v90, 16, v92
	v_ashrrev_i32_e32 v91, 31, v90
	v_lshlrev_b64 v[90:91], 11, v[90:91]
	v_lshl_add_u64 v[90:91], s[92:93], 0, v[90:91]
	v_lshl_add_u64 v[90:91], v[90:91], 0, v[182:183]
	v_cvt_pk_bf16_f32 v94, v186, v187
	v_cvt_pk_bf16_f32 v95, v188, v189
	v_mov_b32_e32 v102, v94
	v_mov_b32_e32 v103, v95
	v_or_b32_e32 v94, 32, v92
	v_or_b32_e32 v92, 48, v92
	v_ashrrev_i32_e32 v93, 31, v92
	v_lshlrev_b64 v[92:93], 11, v[92:93]
	v_ashrrev_i32_e32 v95, 31, v94
	v_lshl_add_u64 v[92:93], s[92:93], 0, v[92:93]
	v_lshlrev_b64 v[94:95], 11, v[94:95]
	v_lshl_add_u64 v[92:93], v[92:93], 0, v[182:183]
	v_lshl_add_u64 v[94:95], s[92:93], 0, v[94:95]
	v_mov_b32_e32 v108, v32
	v_mov_b32_e32 v109, v33
	v_cvt_pk_bf16_f32 v32, v112, v113
	v_cvt_pk_bf16_f32 v33, v114, v115
	v_lshl_add_u64 v[94:95], v[94:95], 0, v[182:183]
	v_mov_b32_e32 v116, v32
	v_mov_b32_e32 v117, v33
	v_cvt_pk_bf16_f32 v32, v84, v85
	v_cvt_pk_bf16_f32 v33, v86, v87
	v_mov_b32_e32 v120, v96
	v_mov_b32_e32 v121, v97
	v_cvt_pk_bf16_f32 v96, v194, v195
	v_cvt_pk_bf16_f32 v97, v196, v197
	v_mov_b32_e32 v124, v32
	v_mov_b32_e32 v125, v33
	v_cvt_pk_bf16_f32 v32, v76, v77
	v_cvt_pk_bf16_f32 v33, v78, v79
	v_mfma_f32_16x16x32_bf16 v[56:59], v[172:175], v[10:13], v[156:159]
	v_mov_b32_e32 v110, v96
	v_mov_b32_e32 v111, v97
	v_cvt_pk_bf16_f32 v96, v224, v225
	v_cvt_pk_bf16_f32 v97, v226, v227
	s_waitcnt lgkmcnt(0)
	v_mfma_f32_16x16x32_bf16 v[12:15], v[152:155], v[10:13], v[4:7]
	v_mov_b32_e32 v82, v32
	v_mov_b32_e32 v83, v33
	v_cvt_pk_bf16_f32 v32, v68, v69
	v_cvt_pk_bf16_f32 v33, v70, v71
	v_mfma_f32_16x16x32_bf16 v[8:11], v[152:155], v[160:163], v[144:147]
	v_mov_b32_e32 v100, v96
	v_mov_b32_e32 v101, v97
	s_nop 1
	v_permlane16_swap_b32_e32 v98, v100
	v_permlane16_swap_b32_e32 v99, v101
	global_store_dwordx4 v[88:89], v[98:101], off
	v_cvt_pk_bf16_f32 v96, v228, v229
	v_cvt_pk_bf16_f32 v97, v230, v231
	v_mfma_f32_16x16x32_bf16 v[4:7], v[152:155], v[164:167], v[148:151]
	v_mov_b32_e32 v74, v32
	v_mov_b32_e32 v75, v33
	v_cvt_pk_bf16_f32 v32, v60, v61
	v_cvt_pk_bf16_f32 v33, v62, v63
	v_mfma_f32_16x16x32_bf16 v[0:3], v[152:155], v[168:171], v[0:3]
	v_mov_b32_e32 v104, v96
	v_mov_b32_e32 v105, v97
	s_nop 1
	v_permlane16_swap_b32_e32 v102, v104
	v_permlane16_swap_b32_e32 v103, v105
	global_store_dwordx4 v[90:91], v[102:105], off
	v_cvt_pk_bf16_f32 v96, v232, v233
	v_cvt_pk_bf16_f32 v97, v234, v235
	v_mov_b32_e32 v118, v32
	v_mov_b32_e32 v119, v33
	s_nop 1
	v_permlane16_swap_b32_e32 v116, v118
	v_permlane16_swap_b32_e32 v117, v119
	global_store_dwordx4 v[88:89], v[116:119], off offset:128
	v_cvt_pk_bf16_f32 v32, v52, v53
	v_cvt_pk_bf16_f32 v33, v54, v55
	v_mov_b32_e32 v122, v96
	v_mov_b32_e32 v123, v97
	s_nop 1
	v_permlane16_swap_b32_e32 v120, v122
	v_permlane16_swap_b32_e32 v121, v123
	global_store_dwordx4 v[94:95], v[120:123], off
	v_cvt_pk_bf16_f32 v96, v236, v237
	v_cvt_pk_bf16_f32 v97, v238, v239
	v_mov_b32_e32 v126, v32
	v_mov_b32_e32 v127, v33
	s_nop 1
	v_permlane16_swap_b32_e32 v124, v126
	v_permlane16_swap_b32_e32 v125, v127
	global_store_dwordx4 v[90:91], v[124:127], off offset:128
	v_cvt_pk_bf16_f32 v32, v44, v45
	v_cvt_pk_bf16_f32 v33, v46, v47
	v_mov_b32_e32 v112, v96
	v_mov_b32_e32 v113, v97
	s_nop 1
	v_permlane16_swap_b32_e32 v110, v112
	v_permlane16_swap_b32_e32 v111, v113
	global_store_dwordx4 v[92:93], v[110:113], off
	v_cvt_pk_bf16_f32 v96, v240, v241
	v_cvt_pk_bf16_f32 v97, v242, v243
	v_cvt_pk_bf16_f32 v56, v56, v57
	v_cvt_pk_bf16_f32 v57, v58, v59
	v_mov_b32_e32 v84, v32
	v_mov_b32_e32 v85, v33
	s_nop 1
	v_permlane16_swap_b32_e32 v82, v84
	v_permlane16_swap_b32_e32 v83, v85
	global_store_dwordx4 v[94:95], v[82:85], off offset:128
	v_cvt_pk_bf16_f32 v32, v36, v37
	v_cvt_pk_bf16_f32 v33, v38, v39
	v_cvt_pk_bf16_f32 v25, v26, v27
	v_cvt_pk_bf16_f32 v20, v20, v21
	v_cvt_pk_bf16_f32 v21, v22, v23
	v_cvt_pk_bf16_f32 v16, v16, v17
	v_cvt_pk_bf16_f32 v17, v18, v19
	v_cvt_pk_bf16_f32 v12, v12, v13
	v_cvt_pk_bf16_f32 v13, v14, v15
	v_cvt_pk_bf16_f32 v8, v8, v9
	v_cvt_pk_bf16_f32 v9, v10, v11
	v_cvt_pk_bf16_f32 v4, v4, v5
	v_cvt_pk_bf16_f32 v5, v6, v7
	v_cvt_pk_bf16_f32 v0, v0, v1
	v_cvt_pk_bf16_f32 v1, v2, v3
	v_mov_b32_e32 v106, v64
	v_mov_b32_e32 v107, v65
	s_nop 1
	v_permlane16_swap_b32_e32 v106, v108
	v_permlane16_swap_b32_e32 v107, v109
	global_store_dwordx4 v[92:93], v[106:109], off offset:64
	v_mov_b32_e32 v98, v56
	v_mov_b32_e32 v99, v57
	s_nop 1
	v_permlane16_swap_b32_e32 v96, v98
	v_permlane16_swap_b32_e32 v97, v99
	global_store_dwordx4 v[88:89], v[96:99], off offset:64
	v_mov_b32_e32 v82, v48
	v_mov_b32_e32 v83, v49
	s_nop 1
	v_permlane16_swap_b32_e32 v80, v82
	v_permlane16_swap_b32_e32 v81, v83
	global_store_dwordx4 v[90:91], v[80:83], off offset:64
	v_mov_b32_e32 v38, v72
	v_mov_b32_e32 v39, v73
	s_nop 1
	v_permlane16_swap_b32_e32 v38, v40
	v_permlane16_swap_b32_e32 v39, v41
	global_store_dwordx4 v[94:95], v[38:41], off offset:64
	v_mov_b32_e32 v76, v32
	v_mov_b32_e32 v77, v33
	s_nop 1
	v_permlane16_swap_b32_e32 v74, v76
	v_permlane16_swap_b32_e32 v75, v77
	global_store_dwordx4 v[92:93], v[74:77], off offset:128
	v_mov_b32_e32 v30, v12
	v_mov_b32_e32 v31, v13
	s_nop 1
	v_permlane16_swap_b32_e32 v28, v30
	v_permlane16_swap_b32_e32 v29, v31
	global_store_dwordx4 v[88:89], v[28:31], off offset:192
	v_mov_b32_e32 v26, v8
	v_mov_b32_e32 v27, v9
	s_nop 1
	v_permlane16_swap_b32_e32 v24, v26
	v_permlane16_swap_b32_e32 v25, v27
	global_store_dwordx4 v[90:91], v[24:27], off offset:192
	v_mov_b32_e32 v22, v4
	v_mov_b32_e32 v23, v5
	s_nop 1
	v_permlane16_swap_b32_e32 v20, v22
	v_permlane16_swap_b32_e32 v21, v23
	global_store_dwordx4 v[94:95], v[20:23], off offset:192
	v_mov_b32_e32 v18, v0
	v_mov_b32_e32 v19, v1
	s_nop 1
	v_permlane16_swap_b32_e32 v16, v18
	v_permlane16_swap_b32_e32 v17, v19
	global_store_dwordx4 v[92:93], v[16:19], off offset:192

; DI int get_tid() { int t = threadIdx.x; asm volatile("" : "+v"(t)); return t; }
; DI float zero_f() { float z = 0.f; asm volatile("" : "+v"(z)); return z; }
; template <int BM, class Epi>
; DI void gemm_dma(const u16* __restrict__ X, long ldx, const u16* __restrict__ W, long ldw, int K, char* smem,
;                  int m0, int n0, const Epi& epi) {
;     ...
;   const int tid = get_tid(), lane = tid & 63, wave = tid >> 6;
;   const int lr = lane & 15, g = lane >> 4;
;   const int rd = lr * 64 + ((g ^ ((4 - (lr >> 2)) & 3)) << 4);
;   const int xrow0 = BIG ? wave * 64 : (wave & 1) * (BM / 2);
;   const int wrow0 = BIG ? 0 : (wave >> 1) * 64;
;   f32x4 acc[NT][MT];
;   { const float z = zero_f();
; #pragma unroll
;   for (int a = 0; a < NT; ++a)
; #pragma unroll
;     for (int b = 0; b < MT; ++b) acc[a][b] = (f32x4){z, z, z, z}; }
;   const int wu = __builtin_amdgcn_readfirstlane(wave);
;   const unsigned sbase = (unsigned)__builtin_amdgcn_readfirstlane((int)(unsigned)(size_t)smem);
;   const int r16 = lane >> 2, chunk = (lane & 3) ^ ((4 - (r16 >> 2)) & 3);
;   const u16* xs = X + (long)(wu * XD * 16 + r16) * ldx + (chunk << 3);
;   const u16* ws = W + (long)(wu * 32 + r16) * ldw + (chunk << 3);
;   const long ldx16 = 16 * ldx, ldw16 = 16 * ldw;
;   const unsigned xdst = sbase + wu * XD * 1024, wdst = sbase + BM * 64 + wu * 2048;
;     ...
;   const int nk = K >> 5;
;   __syncthreads();
; #pragma unroll
;   for (int s = 0; s < D - 1; ++s) GD_ISSUE(s)
;   int cur = 0, nxt = D - 1, kt = 0;
; DI void knope_tile(const Params& p, int u, char* smem) {
;   const u16* W = (const u16*)(p.ws + OFF_W);
;   const u16* ckvb = (const u16*)(p.ws + OFF_CKVB);
;   EpiBF16 ek{(u16*)(p.ws + OFF_KN), 1024};
;   const int tm = u >> 3, tn = u & 7;
;   gemm_dma<256>(ckvb + (size_t)tm * 256 * 256, 256, W + WO_KV + (size_t)tn * 128 * 256, 256, 256, smem, tm * 256, tn * 128, ek);
; }
.LBB0_981:
	s_cmpk_gt_i32 s5, 0x62f
	s_mov_b64 s[38:39], -1
	s_cbranch_scc0 .LBB0_983
	s_add_i32 s4, s5, 0xfffff9d0
	s_bfe_u32 s98, s4, 0x30003
	s_and_b32 s99, s4, 7
	s_lshl_b32 s99, s99, 3
	s_andn2_b32 s4, s4, 63
	s_or_b32 s4, s4, s99
	s_or_b32 s4, s4, s98
	s_lshr_b32 s6, s4, 3
	s_and_b32 s4, s4, 7
	s_lshl_b32 s7, s6, 17
	s_add_u32 s8, s0, s7
	s_addc_u32 s9, s1, 0
	s_lshl_b32 s7, s4, 16
	v_mov_b32_e32 v9, v185
	s_add_u32 s10, s87, s7
	s_addc_u32 s11, s90, 0
	v_readfirstlane_b32 s7, v9
	v_lshrrev_b32_e32 v4, 4, v9
	s_ashr_i32 s12, s7, 6
	v_bfe_u32 v6, v9, 2, 4
	v_sub_u32_e32 v4, 0, v4
	s_andn2_b32 s7, s7, 63
	v_lshrrev_b32_e32 v1, 2, v9
	v_xor_b32_e32 v7, v9, v4
	v_or_b32_e32 v4, s7, v6
	v_and_b32_e32 v89, 15, v9
	v_bfe_u32 v88, v9, 4, 2
	v_sub_u32_e32 v1, 0, v1
	v_ashrrev_i32_e32 v5, 31, v4
	v_lshlrev_b32_e32 v0, 6, v89
	v_bitop3_b32 v1, v88, v1, 3 bitop3:0x78
	v_lshlrev_b64 v[4:5], 9, v[4:5]
	v_lshlrev_b32_e32 v7, 4, v7
	v_lshl_or_b32 v6, s12, 5, v6
	v_lshl_or_b32 v8, v1, 4, v0
	v_mov_b32_e32 v0, v183
	v_lshl_add_u64 v[4:5], s[8:9], 0, v[4:5]
	v_and_b32_e32 v182, 48, v7
	v_ashrrev_i32_e32 v7, 31, v6
	v_lshl_add_u64 v[4:5], v[4:5], 0, v[182:183]
	v_lshlrev_b64 v[6:7], 9, v[6:7]
	s_lshl_b32 s14, s12, 12
	s_waitcnt lgkmcnt(0)
	s_barrier
	s_mov_b32 m0, s14
	s_nop 0
	global_load_lds_dwordx4 v[4:5], off
	s_mov_b64 s[8:9], 0x2000
	v_lshl_add_u64 v[6:7], s[10:11], 0, v[6:7]
	v_lshl_add_u64 v[10:11], v[4:5], 0, s[8:9]
	s_or_b32 s15, s14, 0x400
	s_mov_b32 m0, s15
	s_nop 0
	global_load_lds_dwordx4 v[10:11], off
	s_mov_b64 s[10:11], 0x4000
	v_lshl_add_u64 v[10:11], v[4:5], 0, s[10:11]
	s_or_b32 s16, s14, 0x800
	s_mov_b32 m0, s16
	s_nop 0
	global_load_lds_dwordx4 v[10:11], off
	s_mov_b64 s[10:11], 0x6000
	s_lshl_b32 s42, s12, 11
	v_lshl_add_u64 v[10:11], v[4:5], 0, s[10:11]
	s_or_b32 s17, s14, 0xc00
	s_mov_b32 m0, s17
	s_nop 0
	global_load_lds_dwordx4 v[10:11], off
	v_lshl_add_u64 v[6:7], v[6:7], 0, v[182:183]
	s_add_i32 s13, s42, 0x4000
	s_mov_b32 m0, s13
	s_nop 0
	global_load_lds_dwordx4 v[6:7], off
	v_lshl_add_u64 v[10:11], v[6:7], 0, s[8:9]
	s_add_i32 s18, s42, 0x4400
	s_mov_b32 m0, s18
	s_nop 0
	global_load_lds_dwordx4 v[10:11], off
	v_lshl_add_u64 v[10:11], v[4:5], 0, 64
	s_add_i32 s7, s14, 0x6000
	s_mov_b32 m0, s7
	s_nop 0
	global_load_lds_dwordx4 v[10:11], off
	s_mov_b64 s[20:21], 0x2040
	v_lshl_add_u64 v[10:11], v[4:5], 0, s[20:21]
	s_add_i32 s8, s14, 0x6400
	s_mov_b32 m0, s8
	s_nop 0
	global_load_lds_dwordx4 v[10:11], off
	s_mov_b64 s[10:11], 0x4040
	v_lshl_add_u64 v[10:11], v[4:5], 0, s[10:11]
	s_add_i32 s9, s14, 0x6800
	s_mov_b32 m0, s9
	s_nop 0
	global_load_lds_dwordx4 v[10:11], off
	s_mov_b64 s[10:11], 0x6040
	v_lshl_add_u64 v[10:11], v[4:5], 0, s[10:11]
	s_add_i32 s10, s14, 0x6c00
	s_mov_b32 m0, s10
	s_nop 0
	global_load_lds_dwordx4 v[10:11], off
	v_lshl_add_u64 v[12:13], v[6:7], 0, 64
	s_add_i32 s11, s42, 0xa000
	s_mov_b32 m0, s11
	s_nop 0
	global_load_lds_dwordx4 v[12:13], off
	v_lshl_add_u64 v[10:11], v[6:7], 0, s[20:21]
	s_add_i32 s12, s42, 0xa400
	s_mov_b32 m0, s12
	s_nop 0
	global_load_lds_dwordx4 v[10:11], off
	s_waitcnt vmcnt(6)
	s_barrier
	v_lshl_add_u64 v[12:13], v[4:5], 0, s[28:29]
	s_add_i32 s19, s14, 0xc000
	s_mov_b32 m0, s19
	s_nop 0
	global_load_lds_dwordx4 v[12:13], off
	s_mov_b64 s[20:21], 0x2080
	v_lshl_add_u64 v[12:13], v[4:5], 0, s[20:21]
	s_add_i32 s34, s14, 0xc400
	s_mov_b32 m0, s34
	s_nop 0
	global_load_lds_dwordx4 v[12:13], off
	v_lshl_add_u64 v[12:13], v[4:5], 0, s[94:95]
	s_add_i32 s38, s14, 0xc800
	s_mov_b32 m0, s38
	s_nop 0
	global_load_lds_dwordx4 v[12:13], off
	s_mov_b64 s[22:23], 0x6080
	v_lshl_add_u64 v[12:13], v[4:5], 0, s[22:23]
	s_add_i32 s43, s14, 0xcc00
	s_mov_b32 m0, s43
	s_nop 0
	global_load_lds_dwordx4 v[12:13], off
	v_and_b32_e32 v90, 0xffffffc0, v9
	v_lshl_add_u64 v[10:11], v[6:7], 0, s[28:29]
	s_add_i32 s39, s42, 0x10000
	s_mov_b32 m0, s39
	s_nop 0
	global_load_lds_dwordx4 v[10:11], off
	v_lshl_add_u64 v[10:11], v[6:7], 0, s[20:21]
	s_add_i32 s42, s42, 0x10400
	s_mov_b32 m0, s42
	s_nop 0
	global_load_lds_dwordx4 v[10:11], off
	v_lshl_or_b32 v9, v90, 6, v8
	ds_read_b128 v[10:13], v9
	s_waitcnt vmcnt(7)
	ds_read_b128 v[14:17], v9 offset:1024
	s_waitcnt vmcnt(5)
	ds_read_b128 v[18:21], v9 offset:2048
	s_waitcnt vmcnt(5)
	ds_read_b128 v[22:25], v9 offset:3072
	s_waitcnt vmcnt(4)
	ds_read_b128 v[26:29], v8 offset:16384
	s_waitcnt vmcnt(4)
	ds_read_b128 v[30:33], v8 offset:17408
	ds_read_b128 v[34:37], v8 offset:18432
	ds_read_b128 v[38:41], v8 offset:19456
	s_waitcnt vmcnt(0)
	ds_read_b128 v[96:99], v8 offset:20480
	ds_read_b128 v[100:103], v8 offset:21504
	ds_read_b128 v[104:107], v8 offset:22528
	ds_read_b128 v[108:111], v8 offset:23552
	s_mov_b64 s[20:21], 0xc0
	v_mov_b32_e32 v1, v0
	v_mov_b32_e32 v2, v0
	v_mov_b32_e32 v3, v0
	v_lshl_add_u64 v[86:87], v[4:5], 0, s[20:21]
	v_lshl_add_u64 v[148:149], v[6:7], 0, s[20:21]
	s_waitcnt vmcnt(6)
	s_waitcnt lgkmcnt(0)
	s_barrier
; template <int N> DI void wait_vm() { asm volatile("s_waitcnt vmcnt(%0)" ::"n"(N) : "memory"); }
; template <int BM, class Epi>
; DI void gemm_dma(const u16* __restrict__ X, long ldx, const u16* __restrict__ W, long ldw, int K, char* smem,
;                  int m0, int n0, const Epi& epi) {
;     ...
;   do {
;     if (kt + D - 2 < nk) wait_vm<PW * (D - 2)>(); else wait_vm<0>();
;     __syncthreads();
;     if (kt + D - 1 < nk) GD_ISSUE(nxt)
;     nxt = (nxt + 1 == D) ? 0 : nxt + 1;
;     const char* base = smem + cur * STG;
;     cur = (cur + 1 == D) ? 0 : cur + 1;
;     bf16x8 xf[MT];
; #pragma unroll
;     for (int i = 0; i < MT; ++i) xf[i] = *(const bf16x8*)(base + (xrow0 + i * 16) * 64 + rd);
; #pragma unroll
;     for (int nh = 0; nh < NT / 4; ++nh) {
;       bf16x8 wf[4];
; #pragma unroll
;       for (int i = 0; i < 4; ++i) wf[i] = *(const bf16x8*)(base + BM * 64 + (wrow0 + (nh * 4 + i) * 16) * 64 + rd);
; #pragma unroll
;       for (int i = 0; i < 4; ++i)
; #pragma unroll
;         for (int mt = 0; mt < MT; ++mt)
;           acc[nh * 4 + i][mt] = __builtin_amdgcn_mfma_f32_16x16x32_bf16(wf[i], xf[mt], acc[nh * 4 + i][mt], 0, 0, 0);
;     }
;   } while (++kt < nk);
	s_mov_b32 m0, s14
	s_nop 0
	global_load_lds_dwordx4 v[86:87], off
	s_mov_b64 s[20:21], 0x20c0
	v_mfma_f32_16x16x32_bf16 v[42:45], v[26:29], v[10:13], v[0:3]
	s_mov_b64 s[22:23], 0x40c0
	v_or_b32_e32 v91, 0x10000, v8
	v_or_b32_e32 v174, 0x10400, v8
	v_mfma_f32_16x16x32_bf16 v[46:49], v[26:29], v[14:17], v[0:3]
	v_or_b32_e32 v175, 0x10800, v8
	v_or_b32_e32 v176, 0x10c00, v8
	v_or_b32_e32 v177, 0x11000, v8
	v_mfma_f32_16x16x32_bf16 v[50:53], v[26:29], v[18:21], v[0:3]
	v_or_b32_e32 v178, 0x11400, v8
	v_or_b32_e32 v179, 0x11800, v8
	v_or_b32_e32 v180, 0x11c00, v8
	v_mfma_f32_16x16x32_bf16 v[26:29], v[26:29], v[22:25], v[0:3]
	v_lshl_add_u32 v90, s6, 8, v90
	s_lshl_b32 s4, s4, 8
	v_lshl_or_b32 v182, v88, 3, s4
	v_mfma_f32_16x16x32_bf16 v[54:57], v[30:33], v[10:13], v[0:3]
	v_mfma_f32_16x16x32_bf16 v[58:61], v[30:33], v[14:17], v[0:3]
	v_mfma_f32_16x16x32_bf16 v[62:65], v[30:33], v[18:21], v[0:3]
	v_mfma_f32_16x16x32_bf16 v[30:33], v[30:33], v[22:25], v[0:3]
	v_mfma_f32_16x16x32_bf16 v[66:69], v[34:37], v[10:13], v[0:3]
	v_mfma_f32_16x16x32_bf16 v[70:73], v[34:37], v[14:17], v[0:3]
	v_mfma_f32_16x16x32_bf16 v[74:77], v[34:37], v[18:21], v[0:3]
	v_mfma_f32_16x16x32_bf16 v[34:37], v[34:37], v[22:25], v[0:3]
	v_mfma_f32_16x16x32_bf16 v[78:81], v[38:41], v[10:13], v[0:3]
	v_mfma_f32_16x16x32_bf16 v[82:85], v[38:41], v[14:17], v[0:3]
	v_mfma_f32_16x16x32_bf16 v[92:95], v[38:41], v[18:21], v[0:3]
	v_mfma_f32_16x16x32_bf16 v[38:41], v[38:41], v[22:25], v[0:3]
	v_mfma_f32_16x16x32_bf16 v[112:115], v[96:99], v[10:13], v[0:3]
	v_mfma_f32_16x16x32_bf16 v[116:119], v[96:99], v[14:17], v[0:3]
	v_mfma_f32_16x16x32_bf16 v[120:123], v[96:99], v[18:21], v[0:3]
	v_mfma_f32_16x16x32_bf16 v[96:99], v[96:99], v[22:25], v[0:3]
	v_mfma_f32_16x16x32_bf16 v[124:127], v[100:103], v[10:13], v[0:3]
	v_mfma_f32_16x16x32_bf16 v[128:131], v[100:103], v[14:17], v[0:3]
	v_mfma_f32_16x16x32_bf16 v[132:135], v[100:103], v[18:21], v[0:3]
	v_mfma_f32_16x16x32_bf16 v[100:103], v[100:103], v[22:25], v[0:3]
	v_mfma_f32_16x16x32_bf16 v[136:139], v[104:107], v[10:13], v[0:3]
	v_mfma_f32_16x16x32_bf16 v[140:143], v[104:107], v[14:17], v[0:3]
	v_mfma_f32_16x16x32_bf16 v[144:147], v[104:107], v[18:21], v[0:3]
	v_mfma_f32_16x16x32_bf16 v[104:107], v[104:107], v[22:25], v[0:3]
	v_mfma_f32_16x16x32_bf16 v[10:13], v[108:111], v[10:13], v[0:3]
	v_mfma_f32_16x16x32_bf16 v[14:17], v[108:111], v[14:17], v[0:3]
	v_mfma_f32_16x16x32_bf16 v[18:21], v[108:111], v[18:21], v[0:3]
	v_mfma_f32_16x16x32_bf16 v[0:3], v[108:111], v[22:25], v[0:3]
	v_lshl_add_u64 v[22:23], v[4:5], 0, s[20:21]
	s_mov_b32 m0, s15
	s_nop 0
	global_load_lds_dwordx4 v[22:23], off
	v_lshl_add_u64 v[22:23], v[4:5], 0, s[22:23]
	s_mov_b32 m0, s16
	s_nop 0
	global_load_lds_dwordx4 v[22:23], off
	s_mov_b64 s[22:23], 0x60c0
	v_lshl_add_u64 v[22:23], v[4:5], 0, s[22:23]
	s_mov_b32 m0, s17
	s_nop 0
	global_load_lds_dwordx4 v[22:23], off
	v_lshl_add_u64 v[22:23], v[6:7], 0, s[20:21]
	s_mov_b32 m0, s13
	s_nop 0
	global_load_lds_dwordx4 v[148:149], off
	s_mov_b64 s[20:21], 0x100
	s_mov_b32 m0, s18
	s_nop 0
	global_load_lds_dwordx4 v[22:23], off
	ds_read_b128 v[22:25], v9 offset:24576
	ds_read_b128 v[108:111], v9 offset:25600
	ds_read_b128 v[148:151], v9 offset:26624
	ds_read_b128 v[152:155], v9 offset:27648
	ds_read_b128 v[156:159], v8 offset:40960
	ds_read_b128 v[160:163], v8 offset:41984
	ds_read_b128 v[164:167], v8 offset:43008
	ds_read_b128 v[168:171], v8 offset:44032
	s_waitcnt lgkmcnt(3)
	v_mfma_f32_16x16x32_bf16 v[42:45], v[156:159], v[22:25], v[42:45]
	v_lshl_add_u64 v[86:87], v[4:5], 0, s[20:21]
	v_lshl_add_u64 v[172:173], v[6:7], 0, s[20:21]
	s_mov_b64 s[20:21], 0x2100
	v_mfma_f32_16x16x32_bf16 v[46:49], v[156:159], v[108:111], v[46:49]
	s_mov_b64 s[22:23], 0x4100
	v_mfma_f32_16x16x32_bf16 v[50:53], v[156:159], v[148:151], v[50:53]
	v_mfma_f32_16x16x32_bf16 v[26:29], v[156:159], v[152:155], v[26:29]
	s_waitcnt lgkmcnt(2)
	v_mfma_f32_16x16x32_bf16 v[54:57], v[160:163], v[22:25], v[54:57]
	v_mfma_f32_16x16x32_bf16 v[58:61], v[160:163], v[108:111], v[58:61]
	v_mfma_f32_16x16x32_bf16 v[62:65], v[160:163], v[148:151], v[62:65]
	v_mfma_f32_16x16x32_bf16 v[30:33], v[160:163], v[152:155], v[30:33]
	s_waitcnt lgkmcnt(1)
	v_mfma_f32_16x16x32_bf16 v[66:69], v[164:167], v[22:25], v[66:69]
	v_mfma_f32_16x16x32_bf16 v[70:73], v[164:167], v[108:111], v[70:73]
	v_mfma_f32_16x16x32_bf16 v[74:77], v[164:167], v[148:151], v[74:77]
	v_mfma_f32_16x16x32_bf16 v[34:37], v[164:167], v[152:155], v[34:37]
	s_waitcnt lgkmcnt(0)
	v_mfma_f32_16x16x32_bf16 v[78:81], v[168:171], v[22:25], v[78:81]
	v_mfma_f32_16x16x32_bf16 v[82:85], v[168:171], v[108:111], v[82:85]
	v_mfma_f32_16x16x32_bf16 v[92:95], v[168:171], v[148:151], v[92:95]
	v_mfma_f32_16x16x32_bf16 v[38:41], v[168:171], v[152:155], v[38:41]
	ds_read_b128 v[156:159], v8 offset:45056
	ds_read_b128 v[160:163], v8 offset:46080
	ds_read_b128 v[164:167], v8 offset:47104
	ds_read_b128 v[168:171], v8 offset:48128
	s_waitcnt vmcnt(6)
	s_waitcnt lgkmcnt(0)
	s_barrier
; template <int N> DI void wait_vm() { asm volatile("s_waitcnt vmcnt(%0)" ::"n"(N) : "memory"); }
; template <int BM, class Epi>
; DI void gemm_dma(const u16* __restrict__ X, long ldx, const u16* __restrict__ W, long ldw, int K, char* smem,
;                  int m0, int n0, const Epi& epi) {
;     ...
;   const int nk = K >> 5;
;   __syncthreads();
; #pragma unroll
;   for (int s = 0; s < D - 1; ++s) GD_ISSUE(s)
;   int cur = 0, nxt = D - 1, kt = 0;
;   do {
;     if (kt + D - 2 < nk) wait_vm<PW * (D - 2)>(); else wait_vm<0>();
;     __syncthreads();
;     if (kt + D - 1 < nk) GD_ISSUE(nxt)
;     nxt = (nxt + 1 == D) ? 0 : nxt + 1;
;     const char* base = smem + cur * STG;
;     cur = (cur + 1 == D) ? 0 : cur + 1;
;     bf16x8 xf[MT];
; #pragma unroll
;     for (int i = 0; i < MT; ++i) xf[i] = *(const bf16x8*)(base + (xrow0 + i * 16) * 64 + rd);
; #pragma unroll
;     for (int nh = 0; nh < NT / 4; ++nh) {
;       bf16x8 wf[4];
; #pragma unroll
;       for (int i = 0; i < 4; ++i) wf[i] = *(const bf16x8*)(base + BM * 64 + (wrow0 + (nh * 4 + i) * 16) * 64 + rd);
; #pragma unroll
;       for (int i = 0; i < 4; ++i)
; #pragma unroll
;         for (int mt = 0; mt < MT; ++mt)
;           acc[nh * 4 + i][mt] = __builtin_amdgcn_mfma_f32_16x16x32_bf16(wf[i], xf[mt], acc[nh * 4 + i][mt], 0, 0, 0);
;     }
;   } while (++kt < nk);
	s_mov_b32 m0, s7
	s_nop 0
	global_load_lds_dwordx4 v[86:87], off
	v_mfma_f32_16x16x32_bf16 v[112:115], v[156:159], v[22:25], v[112:115]
	v_mfma_f32_16x16x32_bf16 v[124:127], v[160:163], v[22:25], v[124:127]
	v_mfma_f32_16x16x32_bf16 v[136:139], v[164:167], v[22:25], v[136:139]
	v_mfma_f32_16x16x32_bf16 v[10:13], v[168:171], v[22:25], v[10:13]
	v_lshl_add_u64 v[22:23], v[4:5], 0, s[20:21]
	s_mov_b32 m0, s8
	s_nop 0
	global_load_lds_dwordx4 v[22:23], off
	v_lshl_add_u64 v[22:23], v[4:5], 0, s[22:23]
	s_mov_b32 m0, s9
	s_nop 0
	global_load_lds_dwordx4 v[22:23], off
	s_mov_b64 s[22:23], 0x6100
	v_lshl_add_u64 v[22:23], v[4:5], 0, s[22:23]
	s_mov_b32 m0, s10
	s_nop 0
	global_load_lds_dwordx4 v[22:23], off
	v_lshl_add_u64 v[22:23], v[6:7], 0, s[20:21]
	s_mov_b32 m0, s11
	s_nop 0
	global_load_lds_dwordx4 v[172:173], off
	v_mfma_f32_16x16x32_bf16 v[116:119], v[156:159], v[108:111], v[116:119]
	s_mov_b32 m0, s12
	s_nop 0
	global_load_lds_dwordx4 v[22:23], off
	s_mov_b64 s[20:21], 0x140
	v_lshl_add_u64 v[86:87], v[4:5], 0, s[20:21]
	v_mfma_f32_16x16x32_bf16 v[120:123], v[156:159], v[148:151], v[120:123]
	v_lshl_add_u64 v[172:173], v[6:7], 0, s[20:21]
	s_mov_b64 s[20:21], 0x2140
	s_mov_b64 s[22:23], 0x4140
	v_mfma_f32_16x16x32_bf16 v[96:99], v[156:159], v[152:155], v[96:99]
	v_mfma_f32_16x16x32_bf16 v[128:131], v[160:163], v[108:111], v[128:131]
	v_mfma_f32_16x16x32_bf16 v[132:135], v[160:163], v[148:151], v[132:135]
	v_mfma_f32_16x16x32_bf16 v[100:103], v[160:163], v[152:155], v[100:103]
	v_mfma_f32_16x16x32_bf16 v[140:143], v[164:167], v[108:111], v[140:143]
	v_mfma_f32_16x16x32_bf16 v[144:147], v[164:167], v[148:151], v[144:147]
	v_mfma_f32_16x16x32_bf16 v[104:107], v[164:167], v[152:155], v[104:107]
	v_mfma_f32_16x16x32_bf16 v[14:17], v[168:171], v[108:111], v[14:17]
	v_mfma_f32_16x16x32_bf16 v[18:21], v[168:171], v[148:151], v[18:21]
	v_mfma_f32_16x16x32_bf16 v[0:3], v[168:171], v[152:155], v[0:3]
	ds_read_b128 v[22:25], v9 offset:49152
	ds_read_b128 v[108:111], v9 offset:50176
	ds_read_b128 v[148:151], v9 offset:51200
	ds_read_b128 v[152:155], v9 offset:52224
	ds_read_b128 v[156:159], v91
	ds_read_b128 v[160:163], v174
	ds_read_b128 v[164:167], v175
	ds_read_b128 v[168:171], v176
	s_waitcnt lgkmcnt(3)
	v_mfma_f32_16x16x32_bf16 v[42:45], v[156:159], v[22:25], v[42:45]
	v_mfma_f32_16x16x32_bf16 v[46:49], v[156:159], v[108:111], v[46:49]
	v_mfma_f32_16x16x32_bf16 v[50:53], v[156:159], v[148:151], v[50:53]
	v_mfma_f32_16x16x32_bf16 v[26:29], v[156:159], v[152:155], v[26:29]
	ds_read_b128 v[156:159], v177
	s_waitcnt lgkmcnt(3)
	v_mfma_f32_16x16x32_bf16 v[54:57], v[160:163], v[22:25], v[54:57]
	v_mfma_f32_16x16x32_bf16 v[58:61], v[160:163], v[108:111], v[58:61]
	v_mfma_f32_16x16x32_bf16 v[62:65], v[160:163], v[148:151], v[62:65]
	v_mfma_f32_16x16x32_bf16 v[30:33], v[160:163], v[152:155], v[30:33]
	ds_read_b128 v[160:163], v178
	s_waitcnt lgkmcnt(3)
	v_mfma_f32_16x16x32_bf16 v[66:69], v[164:167], v[22:25], v[66:69]
	v_mfma_f32_16x16x32_bf16 v[70:73], v[164:167], v[108:111], v[70:73]
	v_mfma_f32_16x16x32_bf16 v[74:77], v[164:167], v[148:151], v[74:77]
	v_mfma_f32_16x16x32_bf16 v[34:37], v[164:167], v[152:155], v[34:37]
	ds_read_b128 v[164:167], v179
	s_waitcnt lgkmcnt(3)
	v_mfma_f32_16x16x32_bf16 v[78:81], v[168:171], v[22:25], v[78:81]
	v_mfma_f32_16x16x32_bf16 v[82:85], v[168:171], v[108:111], v[82:85]
	v_mfma_f32_16x16x32_bf16 v[92:95], v[168:171], v[148:151], v[92:95]
	v_mfma_f32_16x16x32_bf16 v[38:41], v[168:171], v[152:155], v[38:41]
	ds_read_b128 v[168:171], v180
	s_waitcnt vmcnt(6)
	s_waitcnt lgkmcnt(0)
	s_barrier
	s_mov_b32 m0, s19
	s_nop 0
	global_load_lds_dwordx4 v[86:87], off
	v_mfma_f32_16x16x32_bf16 v[112:115], v[156:159], v[22:25], v[112:115]
	v_mfma_f32_16x16x32_bf16 v[124:127], v[160:163], v[22:25], v[124:127]
	v_mfma_f32_16x16x32_bf16 v[136:139], v[164:167], v[22:25], v[136:139]
	v_mfma_f32_16x16x32_bf16 v[10:13], v[168:171], v[22:25], v[10:13]
	v_lshl_add_u64 v[22:23], v[4:5], 0, s[20:21]
	s_mov_b32 m0, s34
	s_nop 0
	global_load_lds_dwordx4 v[22:23], off
	v_lshl_add_u64 v[22:23], v[4:5], 0, s[22:23]
	s_mov_b32 m0, s38
	s_nop 0
	global_load_lds_dwordx4 v[22:23], off
	s_mov_b64 s[22:23], 0x6140
	v_lshl_add_u64 v[22:23], v[4:5], 0, s[22:23]
	s_mov_b32 m0, s43
	s_nop 0
	global_load_lds_dwordx4 v[22:23], off
	v_lshl_add_u64 v[22:23], v[6:7], 0, s[20:21]
	s_mov_b32 m0, s39
	s_nop 0
	global_load_lds_dwordx4 v[172:173], off
	v_mfma_f32_16x16x32_bf16 v[116:119], v[156:159], v[108:111], v[116:119]
	s_mov_b32 m0, s42
	s_nop 0
	global_load_lds_dwordx4 v[22:23], off
	s_mov_b64 s[20:21], 0x180
	v_lshl_add_u64 v[86:87], v[4:5], 0, s[20:21]
	v_mfma_f32_16x16x32_bf16 v[120:123], v[156:159], v[148:151], v[120:123]
	v_lshl_add_u64 v[172:173], v[6:7], 0, s[20:21]
	s_mov_b64 s[20:21], 0x2180
	s_mov_b64 s[38:39], 0
	v_mfma_f32_16x16x32_bf16 v[96:99], v[156:159], v[152:155], v[96:99]
	v_mfma_f32_16x16x32_bf16 v[128:131], v[160:163], v[108:111], v[128:131]
	v_mfma_f32_16x16x32_bf16 v[132:135], v[160:163], v[148:151], v[132:135]
	v_mfma_f32_16x16x32_bf16 v[100:103], v[160:163], v[152:155], v[100:103]
	v_mfma_f32_16x16x32_bf16 v[140:143], v[164:167], v[108:111], v[140:143]
	v_mfma_f32_16x16x32_bf16 v[144:147], v[164:167], v[148:151], v[144:147]
	v_mfma_f32_16x16x32_bf16 v[104:107], v[164:167], v[152:155], v[104:107]
	v_mfma_f32_16x16x32_bf16 v[14:17], v[168:171], v[108:111], v[14:17]
	v_mfma_f32_16x16x32_bf16 v[18:21], v[168:171], v[148:151], v[18:21]
	v_mfma_f32_16x16x32_bf16 v[0:3], v[168:171], v[152:155], v[0:3]
	ds_read_b128 v[22:25], v9
	ds_read_b128 v[108:111], v9 offset:1024
	ds_read_b128 v[148:151], v9 offset:2048
	ds_read_b128 v[152:155], v9 offset:3072
	ds_read_b128 v[156:159], v8 offset:16384
	ds_read_b128 v[160:163], v8 offset:17408
	ds_read_b128 v[164:167], v8 offset:18432
	ds_read_b128 v[168:171], v8 offset:19456
	s_waitcnt lgkmcnt(3)
; template <int N> DI void wait_vm() { asm volatile("s_waitcnt vmcnt(%0)" ::"n"(N) : "memory"); }
; template <int BM, class Epi>
; DI void gemm_dma(const u16* __restrict__ X, long ldx, const u16* __restrict__ W, long ldw, int K, char* smem,
;                  int m0, int n0, const Epi& epi) {
;     ...
;   const int nk = K >> 5;
;   __syncthreads();
; #pragma unroll
;   for (int s = 0; s < D - 1; ++s) GD_ISSUE(s)
;   int cur = 0, nxt = D - 1, kt = 0;
;   do {
;     if (kt + D - 2 < nk) wait_vm<PW * (D - 2)>(); else wait_vm<0>();
;     __syncthreads();
;     if (kt + D - 1 < nk) GD_ISSUE(nxt)
;     nxt = (nxt + 1 == D) ? 0 : nxt + 1;
;     const char* base = smem + cur * STG;
;     cur = (cur + 1 == D) ? 0 : cur + 1;
;     bf16x8 xf[MT];
; #pragma unroll
;     for (int i = 0; i < MT; ++i) xf[i] = *(const bf16x8*)(base + (xrow0 + i * 16) * 64 + rd);
; #pragma unroll
;     for (int nh = 0; nh < NT / 4; ++nh) {
;       bf16x8 wf[4];
; #pragma unroll
;       for (int i = 0; i < 4; ++i) wf[i] = *(const bf16x8*)(base + BM * 64 + (wrow0 + (nh * 4 + i) * 16) * 64 + rd);
; #pragma unroll
;       for (int i = 0; i < 4; ++i)
; #pragma unroll
;         for (int mt = 0; mt < MT; ++mt)
;           acc[nh * 4 + i][mt] = __builtin_amdgcn_mfma_f32_16x16x32_bf16(wf[i], xf[mt], acc[nh * 4 + i][mt], 0, 0, 0);
;     }
;   } while (++kt < nk);
	v_mfma_f32_16x16x32_bf16 v[42:45], v[156:159], v[22:25], v[42:45]
	v_mfma_f32_16x16x32_bf16 v[46:49], v[156:159], v[108:111], v[46:49]
	v_mfma_f32_16x16x32_bf16 v[50:53], v[156:159], v[148:151], v[50:53]
	v_mfma_f32_16x16x32_bf16 v[26:29], v[156:159], v[152:155], v[26:29]
	s_waitcnt lgkmcnt(2)
	v_mfma_f32_16x16x32_bf16 v[54:57], v[160:163], v[22:25], v[54:57]
	v_mfma_f32_16x16x32_bf16 v[58:61], v[160:163], v[108:111], v[58:61]
	v_mfma_f32_16x16x32_bf16 v[62:65], v[160:163], v[148:151], v[62:65]
	v_mfma_f32_16x16x32_bf16 v[30:33], v[160:163], v[152:155], v[30:33]
	s_waitcnt lgkmcnt(1)
	v_mfma_f32_16x16x32_bf16 v[66:69], v[164:167], v[22:25], v[66:69]
	v_mfma_f32_16x16x32_bf16 v[70:73], v[164:167], v[108:111], v[70:73]
	v_mfma_f32_16x16x32_bf16 v[74:77], v[164:167], v[148:151], v[74:77]
	v_mfma_f32_16x16x32_bf16 v[34:37], v[164:167], v[152:155], v[34:37]
	s_waitcnt lgkmcnt(0)
	v_mfma_f32_16x16x32_bf16 v[78:81], v[168:171], v[22:25], v[78:81]
	v_mfma_f32_16x16x32_bf16 v[82:85], v[168:171], v[108:111], v[82:85]
	v_mfma_f32_16x16x32_bf16 v[92:95], v[168:171], v[148:151], v[92:95]
	v_mfma_f32_16x16x32_bf16 v[38:41], v[168:171], v[152:155], v[38:41]
	ds_read_b128 v[156:159], v8 offset:20480
	ds_read_b128 v[160:163], v8 offset:21504
	ds_read_b128 v[164:167], v8 offset:22528
	ds_read_b128 v[168:171], v8 offset:23552
	s_waitcnt vmcnt(6)
	s_waitcnt lgkmcnt(0)
	s_barrier
	s_mov_b32 m0, s14
	s_nop 0
	global_load_lds_dwordx4 v[86:87], off
	v_mfma_f32_16x16x32_bf16 v[112:115], v[156:159], v[22:25], v[112:115]
	v_mfma_f32_16x16x32_bf16 v[124:127], v[160:163], v[22:25], v[124:127]
	v_mfma_f32_16x16x32_bf16 v[136:139], v[164:167], v[22:25], v[136:139]
	v_mfma_f32_16x16x32_bf16 v[10:13], v[168:171], v[22:25], v[10:13]
	v_lshl_add_u64 v[22:23], v[4:5], 0, s[20:21]
	s_mov_b32 m0, s15
	s_nop 0
	global_load_lds_dwordx4 v[22:23], off
	s_mov_b64 s[14:15], 0x4180
	v_lshl_add_u64 v[22:23], v[4:5], 0, s[14:15]
	s_mov_b32 m0, s16
	s_nop 0
	global_load_lds_dwordx4 v[22:23], off
	s_mov_b64 s[14:15], 0x6180
	v_lshl_add_u64 v[22:23], v[4:5], 0, s[14:15]
	s_mov_b32 m0, s17
	s_nop 0
	global_load_lds_dwordx4 v[22:23], off
	v_lshl_add_u64 v[22:23], v[6:7], 0, s[20:21]
	s_mov_b32 m0, s13
	s_nop 0
	global_load_lds_dwordx4 v[172:173], off
	s_mov_b32 m0, s18
	s_nop 0
	global_load_lds_dwordx4 v[22:23], off
	v_mfma_f32_16x16x32_bf16 v[116:119], v[156:159], v[108:111], v[116:119]
	s_mov_b64 s[14:15], 0x1c0
	v_lshl_add_u64 v[86:87], v[4:5], 0, s[14:15]
	v_lshl_add_u64 v[172:173], v[6:7], 0, s[14:15]
	v_mfma_f32_16x16x32_bf16 v[120:123], v[156:159], v[148:151], v[120:123]
	s_mov_b64 s[14:15], 0x21c0
	s_mov_b64 s[16:17], 0x41c0
	v_mfma_f32_16x16x32_bf16 v[96:99], v[156:159], v[152:155], v[96:99]
	v_mfma_f32_16x16x32_bf16 v[128:131], v[160:163], v[108:111], v[128:131]
	v_mfma_f32_16x16x32_bf16 v[132:135], v[160:163], v[148:151], v[132:135]
	v_mfma_f32_16x16x32_bf16 v[100:103], v[160:163], v[152:155], v[100:103]
	v_mfma_f32_16x16x32_bf16 v[140:143], v[164:167], v[108:111], v[140:143]
	v_mfma_f32_16x16x32_bf16 v[144:147], v[164:167], v[148:151], v[144:147]
	v_mfma_f32_16x16x32_bf16 v[104:107], v[164:167], v[152:155], v[104:107]
	v_mfma_f32_16x16x32_bf16 v[14:17], v[168:171], v[108:111], v[14:17]
	v_mfma_f32_16x16x32_bf16 v[18:21], v[168:171], v[148:151], v[18:21]
	v_mfma_f32_16x16x32_bf16 v[0:3], v[168:171], v[152:155], v[0:3]
	ds_read_b128 v[22:25], v9 offset:24576
	ds_read_b128 v[108:111], v9 offset:25600
	ds_read_b128 v[148:151], v9 offset:26624
	ds_read_b128 v[152:155], v9 offset:27648
	ds_read_b128 v[156:159], v8 offset:40960
	ds_read_b128 v[160:163], v8 offset:41984
	ds_read_b128 v[164:167], v8 offset:43008
	ds_read_b128 v[168:171], v8 offset:44032
	s_waitcnt lgkmcnt(3)
	v_mfma_f32_16x16x32_bf16 v[42:45], v[156:159], v[22:25], v[42:45]
	v_mfma_f32_16x16x32_bf16 v[46:49], v[156:159], v[108:111], v[46:49]
	v_mfma_f32_16x16x32_bf16 v[50:53], v[156:159], v[148:151], v[50:53]
	v_mfma_f32_16x16x32_bf16 v[26:29], v[156:159], v[152:155], v[26:29]
	s_waitcnt lgkmcnt(2)
	v_mfma_f32_16x16x32_bf16 v[54:57], v[160:163], v[22:25], v[54:57]
	v_mfma_f32_16x16x32_bf16 v[58:61], v[160:163], v[108:111], v[58:61]
	v_mfma_f32_16x16x32_bf16 v[62:65], v[160:163], v[148:151], v[62:65]
	v_mfma_f32_16x16x32_bf16 v[30:33], v[160:163], v[152:155], v[30:33]
	s_waitcnt lgkmcnt(1)
	v_mfma_f32_16x16x32_bf16 v[66:69], v[164:167], v[22:25], v[66:69]
	v_mfma_f32_16x16x32_bf16 v[70:73], v[164:167], v[108:111], v[70:73]
	v_mfma_f32_16x16x32_bf16 v[74:77], v[164:167], v[148:151], v[74:77]
	v_mfma_f32_16x16x32_bf16 v[34:37], v[164:167], v[152:155], v[34:37]
	s_waitcnt lgkmcnt(0)
	v_mfma_f32_16x16x32_bf16 v[78:81], v[168:171], v[22:25], v[78:81]
	v_mfma_f32_16x16x32_bf16 v[82:85], v[168:171], v[108:111], v[82:85]
	v_mfma_f32_16x16x32_bf16 v[92:95], v[168:171], v[148:151], v[92:95]
	v_mfma_f32_16x16x32_bf16 v[38:41], v[168:171], v[152:155], v[38:41]
	ds_read_b128 v[156:159], v8 offset:45056
	ds_read_b128 v[160:163], v8 offset:46080
	ds_read_b128 v[164:167], v8 offset:47104
	ds_read_b128 v[168:171], v8 offset:48128
	s_waitcnt vmcnt(6)
	s_waitcnt lgkmcnt(0)
	s_barrier
; template <int N> DI void wait_vm() { asm volatile("s_waitcnt vmcnt(%0)" ::"n"(N) : "memory"); }
; template <int BM, class Epi>
; DI void gemm_dma(const u16* __restrict__ X, long ldx, const u16* __restrict__ W, long ldw, int K, char* smem,
;                  int m0, int n0, const Epi& epi) {
;     ...
;   const int nk = K >> 5;
;   __syncthreads();
; #pragma unroll
;   for (int s = 0; s < D - 1; ++s) GD_ISSUE(s)
;   int cur = 0, nxt = D - 1, kt = 0;
;   do {
;     if (kt + D - 2 < nk) wait_vm<PW * (D - 2)>(); else wait_vm<0>();
;     __syncthreads();
;     if (kt + D - 1 < nk) GD_ISSUE(nxt)
;     nxt = (nxt + 1 == D) ? 0 : nxt + 1;
;     const char* base = smem + cur * STG;
;     cur = (cur + 1 == D) ? 0 : cur + 1;
;     bf16x8 xf[MT];
; #pragma unroll
;     for (int i = 0; i < MT; ++i) xf[i] = *(const bf16x8*)(base + (xrow0 + i * 16) * 64 + rd);
; #pragma unroll
;     for (int nh = 0; nh < NT / 4; ++nh) {
;       bf16x8 wf[4];
; #pragma unroll
;       for (int i = 0; i < 4; ++i) wf[i] = *(const bf16x8*)(base + BM * 64 + (wrow0 + (nh * 4 + i) * 16) * 64 + rd);
; #pragma unroll
;       for (int i = 0; i < 4; ++i)
; #pragma unroll
;         for (int mt = 0; mt < MT; ++mt)
;           acc[nh * 4 + i][mt] = __builtin_amdgcn_mfma_f32_16x16x32_bf16(wf[i], xf[mt], acc[nh * 4 + i][mt], 0, 0, 0);
;     }
;   } while (++kt < nk);
	s_mov_b32 m0, s7
	s_nop 0
	global_load_lds_dwordx4 v[86:87], off
	v_mfma_f32_16x16x32_bf16 v[112:115], v[156:159], v[22:25], v[112:115]
	v_mfma_f32_16x16x32_bf16 v[124:127], v[160:163], v[22:25], v[124:127]
	v_mfma_f32_16x16x32_bf16 v[136:139], v[164:167], v[22:25], v[136:139]
	v_mfma_f32_16x16x32_bf16 v[10:13], v[168:171], v[22:25], v[10:13]
	v_lshl_add_u64 v[22:23], v[4:5], 0, s[14:15]
	s_mov_b32 m0, s8
	s_nop 0
	global_load_lds_dwordx4 v[22:23], off
	v_lshl_add_u64 v[22:23], v[4:5], 0, s[16:17]
	s_mov_b32 m0, s9
	s_nop 0
	global_load_lds_dwordx4 v[22:23], off
	s_mov_b64 s[8:9], 0x61c0
	v_lshl_add_u64 v[4:5], v[4:5], 0, s[8:9]
	s_mov_b32 m0, s10
	s_nop 0
	global_load_lds_dwordx4 v[4:5], off
	v_lshl_add_u64 v[4:5], v[6:7], 0, s[14:15]
	s_mov_b32 m0, s11
	s_nop 0
	global_load_lds_dwordx4 v[172:173], off
	v_mfma_f32_16x16x32_bf16 v[116:119], v[156:159], v[108:111], v[116:119]
	s_mov_b32 m0, s12
	s_nop 0
	global_load_lds_dwordx4 v[4:5], off
	v_readlane_b32 s8, v255, 5
	v_readlane_b32 s14, v255, 11
	v_mfma_f32_16x16x32_bf16 v[120:123], v[156:159], v[148:151], v[120:123]
	v_readlane_b32 s9, v255, 6
	v_readlane_b32 s10, v255, 7
	v_readlane_b32 s11, v255, 8
	v_mfma_f32_16x16x32_bf16 v[96:99], v[156:159], v[152:155], v[96:99]
	v_readlane_b32 s12, v255, 9
	v_readlane_b32 s13, v255, 10
	v_readlane_b32 s15, v255, 12
	v_mfma_f32_16x16x32_bf16 v[128:131], v[160:163], v[108:111], v[128:131]
	s_add_i32 s4, s5, s14
	v_mfma_f32_16x16x32_bf16 v[132:135], v[160:163], v[148:151], v[132:135]
	v_mfma_f32_16x16x32_bf16 v[100:103], v[160:163], v[152:155], v[100:103]
	v_mfma_f32_16x16x32_bf16 v[140:143], v[164:167], v[108:111], v[140:143]
	v_mfma_f32_16x16x32_bf16 v[144:147], v[164:167], v[148:151], v[144:147]
	v_mfma_f32_16x16x32_bf16 v[104:107], v[164:167], v[152:155], v[104:107]
	v_mfma_f32_16x16x32_bf16 v[14:17], v[168:171], v[108:111], v[14:17]
	v_mfma_f32_16x16x32_bf16 v[18:21], v[168:171], v[148:151], v[18:21]
	v_mfma_f32_16x16x32_bf16 v[0:3], v[168:171], v[152:155], v[0:3]
	ds_read_b128 v[4:7], v9 offset:49152
	ds_read_b128 v[22:25], v9 offset:50176
	ds_read_b128 v[108:111], v9 offset:51200
	ds_read_b128 v[148:151], v9 offset:52224
	ds_read_b128 v[152:155], v91
	ds_read_b128 v[156:159], v174
	ds_read_b128 v[160:163], v175
	ds_read_b128 v[164:167], v176
	s_waitcnt lgkmcnt(3)
	v_mfma_f32_16x16x32_bf16 v[42:45], v[152:155], v[4:7], v[42:45]
	v_mfma_f32_16x16x32_bf16 v[46:49], v[152:155], v[22:25], v[46:49]
	v_mfma_f32_16x16x32_bf16 v[50:53], v[152:155], v[108:111], v[50:53]
	v_mfma_f32_16x16x32_bf16 v[26:29], v[152:155], v[148:151], v[26:29]
	s_waitcnt lgkmcnt(2)
	v_mfma_f32_16x16x32_bf16 v[54:57], v[156:159], v[4:7], v[54:57]
	v_mfma_f32_16x16x32_bf16 v[58:61], v[156:159], v[22:25], v[58:61]
	v_mfma_f32_16x16x32_bf16 v[62:65], v[156:159], v[108:111], v[62:65]
	v_mfma_f32_16x16x32_bf16 v[30:33], v[156:159], v[148:151], v[30:33]
	s_waitcnt lgkmcnt(1)
	v_mfma_f32_16x16x32_bf16 v[66:69], v[160:163], v[4:7], v[66:69]
	v_mfma_f32_16x16x32_bf16 v[70:73], v[160:163], v[22:25], v[70:73]
	v_mfma_f32_16x16x32_bf16 v[74:77], v[160:163], v[108:111], v[74:77]
	v_mfma_f32_16x16x32_bf16 v[34:37], v[160:163], v[148:151], v[34:37]
	s_waitcnt lgkmcnt(0)
	v_mfma_f32_16x16x32_bf16 v[78:81], v[164:167], v[4:7], v[78:81]
	v_mfma_f32_16x16x32_bf16 v[82:85], v[164:167], v[22:25], v[82:85]
	v_mfma_f32_16x16x32_bf16 v[92:95], v[164:167], v[108:111], v[92:95]
	v_mfma_f32_16x16x32_bf16 v[38:41], v[164:167], v[148:151], v[38:41]
	ds_read_b128 v[152:155], v177
	ds_read_b128 v[156:159], v178
	ds_read_b128 v[160:163], v179
	ds_read_b128 v[164:167], v180
	s_waitcnt vmcnt(6)
	s_waitcnt lgkmcnt(0)
	v_mfma_f32_16x16x32_bf16 v[112:115], v[152:155], v[4:7], v[112:115]
	s_barrier
	v_mfma_f32_16x16x32_bf16 v[116:119], v[152:155], v[22:25], v[116:119]
	v_mfma_f32_16x16x32_bf16 v[120:123], v[152:155], v[108:111], v[120:123]
	v_mfma_f32_16x16x32_bf16 v[96:99], v[152:155], v[148:151], v[96:99]
	v_mfma_f32_16x16x32_bf16 v[124:127], v[156:159], v[4:7], v[124:127]
	v_mfma_f32_16x16x32_bf16 v[128:131], v[156:159], v[22:25], v[128:131]
	v_mfma_f32_16x16x32_bf16 v[132:135], v[156:159], v[108:111], v[132:135]
	v_mfma_f32_16x16x32_bf16 v[100:103], v[156:159], v[148:151], v[100:103]
	v_mfma_f32_16x16x32_bf16 v[136:139], v[160:163], v[4:7], v[136:139]
	v_mfma_f32_16x16x32_bf16 v[140:143], v[160:163], v[22:25], v[140:143]
	v_mfma_f32_16x16x32_bf16 v[144:147], v[160:163], v[108:111], v[144:147]
	v_mfma_f32_16x16x32_bf16 v[104:107], v[160:163], v[148:151], v[104:107]
	v_mfma_f32_16x16x32_bf16 v[4:7], v[164:167], v[4:7], v[10:13]
	v_mfma_f32_16x16x32_bf16 v[10:13], v[164:167], v[22:25], v[14:17]
	v_mfma_f32_16x16x32_bf16 v[14:17], v[164:167], v[108:111], v[18:21]
	v_mfma_f32_16x16x32_bf16 v[0:3], v[164:167], v[148:151], v[0:3]
	s_nop 1
	ds_read_b128 v[18:21], v8 offset:23552
	ds_read_b128 v[22:25], v8 offset:22528
	ds_read_b128 v[108:111], v8 offset:21504
	ds_read_b128 v[148:151], v8 offset:20480
	ds_read_b128 v[152:155], v8 offset:19456
	ds_read_b128 v[156:159], v8 offset:18432
	ds_read_b128 v[160:163], v8 offset:17408
	ds_read_b128 v[164:167], v8 offset:16384
	ds_read_b128 v[168:171], v9 offset:3072
	ds_read_b128 v[172:175], v9 offset:2048
	ds_read_b128 v[176:179], v9 offset:1024
	ds_read_b128 v[186:189], v9
	s_waitcnt vmcnt(0)
	s_waitcnt lgkmcnt(0)
	v_mfma_f32_16x16x32_bf16 v[42:45], v[164:167], v[186:189], v[42:45]
	s_barrier
; template <int N> DI void wait_vm() { asm volatile("s_waitcnt vmcnt(%0)" ::"n"(N) : "memory"); }
; DI void st_bf4(u16* p, float a, float b, float c, float d) { *(uint2*)p = make_uint2(pk2(a, b), pk2(c, d)); }
; template <int BM, class Epi>
; DI void gemm_dma(const u16* __restrict__ X, long ldx, const u16* __restrict__ W, long ldw, int K, char* smem,
;                  int m0, int n0, const Epi& epi) {
;     ...
;   do {
;     if (kt + D - 2 < nk) wait_vm<PW * (D - 2)>(); else wait_vm<0>();
;     __syncthreads();
;     if (kt + D - 1 < nk) GD_ISSUE(nxt)
;     nxt = (nxt + 1 == D) ? 0 : nxt + 1;
;     const char* base = smem + cur * STG;
;     cur = (cur + 1 == D) ? 0 : cur + 1;
;     bf16x8 xf[MT];
; #pragma unroll
;     for (int i = 0; i < MT; ++i) xf[i] = *(const bf16x8*)(base + (xrow0 + i * 16) * 64 + rd);
; #pragma unroll
;     for (int nh = 0; nh < NT / 4; ++nh) {
;       bf16x8 wf[4];
; #pragma unroll
;       for (int i = 0; i < 4; ++i) wf[i] = *(const bf16x8*)(base + BM * 64 + (wrow0 + (nh * 4 + i) * 16) * 64 + rd);
; #pragma unroll
;       for (int i = 0; i < 4; ++i)
; #pragma unroll
;         for (int mt = 0; mt < MT; ++mt)
;           acc[nh * 4 + i][mt] = __builtin_amdgcn_mfma_f32_16x16x32_bf16(wf[i], xf[mt], acc[nh * 4 + i][mt], 0, 0, 0);
;     }
;   } while (++kt < nk);
;   template <int NT, int MT> DI void run(f32x4 (&acc)[NT][MT], int mb, int nb) const {
; #pragma unroll
;     for (int nt = 0; nt < NT; ++nt)
; #pragma unroll
;       for (int mt = 0; mt < MT; ++mt) {
;         f32x4 v = acc[nt][mt];
;         st_bf4(C + (size_t)(mb + mt * 16) * ldc + nb + nt * 16, v[0], v[1], v[2], v[3]);
;       }
;   }
	v_mfma_f32_16x16x32_bf16 v[46:49], v[164:167], v[176:179], v[46:49]
	v_mfma_f32_16x16x32_bf16 v[50:53], v[164:167], v[172:175], v[50:53]
	v_mfma_f32_16x16x32_bf16 v[26:29], v[164:167], v[168:171], v[26:29]
	v_mfma_f32_16x16x32_bf16 v[54:57], v[160:163], v[186:189], v[54:57]
	v_mfma_f32_16x16x32_bf16 v[58:61], v[160:163], v[176:179], v[58:61]
	v_mfma_f32_16x16x32_bf16 v[62:65], v[160:163], v[172:175], v[62:65]
	v_mfma_f32_16x16x32_bf16 v[30:33], v[160:163], v[168:171], v[30:33]
	v_mfma_f32_16x16x32_bf16 v[66:69], v[156:159], v[186:189], v[66:69]
	v_mfma_f32_16x16x32_bf16 v[70:73], v[156:159], v[176:179], v[70:73]
	v_mfma_f32_16x16x32_bf16 v[74:77], v[156:159], v[172:175], v[74:77]
	v_mfma_f32_16x16x32_bf16 v[34:37], v[156:159], v[168:171], v[34:37]
	v_mfma_f32_16x16x32_bf16 v[156:159], v[152:155], v[186:189], v[78:81]
	v_mfma_f32_16x16x32_bf16 v[84:87], v[152:155], v[176:179], v[82:85]
	v_mfma_f32_16x16x32_bf16 v[92:95], v[152:155], v[172:175], v[92:95]
	v_mfma_f32_16x16x32_bf16 v[152:155], v[152:155], v[168:171], v[38:41]
	v_mfma_f32_16x16x32_bf16 v[112:115], v[148:151], v[186:189], v[112:115]
	v_mfma_f32_16x16x32_bf16 v[116:119], v[148:151], v[176:179], v[116:119]
	v_mfma_f32_16x16x32_bf16 v[120:123], v[148:151], v[172:175], v[120:123]
	v_mfma_f32_16x16x32_bf16 v[96:99], v[148:151], v[168:171], v[96:99]
	v_mfma_f32_16x16x32_bf16 v[124:127], v[108:111], v[186:189], v[124:127]
	v_mfma_f32_16x16x32_bf16 v[128:131], v[108:111], v[176:179], v[128:131]
	v_mfma_f32_16x16x32_bf16 v[132:135], v[108:111], v[172:175], v[132:135]
	v_mfma_f32_16x16x32_bf16 v[100:103], v[108:111], v[168:171], v[100:103]
	v_mfma_f32_16x16x32_bf16 v[108:111], v[22:25], v[186:189], v[136:139]
	v_mfma_f32_16x16x32_bf16 v[136:139], v[22:25], v[176:179], v[140:143]
	v_mfma_f32_16x16x32_bf16 v[140:143], v[22:25], v[172:175], v[144:147]
	v_mfma_f32_16x16x32_bf16 v[104:107], v[22:25], v[168:171], v[104:107]
	v_mfma_f32_16x16x32_bf16 v[4:7], v[18:21], v[186:189], v[4:7]
	v_mfma_f32_16x16x32_bf16 v[144:147], v[18:21], v[176:179], v[10:13]
	v_mfma_f32_16x16x32_bf16 v[148:151], v[18:21], v[172:175], v[14:17]
	v_mfma_f32_16x16x32_bf16 v[0:3], v[18:21], v[168:171], v[0:3]
	s_nop 0
	ds_read_b128 v[10:13], v9 offset:24576
	ds_read_b128 v[160:163], v9 offset:25600
	ds_read_b128 v[164:167], v9 offset:26624
	ds_read_b128 v[168:171], v9 offset:27648
	ds_read_b128 v[14:17], v8 offset:40960
	ds_read_b128 v[18:21], v8 offset:41984
	ds_read_b128 v[22:25], v8 offset:43008
	ds_read_b128 v[172:175], v8 offset:44032
	s_waitcnt lgkmcnt(3)
	v_mfma_f32_16x16x32_bf16 v[176:179], v[14:17], v[10:13], v[42:45]
	v_mfma_f32_16x16x32_bf16 v[186:189], v[14:17], v[160:163], v[46:49]
	v_mfma_f32_16x16x32_bf16 v[190:193], v[14:17], v[164:167], v[50:53]
	v_mfma_f32_16x16x32_bf16 v[194:197], v[14:17], v[168:171], v[26:29]
	s_waitcnt lgkmcnt(2)
	v_mfma_f32_16x16x32_bf16 v[224:227], v[18:21], v[10:13], v[54:57]
	v_mfma_f32_16x16x32_bf16 v[228:231], v[18:21], v[160:163], v[58:61]
	v_mfma_f32_16x16x32_bf16 v[232:235], v[18:21], v[164:167], v[62:65]
	v_mfma_f32_16x16x32_bf16 v[236:239], v[18:21], v[168:171], v[30:33]
	s_waitcnt lgkmcnt(1)
	v_mfma_f32_16x16x32_bf16 v[240:243], v[22:25], v[10:13], v[66:69]
	v_mfma_f32_16x16x32_bf16 v[64:67], v[22:25], v[168:171], v[34:37]
	s_waitcnt lgkmcnt(0)
	v_mfma_f32_16x16x32_bf16 v[40:43], v[172:175], v[164:167], v[92:95]
	v_mfma_f32_16x16x32_bf16 v[32:35], v[172:175], v[168:171], v[152:155]
	ds_read_b128 v[14:17], v8 offset:45056
	ds_read_b128 v[18:21], v8 offset:46080
	ds_read_b128 v[92:95], v8 offset:47104
	ds_read_b128 v[152:155], v8 offset:48128
	s_nop 0
	v_cvt_pk_bf16_f32 v64, v64, v65
	v_cvt_pk_bf16_f32 v65, v66, v67
	v_mfma_f32_16x16x32_bf16 v[80:83], v[22:25], v[160:163], v[70:73]
	v_cvt_pk_bf16_f32 v32, v32, v33
	v_cvt_pk_bf16_f32 v33, v34, v35
	v_cvt_pk_bf16_f32 v40, v40, v41
	v_mfma_f32_16x16x32_bf16 v[72:75], v[22:25], v[164:167], v[74:77]
	v_cvt_pk_bf16_f32 v41, v42, v43
	s_nop 2
	v_cvt_pk_bf16_f32 v80, v80, v81
	v_cvt_pk_bf16_f32 v81, v82, v83
	v_mfma_f32_16x16x32_bf16 v[48:51], v[172:175], v[160:163], v[84:87]
	s_waitcnt lgkmcnt(3)
	v_mfma_f32_16x16x32_bf16 v[112:115], v[14:17], v[10:13], v[112:115]
	v_cvt_pk_bf16_f32 v72, v72, v73
	v_cvt_pk_bf16_f32 v73, v74, v75
	s_nop 3
	v_cvt_pk_bf16_f32 v48, v48, v49
	v_mfma_f32_16x16x32_bf16 v[84:87], v[14:17], v[160:163], v[116:119]
	v_cvt_pk_bf16_f32 v49, v50, v51
	v_mfma_f32_16x16x32_bf16 v[76:79], v[14:17], v[164:167], v[120:123]
	v_mfma_f32_16x16x32_bf16 v[68:71], v[14:17], v[168:171], v[96:99]
	s_waitcnt lgkmcnt(2)
	v_mfma_f32_16x16x32_bf16 v[60:63], v[18:21], v[10:13], v[124:127]
	s_nop 0
	v_cvt_pk_bf16_f32 v96, v190, v191
	v_cvt_pk_bf16_f32 v97, v192, v193
	v_mfma_f32_16x16x32_bf16 v[52:55], v[18:21], v[160:163], v[128:131]
	v_mfma_f32_16x16x32_bf16 v[44:47], v[18:21], v[164:167], v[132:135]
	v_mfma_f32_16x16x32_bf16 v[36:39], v[18:21], v[168:171], v[100:103]
	s_waitcnt lgkmcnt(1)
; DI unsigned pk2(float a, float b) { f32x2_t f = {a, b}; return __builtin_bit_cast(unsigned, __builtin_convertvector(f, bf16x2_t)); }
; DI void st_bf4(u16* p, float a, float b, float c, float d) { *(uint2*)p = make_uint2(pk2(a, b), pk2(c, d)); }
;   template <int NT, int MT> DI void run(f32x4 (&acc)[NT][MT], int mb, int nb) const {
; #pragma unroll
;     for (int nt = 0; nt < NT; ++nt)
; #pragma unroll
;       for (int mt = 0; mt < MT; ++mt) {
;         f32x4 v = acc[nt][mt];
;         st_bf4(C + (size_t)(mb + mt * 16) * ldc + nb + nt * 16, v[0], v[1], v[2], v[3]);
;       }
;   }
	v_mfma_f32_16x16x32_bf16 v[28:31], v[92:95], v[10:13], v[108:111]
	v_mfma_f32_16x16x32_bf16 v[24:27], v[92:95], v[160:163], v[136:139]
	v_mfma_f32_16x16x32_bf16 v[20:23], v[92:95], v[164:167], v[140:143]
	s_nop 5
	v_cvt_pk_bf16_f32 v28, v28, v29
	v_cvt_pk_bf16_f32 v29, v30, v31
	v_cvt_pk_bf16_f32 v24, v24, v25
	v_mfma_f32_16x16x32_bf16 v[16:19], v[92:95], v[168:171], v[104:107]
	v_or_b32_e32 v92, v90, v89
	v_ashrrev_i32_e32 v93, 31, v92
	v_lshlrev_b64 v[90:91], 11, v[92:93]
	v_lshl_add_u64 v[90:91], s[92:93], 0, v[90:91]
	v_bfe_u32 v34, v185, 4, 1
	v_mad_u32_u24 v182, v34, 24, v182
	v_lshl_add_u64 v[88:89], v[90:91], 0, v[182:183]
	v_cvt_pk_bf16_f32 v90, v176, v177
	v_cvt_pk_bf16_f32 v91, v178, v179
	v_mov_b32_e32 v98, v90
	v_mov_b32_e32 v99, v91
	v_or_b32_e32 v90, 16, v92
	v_ashrrev_i32_e32 v91, 31, v90
	v_lshlrev_b64 v[90:91], 11, v[90:91]
	v_lshl_add_u64 v[90:91], s[92:93], 0, v[90:91]
	v_lshl_add_u64 v[90:91], v[90:91], 0, v[182:183]
	v_cvt_pk_bf16_f32 v94, v186, v187
	v_cvt_pk_bf16_f32 v95, v188, v189
	v_mov_b32_e32 v102, v94
	v_mov_b32_e32 v103, v95
	v_or_b32_e32 v94, 32, v92
	v_or_b32_e32 v92, 48, v92
	v_ashrrev_i32_e32 v93, 31, v92
	v_lshlrev_b64 v[92:93], 11, v[92:93]
	v_ashrrev_i32_e32 v95, 31, v94
	v_lshl_add_u64 v[92:93], s[92:93], 0, v[92:93]
	v_lshlrev_b64 v[94:95], 11, v[94:95]
	v_lshl_add_u64 v[92:93], v[92:93], 0, v[182:183]
	v_lshl_add_u64 v[94:95], s[92:93], 0, v[94:95]
	v_mov_b32_e32 v108, v32
	v_mov_b32_e32 v109, v33
	v_cvt_pk_bf16_f32 v32, v112, v113
	v_cvt_pk_bf16_f32 v33, v114, v115
	v_lshl_add_u64 v[94:95], v[94:95], 0, v[182:183]
	v_mov_b32_e32 v116, v32
	v_mov_b32_e32 v117, v33
	v_cvt_pk_bf16_f32 v32, v84, v85
	v_cvt_pk_bf16_f32 v33, v86, v87
	v_mov_b32_e32 v120, v96
	v_mov_b32_e32 v121, v97
	v_cvt_pk_bf16_f32 v96, v194, v195
	v_cvt_pk_bf16_f32 v97, v196, v197
	v_mov_b32_e32 v124, v32
	v_mov_b32_e32 v125, v33
	v_cvt_pk_bf16_f32 v32, v76, v77
	v_cvt_pk_bf16_f32 v33, v78, v79
	v_mfma_f32_16x16x32_bf16 v[56:59], v[172:175], v[10:13], v[156:159]
	v_mov_b32_e32 v110, v96
	v_mov_b32_e32 v111, v97
	v_cvt_pk_bf16_f32 v96, v224, v225
	v_cvt_pk_bf16_f32 v97, v226, v227
	s_waitcnt lgkmcnt(0)
	v_mfma_f32_16x16x32_bf16 v[12:15], v[152:155], v[10:13], v[4:7]
	v_mov_b32_e32 v82, v32
	v_mov_b32_e32 v83, v33
	v_cvt_pk_bf16_f32 v32, v68, v69
	v_cvt_pk_bf16_f32 v33, v70, v71
	v_mfma_f32_16x16x32_bf16 v[8:11], v[152:155], v[160:163], v[144:147]
	v_mov_b32_e32 v100, v96
	v_mov_b32_e32 v101, v97
	s_nop 1
	v_permlane16_swap_b32_e32 v98, v100
	v_permlane16_swap_b32_e32 v99, v101
	global_store_dwordx4 v[88:89], v[98:101], off
	v_cvt_pk_bf16_f32 v96, v228, v229
	v_cvt_pk_bf16_f32 v97, v230, v231
	v_mfma_f32_16x16x32_bf16 v[4:7], v[152:155], v[164:167], v[148:151]
	v_mov_b32_e32 v74, v32
	v_mov_b32_e32 v75, v33
	v_cvt_pk_bf16_f32 v32, v60, v61
	v_cvt_pk_bf16_f32 v33, v62, v63
	v_mfma_f32_16x16x32_bf16 v[0:3], v[152:155], v[168:171], v[0:3]
	v_mov_b32_e32 v104, v96
	v_mov_b32_e32 v105, v97
	s_nop 1
	v_permlane16_swap_b32_e32 v102, v104
	v_permlane16_swap_b32_e32 v103, v105
	global_store_dwordx4 v[90:91], v[102:105], off
	v_cvt_pk_bf16_f32 v96, v232, v233
	v_cvt_pk_bf16_f32 v97, v234, v235
	v_mov_b32_e32 v118, v32
	v_mov_b32_e32 v119, v33
	s_nop 1
	v_permlane16_swap_b32_e32 v116, v118
	v_permlane16_swap_b32_e32 v117, v119
	global_store_dwordx4 v[88:89], v[116:119], off offset:128
	v_cvt_pk_bf16_f32 v32, v52, v53
	v_cvt_pk_bf16_f32 v33, v54, v55
	v_mov_b32_e32 v122, v96
	v_mov_b32_e32 v123, v97
	s_nop 1
	v_permlane16_swap_b32_e32 v120, v122
	v_permlane16_swap_b32_e32 v121, v123
	global_store_dwordx4 v[94:95], v[120:123], off
	v_cvt_pk_bf16_f32 v96, v236, v237
	v_cvt_pk_bf16_f32 v97, v238, v239
	v_mov_b32_e32 v126, v32
	v_mov_b32_e32 v127, v33
	s_nop 1
	v_permlane16_swap_b32_e32 v124, v126
	v_permlane16_swap_b32_e32 v125, v127
	global_store_dwordx4 v[90:91], v[124:127], off offset:128
	v_cvt_pk_bf16_f32 v32, v44, v45
	v_cvt_pk_bf16_f32 v33, v46, v47
	v_mov_b32_e32 v112, v96
	v_mov_b32_e32 v113, v97
	s_nop 1
	v_permlane16_swap_b32_e32 v110, v112
	v_permlane16_swap_b32_e32 v111, v113
	global_store_dwordx4 v[92:93], v[110:113], off
	v_cvt_pk_bf16_f32 v96, v240, v241
	v_cvt_pk_bf16_f32 v97, v242, v243
	v_cvt_pk_bf16_f32 v56, v56, v57
	v_cvt_pk_bf16_f32 v57, v58, v59
	v_mov_b32_e32 v84, v32
	v_mov_b32_e32 v85, v33
	s_nop 1
	v_permlane16_swap_b32_e32 v82, v84
	v_permlane16_swap_b32_e32 v83, v85
	global_store_dwordx4 v[94:95], v[82:85], off offset:128
	v_cvt_pk_bf16_f32 v32, v36, v37
	v_cvt_pk_bf16_f32 v33, v38, v39
	v_cvt_pk_bf16_f32 v25, v26, v27
	v_cvt_pk_bf16_f32 v20, v20, v21
	v_cvt_pk_bf16_f32 v21, v22, v23
	v_cvt_pk_bf16_f32 v16, v16, v17
	v_cvt_pk_bf16_f32 v17, v18, v19
	v_cvt_pk_bf16_f32 v12, v12, v13
	v_cvt_pk_bf16_f32 v13, v14, v15
	v_cvt_pk_bf16_f32 v8, v8, v9
	v_cvt_pk_bf16_f32 v9, v10, v11
	v_cvt_pk_bf16_f32 v4, v4, v5
	v_cvt_pk_bf16_f32 v5, v6, v7
	v_cvt_pk_bf16_f32 v0, v0, v1
	v_cvt_pk_bf16_f32 v1, v2, v3
	v_mov_b32_e32 v106, v64
	v_mov_b32_e32 v107, v65
	s_nop 1
	v_permlane16_swap_b32_e32 v106, v108
	v_permlane16_swap_b32_e32 v107, v109
	global_store_dwordx4 v[92:93], v[106:109], off offset:64
	v_mov_b32_e32 v98, v56
	v_mov_b32_e32 v99, v57
	s_nop 1
	v_permlane16_swap_b32_e32 v96, v98
	v_permlane16_swap_b32_e32 v97, v99
	global_store_dwordx4 v[88:89], v[96:99], off offset:64
	v_mov_b32_e32 v82, v48
	v_mov_b32_e32 v83, v49
	s_nop 1
	v_permlane16_swap_b32_e32 v80, v82
	v_permlane16_swap_b32_e32 v81, v83
	global_store_dwordx4 v[90:91], v[80:83], off offset:64
	v_mov_b32_e32 v38, v72
	v_mov_b32_e32 v39, v73
	s_nop 1
	v_permlane16_swap_b32_e32 v38, v40
	v_permlane16_swap_b32_e32 v39, v41
	global_store_dwordx4 v[94:95], v[38:41], off offset:64
	v_mov_b32_e32 v76, v32
	v_mov_b32_e32 v77, v33
	s_nop 1
	v_permlane16_swap_b32_e32 v74, v76
	v_permlane16_swap_b32_e32 v75, v77
	global_store_dwordx4 v[92:93], v[74:77], off offset:128
	v_mov_b32_e32 v30, v12
	v_mov_b32_e32 v31, v13
	s_nop 1
	v_permlane16_swap_b32_e32 v28, v30
	v_permlane16_swap_b32_e32 v29, v31
	global_store_dwordx4 v[88:89], v[28:31], off offset:192
	v_mov_b32_e32 v26, v8
	v_mov_b32_e32 v27, v9
	s_nop 1
	v_permlane16_swap_b32_e32 v24, v26
	v_permlane16_swap_b32_e32 v25, v27
	global_store_dwordx4 v[90:91], v[24:27], off offset:192
	v_mov_b32_e32 v22, v4
	v_mov_b32_e32 v23, v5
	s_nop 1
	v_permlane16_swap_b32_e32 v20, v22
	v_permlane16_swap_b32_e32 v21, v23
	global_store_dwordx4 v[94:95], v[20:23], off offset:192
	v_mov_b32_e32 v18, v0
	v_mov_b32_e32 v19, v1
	s_nop 1
	v_permlane16_swap_b32_e32 v16, v18
	v_permlane16_swap_b32_e32 v17, v19
	global_store_dwordx4 v[92:93], v[16:19], off offset:192

; template <int N> DI void wait_vm() { asm volatile("s_waitcnt vmcnt(%0)" ::"n"(N) : "memory"); }
; template <int BM, class Epi>
; DI void gemm_dma(const u16* __restrict__ X, long ldx, const u16* __restrict__ W, long ldw, int K, char* smem,
;                  int m0, int n0, const Epi& epi) {
;     ...
;   const int nk = K >> 5;
;   __syncthreads();
; #pragma unroll
;   for (int s = 0; s < D - 1; ++s) GD_ISSUE(s)
;   int cur = 0, nxt = D - 1, kt = 0;
;   do {
;     if (kt + D - 2 < nk) wait_vm<PW * (D - 2)>(); else wait_vm<0>();
;     __syncthreads();
;     if (kt + D - 1 < nk) GD_ISSUE(nxt)
;     nxt = (nxt + 1 == D) ? 0 : nxt + 1;
;     const char* base = smem + cur * STG;
;     cur = (cur + 1 == D) ? 0 : cur + 1;
;     bf16x8 xf[MT];
; #pragma unroll
;     for (int i = 0; i < MT; ++i) xf[i] = *(const bf16x8*)(base + (xrow0 + i * 16) * 64 + rd);
; #pragma unroll
;     for (int nh = 0; nh < NT / 4; ++nh) {
;       bf16x8 wf[4];
; #pragma unroll
;       for (int i = 0; i < 4; ++i) wf[i] = *(const bf16x8*)(base + BM * 64 + (wrow0 + (nh * 4 + i) * 16) * 64 + rd);
; #pragma unroll
;       for (int i = 0; i < 4; ++i)
; #pragma unroll
;         for (int mt = 0; mt < MT; ++mt)
;           acc[nh * 4 + i][mt] = __builtin_amdgcn_mfma_f32_16x16x32_bf16(wf[i], xf[mt], acc[nh * 4 + i][mt], 0, 0, 0);
;     }
;   } while (++kt < nk);
.LBB0_1139:
	s_mul_i32 s12, s10, 0x6000
	v_lshl_add_u64 v[196:197], v[130:131], 0, s[42:43]
	s_waitcnt vmcnt(6)
	s_barrier
	s_mul_i32 s98, s11, 0x6000
	v_or_b32_e32 v137, s98, v134
	v_add_u32_e32 v150, v137, v136
	ds_read_b128 v[138:141], v150
	ds_read_b128 v[142:145], v150 offset:1024
	ds_read_b128 v[146:149], v150 offset:2048
	ds_read_b128 v[150:153], v150 offset:3072
	ds_read_b128 v[154:157], v137 offset:16384
	ds_read_b128 v[158:161], v137 offset:17408
	ds_read_b128 v[162:165], v137 offset:18432
	ds_read_b128 v[166:169], v137 offset:19456
	ds_read_b128 v[226:229], v137 offset:20480
	ds_read_b128 v[230:233], v137 offset:21504
	ds_read_b128 v[234:237], v137 offset:22528
	ds_read_b128 v[238:241], v137 offset:23552
	s_add_i32 s13, s12, s8
	s_mov_b32 m0, s13
	s_nop 0
	global_load_lds_dwordx4 v[196:197], off
	v_lshl_add_u64 v[224:225], v[196:197], 0, s[58:59]
	s_add_i32 s14, s13, 0x400
	s_mov_b32 m0, s14
	s_nop 0
	global_load_lds_dwordx4 v[224:225], off
	v_lshl_add_u64 v[224:225], v[196:197], 0, s[16:17]
	s_add_i32 s14, s13, 0x800
	s_mov_b32 m0, s14
	s_nop 0
	global_load_lds_dwordx4 v[224:225], off
	v_lshl_add_u64 v[196:197], v[196:197], 0, s[18:19]
	s_addk_i32 s13, 0xc00
	s_mov_b32 m0, s13
	s_nop 0
	global_load_lds_dwordx4 v[196:197], off
	s_add_i32 s12, s12, s9
	v_lshl_add_u64 v[194:195], v[128:129], 0, s[42:43]
	s_mov_b32 m0, s12
	s_nop 0
	global_load_lds_dwordx4 v[194:195], off
	s_addk_i32 s12, 0x400
	v_lshl_add_u64 v[194:195], v[194:195], 0, s[58:59]
	s_mov_b32 m0, s12
	s_nop 0
	global_load_lds_dwordx4 v[194:195], off
	s_waitcnt lgkmcnt(7)
	v_mfma_f32_16x16x32_bf16 v[124:127], v[154:157], v[138:141], v[124:127]
	s_add_i32 s10, s10, 1
	s_add_i32 s11, s11, 1
	s_cmp_lg_u32 s10, 3
	v_mfma_f32_16x16x32_bf16 v[120:123], v[154:157], v[142:145], v[120:123]
	s_cselect_b32 s10, s10, 0
	s_cmp_lg_u32 s11, 3
	s_cselect_b32 s11, s11, 0
	v_mfma_f32_16x16x32_bf16 v[116:119], v[154:157], v[146:149], v[116:119]
	s_add_u32 s42, s42, 64
	s_addc_u32 s43, s43, 0
	s_cmpk_lg_i32 s42, 0xf80
	v_mfma_f32_16x16x32_bf16 v[112:115], v[154:157], v[150:153], v[112:115]
	s_waitcnt lgkmcnt(6)
	v_mfma_f32_16x16x32_bf16 v[108:111], v[158:161], v[138:141], v[108:111]
	v_mfma_f32_16x16x32_bf16 v[104:107], v[158:161], v[142:145], v[104:107]
	v_mfma_f32_16x16x32_bf16 v[100:103], v[158:161], v[146:149], v[100:103]
	v_mfma_f32_16x16x32_bf16 v[96:99], v[158:161], v[150:153], v[96:99]
	s_waitcnt lgkmcnt(5)
	v_mfma_f32_16x16x32_bf16 v[92:95], v[162:165], v[138:141], v[92:95]
	v_mfma_f32_16x16x32_bf16 v[88:91], v[162:165], v[142:145], v[88:91]
	v_mfma_f32_16x16x32_bf16 v[84:87], v[162:165], v[146:149], v[84:87]
	v_mfma_f32_16x16x32_bf16 v[80:83], v[162:165], v[150:153], v[80:83]
	s_waitcnt lgkmcnt(4)
	v_mfma_f32_16x16x32_bf16 v[76:79], v[166:169], v[138:141], v[76:79]
	v_mfma_f32_16x16x32_bf16 v[72:75], v[166:169], v[142:145], v[72:75]
	v_mfma_f32_16x16x32_bf16 v[68:71], v[166:169], v[146:149], v[68:71]
	v_mfma_f32_16x16x32_bf16 v[64:67], v[166:169], v[150:153], v[64:67]
	s_waitcnt lgkmcnt(3)
	v_mfma_f32_16x16x32_bf16 v[60:63], v[226:229], v[138:141], v[60:63]
	v_mfma_f32_16x16x32_bf16 v[56:59], v[226:229], v[142:145], v[56:59]
	v_mfma_f32_16x16x32_bf16 v[52:55], v[226:229], v[146:149], v[52:55]
	v_mfma_f32_16x16x32_bf16 v[48:51], v[226:229], v[150:153], v[48:51]
	s_waitcnt lgkmcnt(2)
	v_mfma_f32_16x16x32_bf16 v[44:47], v[230:233], v[138:141], v[44:47]
	v_mfma_f32_16x16x32_bf16 v[40:43], v[230:233], v[142:145], v[40:43]
	v_mfma_f32_16x16x32_bf16 v[36:39], v[230:233], v[146:149], v[36:39]
	v_mfma_f32_16x16x32_bf16 v[32:35], v[230:233], v[150:153], v[32:35]
	s_waitcnt lgkmcnt(1)
	v_mfma_f32_16x16x32_bf16 v[28:31], v[234:237], v[138:141], v[28:31]
	v_mfma_f32_16x16x32_bf16 v[24:27], v[234:237], v[142:145], v[24:27]
	v_mfma_f32_16x16x32_bf16 v[20:23], v[234:237], v[146:149], v[20:23]
	v_mfma_f32_16x16x32_bf16 v[16:19], v[234:237], v[150:153], v[16:19]
	s_waitcnt lgkmcnt(0)
	v_mfma_f32_16x16x32_bf16 v[12:15], v[238:241], v[138:141], v[12:15]
	v_mfma_f32_16x16x32_bf16 v[8:11], v[238:241], v[142:145], v[8:11]
	v_mfma_f32_16x16x32_bf16 v[4:7], v[238:241], v[146:149], v[4:7]
	v_mfma_f32_16x16x32_bf16 v[0:3], v[238:241], v[150:153], v[0:3]
	s_cbranch_scc1 .LBB0_1139
	v_add_u32_e32 v180, v134, v136
	v_or_b32_e32 v148, 0x10000, v134
	v_or_b32_e32 v152, 0x10400, v134
	v_or_b32_e32 v156, 0x10800, v134
	v_or_b32_e32 v160, 0x10c00, v134
	s_waitcnt vmcnt(6)
	s_barrier
	ds_read_b128 v[128:131], v180 offset:49152
	ds_read_b128 v[136:139], v180 offset:50176
	ds_read_b128 v[140:143], v180 offset:51200
	ds_read_b128 v[144:147], v180 offset:52224
	ds_read_b128 v[148:151], v148
	ds_read_b128 v[152:155], v152
	ds_read_b128 v[156:159], v156
	ds_read_b128 v[160:163], v160
	s_waitcnt lgkmcnt(3)
	v_mfma_f32_16x16x32_bf16 v[124:127], v[148:151], v[128:131], v[124:127]
	v_readlane_b32 s8, v252, 33
	v_readlane_b32 s9, v252, 34
	s_lshl_b32 s7, s7, 8
	v_mfma_f32_16x16x32_bf16 v[120:123], v[148:151], v[136:139], v[120:123]
	v_lshl_or_b32 v182, v132, 3, s7
	v_mfma_f32_16x16x32_bf16 v[116:119], v[148:151], v[140:143], v[116:119]
	v_mfma_f32_16x16x32_bf16 v[112:115], v[148:151], v[144:147], v[112:115]
	s_waitcnt lgkmcnt(2)
	v_mfma_f32_16x16x32_bf16 v[108:111], v[152:155], v[128:131], v[108:111]
	v_mfma_f32_16x16x32_bf16 v[104:107], v[152:155], v[136:139], v[104:107]
	v_mfma_f32_16x16x32_bf16 v[100:103], v[152:155], v[140:143], v[100:103]
	v_mfma_f32_16x16x32_bf16 v[96:99], v[152:155], v[144:147], v[96:99]
	s_waitcnt lgkmcnt(1)
	v_mfma_f32_16x16x32_bf16 v[92:95], v[156:159], v[128:131], v[92:95]
	v_mfma_f32_16x16x32_bf16 v[148:151], v[156:159], v[136:139], v[88:91]
	v_mfma_f32_16x16x32_bf16 v[84:87], v[156:159], v[140:143], v[84:87]
	s_nop 1
	v_or_b32_e32 v88, 0x11c00, v134
	ds_read_b128 v[88:91], v88
	v_mfma_f32_16x16x32_bf16 v[152:155], v[156:159], v[144:147], v[80:83]
	s_waitcnt lgkmcnt(1)
	v_mfma_f32_16x16x32_bf16 v[76:79], v[160:163], v[128:131], v[76:79]
	s_nop 0
	v_or_b32_e32 v80, 0x11800, v134
	ds_read_b128 v[80:83], v80
	v_mfma_f32_16x16x32_bf16 v[156:159], v[160:163], v[136:139], v[72:75]
	v_mfma_f32_16x16x32_bf16 v[68:71], v[160:163], v[140:143], v[68:71]
	s_nop 1
	v_or_b32_e32 v72, 0x11400, v134
	ds_read_b128 v[72:75], v72
	v_mfma_f32_16x16x32_bf16 v[160:163], v[160:163], v[144:147], v[64:67]
	s_nop 2
	v_or_b32_e32 v64, 0x11000, v134
	ds_read_b128 v[64:67], v64
	s_waitcnt lgkmcnt(1)
	v_mfma_f32_16x16x32_bf16 v[44:47], v[72:75], v[128:131], v[44:47]
	s_waitcnt vmcnt(0)
	s_waitcnt lgkmcnt(0)
	s_barrier
; DI void st_bf4(u16* p, float a, float b, float c, float d) { *(uint2*)p = make_uint2(pk2(a, b), pk2(c, d)); }
; template <int BM, class Epi>
; DI void gemm_dma(const u16* __restrict__ X, long ldx, const u16* __restrict__ W, long ldw, int K, char* smem,
;                  int m0, int n0, const Epi& epi) {
;     ...
;     bf16x8 xf[MT];
; #pragma unroll
;     for (int i = 0; i < MT; ++i) xf[i] = *(const bf16x8*)(base + (xrow0 + i * 16) * 64 + rd);
; #pragma unroll
;     for (int nh = 0; nh < NT / 4; ++nh) {
;       bf16x8 wf[4];
; #pragma unroll
;       for (int i = 0; i < 4; ++i) wf[i] = *(const bf16x8*)(base + BM * 64 + (wrow0 + (nh * 4 + i) * 16) * 64 + rd);
; #pragma unroll
;       for (int i = 0; i < 4; ++i)
; #pragma unroll
;         for (int mt = 0; mt < MT; ++mt)
;           acc[nh * 4 + i][mt] = __builtin_amdgcn_mfma_f32_16x16x32_bf16(wf[i], xf[mt], acc[nh * 4 + i][mt], 0, 0, 0);
;     }
;   template <int NT, int MT> DI void run(f32x4 (&acc)[NT][MT], int mb, int nb) const {
;     ...
;         st_bf4(C + (size_t)(mb + mt * 16) * ldc + nb + nt * 16, v[0], v[1], v[2], v[3]);
	v_mfma_f32_16x16x32_bf16 v[60:63], v[64:67], v[128:131], v[60:63]
	v_mfma_f32_16x16x32_bf16 v[164:167], v[64:67], v[136:139], v[56:59]
	v_mfma_f32_16x16x32_bf16 v[52:55], v[64:67], v[140:143], v[52:55]
	v_mfma_f32_16x16x32_bf16 v[168:171], v[64:67], v[144:147], v[48:51]
	v_mfma_f32_16x16x32_bf16 v[172:175], v[72:75], v[136:139], v[40:43]
	v_mfma_f32_16x16x32_bf16 v[36:39], v[72:75], v[140:143], v[36:39]
	v_mfma_f32_16x16x32_bf16 v[176:179], v[72:75], v[144:147], v[32:35]
	v_mfma_f32_16x16x32_bf16 v[28:31], v[80:83], v[128:131], v[28:31]
	v_mfma_f32_16x16x32_bf16 v[24:27], v[80:83], v[136:139], v[24:27]
	v_mfma_f32_16x16x32_bf16 v[20:23], v[80:83], v[140:143], v[20:23]
	v_mfma_f32_16x16x32_bf16 v[16:19], v[80:83], v[144:147], v[16:19]
	v_mfma_f32_16x16x32_bf16 v[12:15], v[88:91], v[128:131], v[12:15]
	v_mfma_f32_16x16x32_bf16 v[8:11], v[88:91], v[136:139], v[8:11]
	v_mfma_f32_16x16x32_bf16 v[4:7], v[88:91], v[140:143], v[4:7]
	v_mfma_f32_16x16x32_bf16 v[0:3], v[88:91], v[144:147], v[0:3]
	ds_read_b128 v[128:131], v180
	ds_read_b128 v[136:139], v180 offset:1024
	ds_read_b128 v[140:143], v180 offset:2048
	ds_read_b128 v[144:147], v180 offset:3072
	ds_read_b128 v[32:35], v134 offset:16384
	ds_read_b128 v[40:43], v134 offset:17408
	ds_read_b128 v[48:51], v134 offset:18432
	ds_read_b128 v[186:189], v134 offset:19456
	s_waitcnt lgkmcnt(2)
	v_mfma_f32_16x16x32_bf16 v[108:111], v[40:43], v[128:131], v[108:111]
	v_mfma_f32_16x16x32_bf16 v[104:107], v[40:43], v[136:139], v[104:107]
	v_mfma_f32_16x16x32_bf16 v[100:103], v[40:43], v[140:143], v[100:103]
	s_nop 5
	v_cvt_pk_bf16_f32 v108, v108, v109
	v_cvt_pk_bf16_f32 v109, v110, v111
	v_cvt_pk_bf16_f32 v104, v104, v105
	v_mfma_f32_16x16x32_bf16 v[190:193], v[40:43], v[144:147], v[96:99]
	v_cvt_pk_bf16_f32 v105, v106, v107
	v_cvt_pk_bf16_f32 v100, v100, v101
	v_cvt_pk_bf16_f32 v101, v102, v103
	s_waitcnt lgkmcnt(1)
	v_mfma_f32_16x16x32_bf16 v[80:83], v[48:51], v[136:139], v[148:151]
	v_mfma_f32_16x16x32_bf16 v[64:67], v[48:51], v[144:147], v[152:155]
	s_waitcnt lgkmcnt(0)
	v_mfma_f32_16x16x32_bf16 v[40:43], v[186:189], v[140:143], v[68:71]
	s_nop 2
	ds_read_b128 v[68:71], v134 offset:20480
	ds_read_b128 v[96:99], v134 offset:21504
	ds_read_b128 v[148:151], v134 offset:22528
	ds_read_b128 v[152:155], v134 offset:23552
	v_cvt_pk_bf16_f32 v80, v80, v81
	v_cvt_pk_bf16_f32 v81, v82, v83
	v_mfma_f32_16x16x32_bf16 v[88:91], v[48:51], v[128:131], v[92:95]
	v_cvt_pk_bf16_f32 v64, v64, v65
	v_cvt_pk_bf16_f32 v65, v66, v67
	v_cvt_pk_bf16_f32 v40, v40, v41
	v_mfma_f32_16x16x32_bf16 v[56:59], v[186:189], v[128:131], v[76:79]
	v_cvt_pk_bf16_f32 v41, v42, v43
	s_nop 2
	v_cvt_pk_bf16_f32 v88, v88, v89
	v_cvt_pk_bf16_f32 v89, v90, v91
	s_waitcnt lgkmcnt(3)
	v_mfma_f32_16x16x32_bf16 v[92:95], v[68:71], v[128:131], v[60:63]
	v_mfma_f32_16x16x32_bf16 v[76:79], v[68:71], v[140:143], v[52:55]
	v_cvt_pk_bf16_f32 v56, v56, v57
	v_cvt_pk_bf16_f32 v57, v58, v59
	s_waitcnt lgkmcnt(2)
	v_mfma_f32_16x16x32_bf16 v[60:63], v[96:99], v[128:131], v[44:47]
	v_mfma_f32_16x16x32_bf16 v[52:55], v[96:99], v[136:139], v[172:175]
	v_mfma_f32_16x16x32_bf16 v[44:47], v[96:99], v[140:143], v[36:39]
	v_mfma_f32_16x16x32_bf16 v[36:39], v[96:99], v[144:147], v[176:179]
	v_lshl_add_u32 v96, s40, 8, v135
	v_mfma_f32_16x16x32_bf16 v[124:127], v[32:35], v[128:131], v[124:127]
	s_waitcnt lgkmcnt(1)
	v_mfma_f32_16x16x32_bf16 v[28:31], v[148:151], v[128:131], v[28:31]
	s_waitcnt lgkmcnt(0)
; DI unsigned pk2(float a, float b) { f32x2_t f = {a, b}; return __builtin_bit_cast(unsigned, __builtin_convertvector(f, bf16x2_t)); }
; DI void st_bf4(u16* p, float a, float b, float c, float d) { *(uint2*)p = make_uint2(pk2(a, b), pk2(c, d)); }
;   template <int NT, int MT> DI void run(f32x4 (&acc)[NT][MT], int mb, int nb) const {
; #pragma unroll
;     for (int nt = 0; nt < NT; ++nt)
; #pragma unroll
;       for (int mt = 0; mt < MT; ++mt) {
;         f32x4 v = acc[nt][mt];
;         st_bf4(C + (size_t)(mb + mt * 16) * ldc + nb + nt * 16, v[0], v[1], v[2], v[3]);
;       }
;   }
	v_mfma_f32_16x16x32_bf16 v[12:15], v[152:155], v[128:131], v[12:15]
	v_or_b32_e32 v128, v96, v133
	v_ashrrev_i32_e32 v129, 31, v128
	v_lshlrev_b64 v[96:97], 11, v[128:129]
	v_lshl_add_u64 v[96:97], s[8:9], 0, v[96:97]
	v_bfe_u32 v130, v185, 4, 1
	v_mad_u32_u24 v182, v130, 24, v182
	v_lshl_add_u64 v[96:97], v[96:97], 0, v[182:183]
	v_cvt_pk_bf16_f32 v98, v124, v125
	v_cvt_pk_bf16_f32 v99, v126, v127
	v_mfma_f32_16x16x32_bf16 v[120:123], v[32:35], v[136:139], v[120:123]
	v_mov_b32_e32 v172, v98
	v_mov_b32_e32 v173, v99
	v_or_b32_e32 v98, 16, v128
	v_ashrrev_i32_e32 v99, 31, v98
	v_lshlrev_b64 v[98:99], 11, v[98:99]
	v_lshl_add_u64 v[98:99], s[8:9], 0, v[98:99]
	v_lshl_add_u64 v[98:99], v[98:99], 0, v[182:183]
	s_nop 1
	v_cvt_pk_bf16_f32 v120, v120, v121
	v_cvt_pk_bf16_f32 v121, v122, v123
	v_mfma_f32_16x16x32_bf16 v[116:119], v[32:35], v[140:143], v[116:119]
	v_mov_b32_e32 v176, v120
	v_mov_b32_e32 v177, v121
	v_or_b32_e32 v120, 32, v128
	v_ashrrev_i32_e32 v121, 31, v120
	v_lshlrev_b64 v[120:121], 11, v[120:121]
	v_lshl_add_u64 v[120:121], s[8:9], 0, v[120:121]
	v_lshl_add_u64 v[120:121], v[120:121], 0, v[182:183]
	s_nop 1
	v_cvt_pk_bf16_f32 v116, v116, v117
	v_cvt_pk_bf16_f32 v117, v118, v119
	v_mfma_f32_16x16x32_bf16 v[112:115], v[32:35], v[144:147], v[112:115]
	v_mov_b32_e32 v194, v116
	v_mov_b32_e32 v195, v117
	v_or_b32_e32 v116, 48, v128
	v_ashrrev_i32_e32 v117, 31, v116
	v_mfma_f32_16x16x32_bf16 v[32:35], v[186:189], v[144:147], v[160:163]
	v_lshlrev_b64 v[116:117], 11, v[116:117]
	v_lshl_add_u64 v[116:117], s[8:9], 0, v[116:117]
	v_lshl_add_u64 v[116:117], v[116:117], 0, v[182:183]
	v_mfma_f32_16x16x32_bf16 v[72:75], v[48:51], v[140:143], v[84:87]
	v_cvt_pk_bf16_f32 v112, v112, v113
	s_nop 2
	v_cvt_pk_bf16_f32 v32, v32, v33
	v_cvt_pk_bf16_f32 v33, v34, v35
	v_mfma_f32_16x16x32_bf16 v[84:87], v[68:71], v[136:139], v[164:167]
	v_mov_b32_e32 v130, v32
	v_mov_b32_e32 v131, v33
	v_cvt_pk_bf16_f32 v32, v92, v93
	v_cvt_pk_bf16_f32 v33, v94, v95
	v_mfma_f32_16x16x32_bf16 v[68:71], v[68:71], v[144:147], v[168:171]
	v_mov_b32_e32 v160, v32
	v_mov_b32_e32 v161, v33
	s_nop 2
	v_cvt_pk_bf16_f32 v32, v84, v85
	v_cvt_pk_bf16_f32 v33, v86, v87
	v_mov_b32_e32 v224, v32
	v_mov_b32_e32 v225, v33
	v_cvt_pk_bf16_f32 v32, v76, v77
	v_cvt_pk_bf16_f32 v33, v78, v79
	v_mfma_f32_16x16x32_bf16 v[48:51], v[186:189], v[136:139], v[156:159]
	v_mov_b32_e32 v164, v32
	v_mov_b32_e32 v165, v33
	v_cvt_pk_bf16_f32 v32, v68, v69
	v_cvt_pk_bf16_f32 v33, v70, v71
	v_mfma_f32_16x16x32_bf16 v[24:27], v[148:151], v[136:139], v[24:27]
	v_mov_b32_e32 v168, v32
	v_mov_b32_e32 v169, v33
	v_cvt_pk_bf16_f32 v32, v60, v61
	v_cvt_pk_bf16_f32 v33, v62, v63
	v_mfma_f32_16x16x32_bf16 v[20:23], v[148:151], v[140:143], v[20:23]
	v_mov_b32_e32 v162, v32
	v_mov_b32_e32 v163, v33
	s_nop 1
	v_permlane16_swap_b32_e32 v160, v162
	v_permlane16_swap_b32_e32 v161, v163
	global_store_dwordx4 v[96:97], v[160:163], off offset:128
	v_cvt_pk_bf16_f32 v32, v52, v53
	v_cvt_pk_bf16_f32 v33, v54, v55
	v_mfma_f32_16x16x32_bf16 v[16:19], v[148:151], v[144:147], v[16:19]
	v_mov_b32_e32 v226, v32
	v_mov_b32_e32 v227, v33
	s_nop 1
	v_permlane16_swap_b32_e32 v224, v226
	v_permlane16_swap_b32_e32 v225, v227
	global_store_dwordx4 v[98:99], v[224:227], off offset:128
	v_cvt_pk_bf16_f32 v32, v44, v45
	v_cvt_pk_bf16_f32 v33, v46, v47
	v_mfma_f32_16x16x32_bf16 v[8:11], v[152:155], v[136:139], v[8:11]
	v_cvt_pk_bf16_f32 v113, v114, v115
	v_mov_b32_e32 v196, v100
	v_mov_b32_e32 v197, v101
	s_nop 1
	v_permlane16_swap_b32_e32 v194, v196
	v_permlane16_swap_b32_e32 v195, v197
	global_store_dwordx4 v[120:121], v[194:197], off
	v_cvt_pk_bf16_f32 v100, v190, v191
	v_mfma_f32_16x16x32_bf16 v[4:7], v[152:155], v[140:143], v[4:7]
	v_cvt_pk_bf16_f32 v101, v192, v193
	v_cvt_pk_bf16_f32 v72, v72, v73
	v_cvt_pk_bf16_f32 v73, v74, v75
	v_mfma_f32_16x16x32_bf16 v[0:3], v[152:155], v[144:147], v[0:3]
	v_cvt_pk_bf16_f32 v48, v48, v49
	v_cvt_pk_bf16_f32 v49, v50, v51
	v_mov_b32_e32 v166, v32
	v_mov_b32_e32 v167, v33
	s_nop 1
	v_permlane16_swap_b32_e32 v164, v166
	v_permlane16_swap_b32_e32 v165, v167
	global_store_dwordx4 v[120:121], v[164:167], off offset:128
	v_cvt_pk_bf16_f32 v32, v36, v37
	v_cvt_pk_bf16_f32 v33, v38, v39
	v_cvt_pk_bf16_f32 v28, v28, v29
	v_cvt_pk_bf16_f32 v29, v30, v31
	v_cvt_pk_bf16_f32 v24, v24, v25
	v_cvt_pk_bf16_f32 v25, v26, v27
	v_cvt_pk_bf16_f32 v20, v20, v21
	v_cvt_pk_bf16_f32 v21, v22, v23
	v_cvt_pk_bf16_f32 v16, v16, v17
	v_cvt_pk_bf16_f32 v17, v18, v19
	v_cvt_pk_bf16_f32 v12, v12, v13
	v_cvt_pk_bf16_f32 v13, v14, v15
	v_cvt_pk_bf16_f32 v8, v8, v9
	v_cvt_pk_bf16_f32 v9, v10, v11
	v_cvt_pk_bf16_f32 v4, v4, v5
	v_cvt_pk_bf16_f32 v5, v6, v7
	v_cvt_pk_bf16_f32 v0, v0, v1
	v_cvt_pk_bf16_f32 v1, v2, v3
	v_mov_b32_e32 v174, v108
	v_mov_b32_e32 v175, v109
	s_nop 1
	v_permlane16_swap_b32_e32 v172, v174
	v_permlane16_swap_b32_e32 v173, v175
	global_store_dwordx4 v[96:97], v[172:175], off
	v_mov_b32_e32 v178, v104
	v_mov_b32_e32 v179, v105
	s_nop 1
	v_permlane16_swap_b32_e32 v176, v178
	v_permlane16_swap_b32_e32 v177, v179
	global_store_dwordx4 v[98:99], v[176:179], off
	v_mov_b32_e32 v114, v100
	v_mov_b32_e32 v115, v101
	s_nop 1
	v_permlane16_swap_b32_e32 v112, v114
	v_permlane16_swap_b32_e32 v113, v115
	global_store_dwordx4 v[116:117], v[112:115], off
	v_mov_b32_e32 v128, v64
	v_mov_b32_e32 v129, v65
	s_nop 1
	v_permlane16_swap_b32_e32 v128, v130
	v_permlane16_swap_b32_e32 v129, v131
	global_store_dwordx4 v[116:117], v[128:131], off offset:64
	v_mov_b32_e32 v90, v56
	v_mov_b32_e32 v91, v57
	s_nop 1
	v_permlane16_swap_b32_e32 v88, v90
	v_permlane16_swap_b32_e32 v89, v91
	global_store_dwordx4 v[96:97], v[88:91], off offset:64
	v_mov_b32_e32 v82, v48
	v_mov_b32_e32 v83, v49
	s_nop 1
	v_permlane16_swap_b32_e32 v80, v82
	v_permlane16_swap_b32_e32 v81, v83
	global_store_dwordx4 v[98:99], v[80:83], off offset:64
	v_mov_b32_e32 v74, v40
	v_mov_b32_e32 v75, v41
	s_nop 1
	v_permlane16_swap_b32_e32 v72, v74
	v_permlane16_swap_b32_e32 v73, v75
	global_store_dwordx4 v[120:121], v[72:75], off offset:64
	v_mov_b32_e32 v170, v32
	v_mov_b32_e32 v171, v33
	s_nop 1
	v_permlane16_swap_b32_e32 v168, v170
	v_permlane16_swap_b32_e32 v169, v171
	global_store_dwordx4 v[116:117], v[168:171], off offset:128
	v_mov_b32_e32 v30, v12
	v_mov_b32_e32 v31, v13
	s_nop 1
	v_permlane16_swap_b32_e32 v28, v30
	v_permlane16_swap_b32_e32 v29, v31
	global_store_dwordx4 v[96:97], v[28:31], off offset:192
	v_mov_b32_e32 v26, v8
	v_mov_b32_e32 v27, v9
	s_nop 1
	v_permlane16_swap_b32_e32 v24, v26
	v_permlane16_swap_b32_e32 v25, v27
	global_store_dwordx4 v[98:99], v[24:27], off offset:192
	v_mov_b32_e32 v22, v4
	v_mov_b32_e32 v23, v5
	s_nop 1
	v_permlane16_swap_b32_e32 v20, v22
	v_permlane16_swap_b32_e32 v21, v23
	global_store_dwordx4 v[120:121], v[20:23], off offset:192
	v_mov_b32_e32 v18, v0
	v_mov_b32_e32 v19, v1
	s_nop 1
	v_permlane16_swap_b32_e32 v16, v18
	v_permlane16_swap_b32_e32 v17, v19
	global_store_dwordx4 v[116:117], v[16:19], off offset:192
	s_branch .LBB0_1132
